# all five GEMM main loops rescheduled: 2 barriers per k-step, register-pipelined fragment reads, no wave stagger
# speedup vs baseline: 1.0192x; 1.0192x over previous
; #define LAS __attribute__((address_space(3)))
; #define PG8_STAGE(bufoff, gbase, voff) do { _Pragma("unroll") for (int _i = 0; _i < 2; ++_i) \
;         __builtin_amdgcn_global_load_lds((const unsigned*)((const char*)(gbase) + (voff)[_i]), (LAS unsigned*)(lds + (bufoff) + ldsw + _i * 8192), 16, 0, 0); } while (0)
; #define PG8_WAIT_V(n) asm volatile("s_waitcnt vmcnt(" #n ")" ::: "memory")
; #define PG8_BAR __builtin_amdgcn_s_barrier()
; template <class Epi, int LDA, int LDB, int KK>
; __device__ __forceinline__ void gemm_phase(int wv, LAS unsigned char* lds, const Gemm g, const StaticOrder& S, const Epi& E) {
;     ...
;     const unsigned ldsw = (unsigned)wid * 1024u;
;     const int aoff = lds_byte(wr * 64 + fr, fq * 8), boff = lds_byte(wc * 32 + fr, fq * 8);
;     ...
;     const char* cA = (const char*)g.A + (size_t)cur.pm * tstepA; const char* cB = (const char*)g.Bt + (size_t)cur.pn * tstepB;
;     if constexpr (Epi::ROWSCALE) { if (wid < 4) __builtin_amdgcn_global_load_lds((const unsigned*)(E.rsq + cur.pm * 256 + wid * 64 + lane), (LAS unsigned*)(lds + 131072 + wid * 256), 4, 0, 0); }
;     PG8_STAGE(PG8_SB(0, 0), cB, voffB); PG8_STAGE(PG8_SA(0, 0), cA, voffA); PG8_STAGE(PG8_SB(0, 1), cB + hstepB, voffB); PG8_STAGE(PG8_SA(0, 1), cA + hstepA, voffA);
;     if (wr == 1) PG8_BAR;
;     PG8_WAIT_V(4); PG8_BAR;
;     PG8_STAGE(PG8_SB(1, 0), cB + kstep, voffB); PG8_STAGE(PG8_SA(1, 0), cA + kstep, voffA); PG8_STAGE(PG8_SB(1, 1), cB + hstepB + kstep, voffB);
;     PG8_WAIT_V(6); PG8_BAR;
.LBB0_171:
	s_add_u32 s46, s14, 0x8400000
	s_addc_u32 s47, s15, 0
	s_add_u32 s18, s14, 0x27c00000
	s_addc_u32 s19, s15, 0
	s_and_b32 s22, s6, 3
	s_add_i32 m0, s31, 0x18000
	v_lshl_add_u64 v[10:11], v[10:11], 0, s[58:59]
	s_lshl_b32 s55, s7, 6
	s_lshl_b32 s7, s7, 13
	s_lshl_b32 s20, s22, 12
	s_waitcnt vmcnt(4)
	s_barrier
	global_load_lds_dwordx4 v[10:11], off
	v_lshl_add_u64 v[8:9], v[8:9], 0, s[58:59]
	s_add_i32 m0, s31, 0x1a000
	s_add_i32 s56, s31, 0x8000
	s_add_i32 s68, s31, 0xa000
	global_load_lds_dwordx4 v[8:9], off
	v_lshl_add_u64 v[6:7], v[6:7], 0, s[58:59]
	s_mov_b32 m0, s56
	s_add_u32 s8, s36, 0x80080
	global_load_lds_dwordx4 v[6:7], off
	v_lshl_add_u64 v[4:5], v[4:5], 0, s[58:59]
	s_mov_b32 m0, s68
	s_addc_u32 s9, s37, 0
	global_load_lds_dwordx4 v[4:5], off
	s_add_i32 m0, s31, 0x1c000
	v_lshl_add_u64 v[4:5], s[8:9], 0, v[132:133]
	global_load_lds_dwordx4 v[4:5], off
	v_lshl_add_u64 v[4:5], s[8:9], 0, v[136:137]
	s_add_i32 m0, s31, 0x1e000
	v_and_b32_e32 v148, 15, v12
	global_load_lds_dwordx4 v[4:5], off
	s_add_u32 s98, s34, 0x80080
	s_addc_u32 s99, s35, 0
	v_lshl_add_u64 v[218:219], s[98:99], 0, v[0:1]
	s_add_i32 m0, s31, 0xc000
	s_nop 0
	global_load_lds_dwordx4 v[218:219], off
	v_lshl_add_u64 v[218:219], s[98:99], 0, v[134:135]
	s_add_i32 m0, s31, 0xe000
	s_nop 0
	global_load_lds_dwordx4 v[218:219], off
	v_and_b32_e32 v6, 48, v12
	v_lshlrev_b32_e32 v7, 2, v12
	v_lshl_or_b32 v6, v148, 6, v6
	v_and_b32_e32 v7, 32, v7
	v_bitop3_b32 v150, v6, s20, v7 bitop3:0xde
	s_and_b32 s20, s39, 0xffffffc0
	s_lshl_b32 s6, s6, 8
	s_ashr_i32 s21, s20, 31
	s_add_i32 s69, s6, 0
	v_bitop3_b32 v8, v6, s7, v7 bitop3:0xde
	s_add_i32 s69, s69, 0x20000
	s_lshl_b64 s[6:7], s[20:21], 2
	s_add_u32 s4, s4, s6
	s_addc_u32 s5, s5, s7
	v_lshrrev_b32_e32 v5, 4, v13
	v_lshl_add_u64 v[138:139], s[4:5], 0, v[2:3]
	v_lshlrev_b32_e32 v2, 15, v17
	v_lshlrev_b32_e32 v4, 3, v5
	v_or_b32_e32 v5, s22, v5
	v_and_b32_e32 v2, 0xffff0000, v2
	v_cmp_eq_u32_e64 s[8:9], 0, v5
	v_lshl_add_u32 v2, v18, 12, v2
	v_and_b32_e32 v5, 1, v17
	v_lshl_or_b32 v2, v5, 6, v2
	v_lshl_add_u32 v140, v19, 1, v2
	v_lshlrev_b32_e32 v2, 15, v14
	v_and_b32_e32 v2, 0xffff0000, v2
	s_waitcnt vmcnt(8)
	v_lshl_add_u32 v2, v15, 12, v2
	v_and_b32_e32 v5, 1, v14
	v_lshl_or_b32 v4, s22, 5, v4
	v_lshl_or_b32 v2, v5, 6, v2
	v_or_b32_e32 v149, s55, v148
	s_mov_b32 s71, 0
	v_mov_b32_e32 v141, v3
	v_lshl_add_u32 v142, v16, 1, v2
	v_mov_b32_e32 v143, v3
	v_add_u32_e32 v151, 0, v8
	v_lshlrev_b32_e32 v2, 1, v4
	s_barrier
	s_branch .LBB0_173

; #define LAS __attribute__((address_space(3)))
; #define PG8_STAGE(bufoff, gbase, voff) do { _Pragma("unroll") for (int _i = 0; _i < 2; ++_i) \
;         __builtin_amdgcn_global_load_lds((const unsigned*)((const char*)(gbase) + (voff)[_i]), (LAS unsigned*)(lds + (bufoff) + ldsw + _i * 8192), 16, 0, 0); } while (0)
; #define PG8_LDA(dst, b, h) do { _Pragma("unroll") for (int m = 0; m < 4; ++m) _Pragma("unroll") for (int k = 0; k < 2; ++k) dst[m][k] = *(const LAS bf16x8*)(lds + PG8_SA(b, h) + aoff + m * 2048 + k * 1024); } while (0)
; #define PG8_WAIT_L(n) asm volatile("s_waitcnt lgkmcnt(" #n ")" ::: "memory")
; #define PG8_BAR __builtin_amdgcn_s_barrier()
; template <class Epi, int LDA, int LDB, int KK>
; __device__ __forceinline__ void gemm_phase(int wv, LAS unsigned char* lds, const Gemm g, const StaticOrder& S, const Epi& E) {
;     ...
;     for (;;) {
;         const bool has_next = S.next(ui + 1, nxt);
;         const char* nA = has_next ? (const char*)g.A + (size_t)nxt.pm * tstepA : cA; const char* nB = has_next ? (const char*)g.Bt + (size_t)nxt.pn * tstepB : cB;
;         if constexpr (Epi::ROWSCALE) { if (has_next && wid < 4) __builtin_amdgcn_global_load_lds((const unsigned*)(E.rsq + nxt.pm * 256 + wid * 64 + lane), (LAS unsigned*)(lds + 131072 + ((ui + 1) % 3) * 1024 + wid * 256), 4, 0, 0); }
;         for (int seg = 0, t = 0; seg < Epi::NSEG; ++seg) {
;           const int tend = Epi::HAS_MID ? (seg == 0 ? Epi::MID1 : (seg == 1 ? Epi::MID2 : nt)) : nt;
;           for (; t < tend; t += 2) {
;             const bool last = (t == nt - 2);
;             const char* a1 = cA + (size_t)(t + 1) * kstep;
;             const char* a2 = last ? nA : cA + (size_t)(t + 2) * kstep; const char* b2 = last ? nB : cB + (size_t)(t + 2) * kstep;
;             const char* a3 = a2 + kstep; const char* b3 = b2 + kstep;
;             PG8_LDB(B0, 0, 0); PG8_SCHED; PG8_LDA(At, 0, 0); PG8_STAGE(PG8_SA(1, 1), a1 + hstepA, voffA);
;             PG8_WAIT_L(8); PG8_BAR; PG8_WAIT_L(0); PG8_MMA(0, 0, At, B0); PG8_BAR; PG8_SCHED;
;     ...
; #pragma unroll
;         for (int a = 0; a < 2; ++a)
; #pragma unroll
;             for (int b = 0; b < 2; ++b)
; #pragma unroll
;                 for (int m = 0; m < 4; ++m)
; #pragma unroll
;                     for (int n = 0; n < 2; ++n) acc[a][b][m][n] = (f32x4){0.f, 0.f, 0.f, 0.f};
;         cur = nxt; cA = nA; cB = nB; ++ui;
.LBB0_181:
	s_ashr_i32 s23, s22, 31
	s_lshl_b64 s[24:25], s[22:23], 20
	s_add_u32 s24, s12, s24
	s_addc_u32 s25, s13, s25
	s_and_b64 s[26:27], s[6:7], exec
	s_cselect_b32 s23, s25, s35
	s_cselect_b32 s73, s24, s34
	s_ashr_i32 s21, s20, 31
	s_lshl_b64 s[26:27], s[20:21], 20
	s_add_u32 s26, s41, s26
	s_addc_u32 s27, s42, s27
	s_and_b64 s[6:7], s[6:7], exec
	s_cselect_b32 s21, s27, s37
	s_cselect_b32 s74, s26, s36
	s_add_u32 s75, s36, 0x100
	s_addc_u32 s76, s37, 0
	s_add_u32 s6, s34, 0x80080
	v_mov_b32_e32 v4, 0
	s_addc_u32 s7, s35, 0
	s_mov_b32 s77, -2
	v_mov_b32_e32 v5, v4
	v_mov_b32_e32 v6, v4
	v_mov_b32_e32 v7, v4
	v_mov_b32_e32 v8, v4
	v_mov_b32_e32 v9, v4
	v_mov_b32_e32 v10, v4
	v_mov_b32_e32 v11, v4
	v_mov_b32_e32 v20, v4
	v_mov_b32_e32 v21, v4
	v_mov_b32_e32 v22, v4
	v_mov_b32_e32 v23, v4
	v_mov_b32_e32 v24, v4
	v_mov_b32_e32 v25, v4
	v_mov_b32_e32 v26, v4
	v_mov_b32_e32 v27, v4
	v_mov_b32_e32 v32, v4
	v_mov_b32_e32 v33, v4
	v_mov_b32_e32 v34, v4
	v_mov_b32_e32 v35, v4
	v_mov_b32_e32 v40, v4
	v_mov_b32_e32 v41, v4
	v_mov_b32_e32 v42, v4
	v_mov_b32_e32 v43, v4
	v_mov_b32_e32 v52, v4
	v_mov_b32_e32 v53, v4
	v_mov_b32_e32 v54, v4
	v_mov_b32_e32 v55, v4
	v_mov_b32_e32 v56, v4
	v_mov_b32_e32 v57, v4
	v_mov_b32_e32 v58, v4
	v_mov_b32_e32 v59, v4
	v_mov_b32_e32 v12, v4
	v_mov_b32_e32 v13, v4
	v_mov_b32_e32 v14, v4
	v_mov_b32_e32 v15, v4
	v_mov_b32_e32 v16, v4
	v_mov_b32_e32 v17, v4
	v_mov_b32_e32 v18, v4
	v_mov_b32_e32 v19, v4
	v_mov_b32_e32 v28, v4
	v_mov_b32_e32 v29, v4
	v_mov_b32_e32 v30, v4
	v_mov_b32_e32 v31, v4
	v_mov_b32_e32 v36, v4
	v_mov_b32_e32 v37, v4
	v_mov_b32_e32 v38, v4
	v_mov_b32_e32 v39, v4
	v_mov_b32_e32 v44, v4
	v_mov_b32_e32 v45, v4
	v_mov_b32_e32 v46, v4
	v_mov_b32_e32 v47, v4
	v_mov_b32_e32 v48, v4
	v_mov_b32_e32 v49, v4
	v_mov_b32_e32 v50, v4
	v_mov_b32_e32 v51, v4
	v_mov_b32_e32 v60, v4
	v_mov_b32_e32 v61, v4
	v_mov_b32_e32 v62, v4
	v_mov_b32_e32 v63, v4
	v_mov_b32_e32 v64, v4
	v_mov_b32_e32 v65, v4
	v_mov_b32_e32 v66, v4
	v_mov_b32_e32 v67, v4
	v_mov_b32_e32 v68, v4
	v_mov_b32_e32 v69, v4
	v_mov_b32_e32 v70, v4
	v_mov_b32_e32 v71, v4
	v_mov_b32_e32 v72, v4
	v_mov_b32_e32 v73, v4
	v_mov_b32_e32 v74, v4
	v_mov_b32_e32 v75, v4
	v_mov_b32_e32 v84, v4
	v_mov_b32_e32 v85, v4
	v_mov_b32_e32 v86, v4
	v_mov_b32_e32 v87, v4
	v_mov_b32_e32 v88, v4
	v_mov_b32_e32 v89, v4
	v_mov_b32_e32 v90, v4
	v_mov_b32_e32 v91, v4
	v_mov_b32_e32 v96, v4
	v_mov_b32_e32 v97, v4
	v_mov_b32_e32 v98, v4
	v_mov_b32_e32 v99, v4
	v_mov_b32_e32 v104, v4
	v_mov_b32_e32 v105, v4
	v_mov_b32_e32 v106, v4
	v_mov_b32_e32 v107, v4
	v_mov_b32_e32 v116, v4
	v_mov_b32_e32 v117, v4
	v_mov_b32_e32 v118, v4
	v_mov_b32_e32 v119, v4
	v_mov_b32_e32 v120, v4
	v_mov_b32_e32 v121, v4
	v_mov_b32_e32 v122, v4
	v_mov_b32_e32 v123, v4
	v_mov_b32_e32 v76, v4
	v_mov_b32_e32 v77, v4
	v_mov_b32_e32 v78, v4
	v_mov_b32_e32 v79, v4
	v_mov_b32_e32 v80, v4
	v_mov_b32_e32 v81, v4
	v_mov_b32_e32 v82, v4
	v_mov_b32_e32 v83, v4
	v_mov_b32_e32 v92, v4
	v_mov_b32_e32 v93, v4
	v_mov_b32_e32 v94, v4
	v_mov_b32_e32 v95, v4
	v_mov_b32_e32 v100, v4
	v_mov_b32_e32 v101, v4
	v_mov_b32_e32 v102, v4
	v_mov_b32_e32 v103, v4
	v_mov_b32_e32 v108, v4
	v_mov_b32_e32 v109, v4
	v_mov_b32_e32 v110, v4
	v_mov_b32_e32 v111, v4
	v_mov_b32_e32 v112, v4
	v_mov_b32_e32 v113, v4
	v_mov_b32_e32 v114, v4
	v_mov_b32_e32 v115, v4
	v_mov_b32_e32 v124, v4
	v_mov_b32_e32 v125, v4
	v_mov_b32_e32 v126, v4
	v_mov_b32_e32 v127, v4
	v_mov_b32_e32 v128, v4
	v_mov_b32_e32 v129, v4
	v_mov_b32_e32 v130, v4
	v_mov_b32_e32 v131, v4
	v_add_u32_e32 v197, 0x10000, v150
	ds_read_b128 v[144:147], v197 offset:0
	ds_read_b128 v[152:155], v197 offset:2048
	ds_read_b128 v[156:159], v197 offset:16384
	ds_read_b128 v[160:163], v197 offset:18432
	ds_read_b128 v[164:167], v151 offset:0
	ds_read_b128 v[168:171], v151 offset:2048
	ds_read_b128 v[172:175], v151 offset:4096
	ds_read_b128 v[176:179], v151 offset:6144
.Lin_loop:
	s_add_u32 s34, s6, 0xfff80080
	s_addc_u32 s35, s7, -1
	s_cmp_eq_u32 s77, 28
	s_cselect_b32 s37, s23, s35
	s_cselect_b32 s36, s73, s34
	s_cselect_b32 s35, s21, s76
	s_cselect_b32 s34, s74, s75
	s_waitcnt lgkmcnt(0)
	v_mfma_f32_16x16x32_bf16 v[128:131], v[144:147], v[164:167], v[128:131]
	ds_read_b128 v[202:205], v197 offset:1024
	v_mfma_f32_16x16x32_bf16 v[124:127], v[152:155], v[164:167], v[124:127]
	ds_read_b128 v[206:209], v197 offset:3072
	v_mfma_f32_16x16x32_bf16 v[120:123], v[156:159], v[164:167], v[120:123]
	ds_read_b128 v[210:213], v197 offset:17408
	v_mfma_f32_16x16x32_bf16 v[116:119], v[160:163], v[164:167], v[116:119]
	ds_read_b128 v[214:217], v197 offset:19456
	v_mfma_f32_16x16x32_bf16 v[112:115], v[144:147], v[168:171], v[112:115]
	ds_read_b128 v[180:183], v151 offset:1024
	v_mfma_f32_16x16x32_bf16 v[108:111], v[152:155], v[168:171], v[108:111]
	ds_read_b128 v[184:187], v151 offset:3072
	v_mfma_f32_16x16x32_bf16 v[104:107], v[156:159], v[168:171], v[104:107]
	ds_read_b128 v[188:191], v151 offset:5120
	v_mfma_f32_16x16x32_bf16 v[96:99], v[160:163], v[168:171], v[96:99]
	ds_read_b128 v[192:195], v151 offset:7168
	v_mfma_f32_16x16x32_bf16 v[100:103], v[144:147], v[172:175], v[100:103]
	v_mfma_f32_16x16x32_bf16 v[92:95], v[152:155], v[172:175], v[92:95]
	v_mfma_f32_16x16x32_bf16 v[88:91], v[156:159], v[172:175], v[88:91]
	v_mfma_f32_16x16x32_bf16 v[84:87], v[160:163], v[172:175], v[84:87]
	v_mfma_f32_16x16x32_bf16 v[80:83], v[144:147], v[176:179], v[80:83]
	v_mfma_f32_16x16x32_bf16 v[76:79], v[152:155], v[176:179], v[76:79]
	v_mfma_f32_16x16x32_bf16 v[72:75], v[156:159], v[176:179], v[72:75]
	v_mfma_f32_16x16x32_bf16 v[68:71], v[160:163], v[176:179], v[68:71]
	s_waitcnt vmcnt(8) lgkmcnt(0)
	s_barrier
; #define PG8_STAGE(bufoff, gbase, voff) do { _Pragma("unroll") for (int _i = 0; _i < 2; ++_i) \
;         __builtin_amdgcn_global_load_lds((const unsigned*)((const char*)(gbase) + (voff)[_i]), (LAS unsigned*)(lds + (bufoff) + ldsw + _i * 8192), 16, 0, 0); } while (0)
; #define PG8_LDA(dst, b, h) do { _Pragma("unroll") for (int m = 0; m < 4; ++m) _Pragma("unroll") for (int k = 0; k < 2; ++k) dst[m][k] = *(const LAS bf16x8*)(lds + PG8_SA(b, h) + aoff + m * 2048 + k * 1024); } while (0)
; #define PG8_LDB(dst, b, h) do { _Pragma("unroll") for (int n = 0; n < 2; ++n) _Pragma("unroll") for (int k = 0; k < 2; ++k) dst[n][k] = *(const LAS bf16x8*)(lds + PG8_SB(b, h) + boff + n * 2048 + k * 1024); } while (0)
; #define PG8_WAIT_V(n) asm volatile("s_waitcnt vmcnt(" #n ")" ::: "memory")
; #define PG8_WAIT_L(n) asm volatile("s_waitcnt lgkmcnt(" #n ")" ::: "memory")
; template <class Epi, int LDA, int LDB, int KK>
; __device__ __forceinline__ void gemm_phase(int wv, LAS unsigned char* lds, const Gemm g, const StaticOrder& S, const Epi& E) {
;     ...
;           for (; t < tend; t += 2) {
;             const bool last = (t == nt - 2);
;             const char* a1 = cA + (size_t)(t + 1) * kstep;
;             const char* a2 = last ? nA : cA + (size_t)(t + 2) * kstep; const char* b2 = last ? nB : cB + (size_t)(t + 2) * kstep;
;             const char* a3 = a2 + kstep; const char* b3 = b2 + kstep;
;             PG8_LDB(B0, 0, 0); PG8_SCHED; PG8_LDA(At, 0, 0); PG8_STAGE(PG8_SA(1, 1), a1 + hstepA, voffA);
;             PG8_WAIT_L(8); PG8_BAR; PG8_WAIT_L(0); PG8_MMA(0, 0, At, B0); PG8_BAR; PG8_SCHED;
;             PG8_LDB(B1, 0, 1); PG8_STAGE(PG8_SB(0, 0), b2, voffB);
;             PG8_BAR; PG8_WAIT_L(0); PG8_MMA(0, 1, At, B1); PG8_BAR;
;             PG8_LDA(At, 0, 1); PG8_STAGE(PG8_SA(0, 0), a2, voffA);
;             PG8_BAR; PG8_WAIT_L(0); PG8_MMA(1, 0, At, B0); PG8_BAR; PG8_SCHED;
;             PG8_STAGE(PG8_SB(0, 1), b2 + hstepB, voffB);
;             PG8_WAIT_V(6); PG8_BAR; PG8_MMA(1, 1, At, B1); PG8_BAR;
;             PG8_LDB(B0, 1, 0); PG8_SCHED; PG8_LDA(At, 1, 0); PG8_STAGE(PG8_SA(0, 1), a2 + hstepA, voffA);
;             PG8_WAIT_L(8); PG8_BAR; PG8_WAIT_L(0); PG8_MMA(0, 0, At, B0); PG8_BAR; PG8_SCHED;
;             PG8_LDB(B1, 1, 1); PG8_STAGE(PG8_SB(1, 0), b3, voffB);
;             PG8_BAR; PG8_WAIT_L(0); PG8_MMA(0, 1, At, B1); PG8_BAR;
	v_mfma_f32_16x16x32_bf16 v[128:131], v[202:205], v[180:183], v[128:131]
	ds_read_b128 v[164:167], v151 offset:16384
	v_mfma_f32_16x16x32_bf16 v[124:127], v[206:209], v[180:183], v[124:127]
	ds_read_b128 v[168:171], v151 offset:18432
	v_mfma_f32_16x16x32_bf16 v[120:123], v[210:213], v[180:183], v[120:123]
	ds_read_b128 v[172:175], v151 offset:20480
	v_mfma_f32_16x16x32_bf16 v[116:119], v[214:217], v[180:183], v[116:119]
	ds_read_b128 v[176:179], v151 offset:22528
	v_mfma_f32_16x16x32_bf16 v[112:115], v[202:205], v[184:187], v[112:115]
	v_lshl_add_u64 v[218:219], s[34:35], 0, v[132:133]
	s_add_i32 m0, s31, 0x10000
	v_mfma_f32_16x16x32_bf16 v[108:111], v[206:209], v[184:187], v[108:111]
	global_load_lds_dwordx4 v[218:219], off
	v_mfma_f32_16x16x32_bf16 v[104:107], v[210:213], v[184:187], v[104:107]
	v_mfma_f32_16x16x32_bf16 v[96:99], v[214:217], v[184:187], v[96:99]
	v_lshl_add_u64 v[218:219], s[34:35], 0, v[136:137]
	s_add_i32 m0, s31, 0x12000
	v_mfma_f32_16x16x32_bf16 v[100:103], v[202:205], v[188:191], v[100:103]
	global_load_lds_dwordx4 v[218:219], off
	v_mfma_f32_16x16x32_bf16 v[92:95], v[206:209], v[188:191], v[92:95]
	v_mfma_f32_16x16x32_bf16 v[88:91], v[210:213], v[188:191], v[88:91]
	v_lshl_add_u64 v[218:219], s[36:37], 0, v[0:1]
	s_mov_b32 m0, s31
	v_mfma_f32_16x16x32_bf16 v[84:87], v[214:217], v[188:191], v[84:87]
	global_load_lds_dwordx4 v[218:219], off
	v_mfma_f32_16x16x32_bf16 v[80:83], v[202:205], v[192:195], v[80:83]
	v_mfma_f32_16x16x32_bf16 v[76:79], v[206:209], v[192:195], v[76:79]
	v_mfma_f32_16x16x32_bf16 v[72:75], v[210:213], v[192:195], v[72:75]
	v_mfma_f32_16x16x32_bf16 v[68:71], v[214:217], v[192:195], v[68:71]
	s_waitcnt lgkmcnt(0)
	v_mfma_f32_16x16x32_bf16 v[64:67], v[144:147], v[164:167], v[64:67]
	ds_read_b128 v[180:183], v151 offset:17408
	v_mfma_f32_16x16x32_bf16 v[60:63], v[152:155], v[164:167], v[60:63]
	ds_read_b128 v[184:187], v151 offset:19456
	v_mfma_f32_16x16x32_bf16 v[56:59], v[156:159], v[164:167], v[56:59]
	ds_read_b128 v[188:191], v151 offset:21504
	v_mfma_f32_16x16x32_bf16 v[52:55], v[160:163], v[164:167], v[52:55]
	ds_read_b128 v[192:195], v151 offset:23552
	v_mfma_f32_16x16x32_bf16 v[48:51], v[144:147], v[168:171], v[48:51]
	v_lshl_add_u64 v[218:219], s[36:37], 0, v[134:135]
	s_add_i32 m0, s31, 0x2000
	v_mfma_f32_16x16x32_bf16 v[44:47], v[152:155], v[168:171], v[44:47]
	global_load_lds_dwordx4 v[218:219], off
	v_mfma_f32_16x16x32_bf16 v[40:43], v[156:159], v[168:171], v[40:43]
	v_mfma_f32_16x16x32_bf16 v[32:35], v[160:163], v[168:171], v[32:35]
	s_add_u32 s98, s34, 0x80000
	s_addc_u32 s99, s35, 0
	v_lshl_add_u64 v[218:219], s[98:99], 0, v[132:133]
	s_add_i32 m0, s31, 0x14000
	v_mfma_f32_16x16x32_bf16 v[36:39], v[144:147], v[172:175], v[36:39]
	global_load_lds_dwordx4 v[218:219], off
	v_mfma_f32_16x16x32_bf16 v[28:31], v[152:155], v[172:175], v[28:31]
	v_mfma_f32_16x16x32_bf16 v[24:27], v[156:159], v[172:175], v[24:27]
	v_lshl_add_u64 v[218:219], s[98:99], 0, v[136:137]
	s_add_i32 m0, s31, 0x16000
	v_mfma_f32_16x16x32_bf16 v[20:23], v[160:163], v[172:175], v[20:23]
	global_load_lds_dwordx4 v[218:219], off
	v_mfma_f32_16x16x32_bf16 v[16:19], v[144:147], v[176:179], v[16:19]
	v_mfma_f32_16x16x32_bf16 v[12:15], v[152:155], v[176:179], v[12:15]
	v_mfma_f32_16x16x32_bf16 v[8:11], v[156:159], v[176:179], v[8:11]
	v_mfma_f32_16x16x32_bf16 v[4:7], v[160:163], v[176:179], v[4:7]
	s_waitcnt vmcnt(8) lgkmcnt(0)
	s_barrier
	v_mfma_f32_16x16x32_bf16 v[64:67], v[202:205], v[180:183], v[64:67]
	ds_read_b128 v[144:147], v197 offset:32768
	v_mfma_f32_16x16x32_bf16 v[60:63], v[206:209], v[180:183], v[60:63]
	ds_read_b128 v[152:155], v197 offset:34816
	v_mfma_f32_16x16x32_bf16 v[56:59], v[210:213], v[180:183], v[56:59]
	ds_read_b128 v[156:159], v197 offset:49152
	v_mfma_f32_16x16x32_bf16 v[52:55], v[214:217], v[180:183], v[52:55]
	ds_read_b128 v[160:163], v197 offset:51200
	v_mfma_f32_16x16x32_bf16 v[48:51], v[202:205], v[184:187], v[48:51]
	ds_read_b128 v[164:167], v151 offset:32768
	v_mfma_f32_16x16x32_bf16 v[44:47], v[206:209], v[184:187], v[44:47]
	ds_read_b128 v[168:171], v151 offset:34816
	v_mfma_f32_16x16x32_bf16 v[40:43], v[210:213], v[184:187], v[40:43]
	ds_read_b128 v[172:175], v151 offset:36864
	v_mfma_f32_16x16x32_bf16 v[32:35], v[214:217], v[184:187], v[32:35]
	ds_read_b128 v[176:179], v151 offset:38912
	v_mfma_f32_16x16x32_bf16 v[36:39], v[202:205], v[188:191], v[36:39]
	s_add_u32 s98, s36, 0x80000
	s_addc_u32 s99, s37, 0
	v_lshl_add_u64 v[218:219], s[98:99], 0, v[0:1]
	s_add_i32 m0, s31, 0x4000
	v_mfma_f32_16x16x32_bf16 v[28:31], v[206:209], v[188:191], v[28:31]
	global_load_lds_dwordx4 v[218:219], off
	v_mfma_f32_16x16x32_bf16 v[24:27], v[210:213], v[188:191], v[24:27]
	v_mfma_f32_16x16x32_bf16 v[20:23], v[214:217], v[188:191], v[20:23]
	v_lshl_add_u64 v[218:219], s[98:99], 0, v[134:135]
	s_add_i32 m0, s31, 0x6000
	v_mfma_f32_16x16x32_bf16 v[16:19], v[202:205], v[192:195], v[16:19]
	global_load_lds_dwordx4 v[218:219], off
	v_mfma_f32_16x16x32_bf16 v[12:15], v[206:209], v[192:195], v[12:15]
	v_mfma_f32_16x16x32_bf16 v[8:11], v[210:213], v[192:195], v[8:11]
	v_mfma_f32_16x16x32_bf16 v[4:7], v[214:217], v[192:195], v[4:7]
	s_add_u32 s34, s34, 0x80
	s_addc_u32 s35, s35, 0
	s_add_u32 s36, s36, 0x80
	s_addc_u32 s37, s37, 0
	s_waitcnt lgkmcnt(0)
	v_mfma_f32_16x16x32_bf16 v[128:131], v[144:147], v[164:167], v[128:131]
	ds_read_b128 v[202:205], v197 offset:33792
	v_mfma_f32_16x16x32_bf16 v[124:127], v[152:155], v[164:167], v[124:127]
	ds_read_b128 v[206:209], v197 offset:35840
	v_mfma_f32_16x16x32_bf16 v[120:123], v[156:159], v[164:167], v[120:123]
	ds_read_b128 v[210:213], v197 offset:50176
	v_mfma_f32_16x16x32_bf16 v[116:119], v[160:163], v[164:167], v[116:119]
	ds_read_b128 v[214:217], v197 offset:52224
	v_mfma_f32_16x16x32_bf16 v[112:115], v[144:147], v[168:171], v[112:115]
	ds_read_b128 v[180:183], v151 offset:33792
	v_mfma_f32_16x16x32_bf16 v[108:111], v[152:155], v[168:171], v[108:111]
	ds_read_b128 v[184:187], v151 offset:35840
	v_mfma_f32_16x16x32_bf16 v[104:107], v[156:159], v[168:171], v[104:107]
	ds_read_b128 v[188:191], v151 offset:37888
	v_mfma_f32_16x16x32_bf16 v[96:99], v[160:163], v[168:171], v[96:99]
	ds_read_b128 v[192:195], v151 offset:39936
	v_mfma_f32_16x16x32_bf16 v[100:103], v[144:147], v[172:175], v[100:103]
	v_mfma_f32_16x16x32_bf16 v[92:95], v[152:155], v[172:175], v[92:95]
	v_mfma_f32_16x16x32_bf16 v[88:91], v[156:159], v[172:175], v[88:91]
	v_mfma_f32_16x16x32_bf16 v[84:87], v[160:163], v[172:175], v[84:87]
	v_mfma_f32_16x16x32_bf16 v[80:83], v[144:147], v[176:179], v[80:83]
	v_mfma_f32_16x16x32_bf16 v[76:79], v[152:155], v[176:179], v[76:79]
	v_mfma_f32_16x16x32_bf16 v[72:75], v[156:159], v[176:179], v[72:75]
	v_mfma_f32_16x16x32_bf16 v[68:71], v[160:163], v[176:179], v[68:71]
	s_waitcnt vmcnt(8) lgkmcnt(0)
	s_barrier
; #define LAS __attribute__((address_space(3)))
; #define PG8_STAGE(bufoff, gbase, voff) do { _Pragma("unroll") for (int _i = 0; _i < 2; ++_i) \
;         __builtin_amdgcn_global_load_lds((const unsigned*)((const char*)(gbase) + (voff)[_i]), (LAS unsigned*)(lds + (bufoff) + ldsw + _i * 8192), 16, 0, 0); } while (0)
; #define PG8_LDA(dst, b, h) do { _Pragma("unroll") for (int m = 0; m < 4; ++m) _Pragma("unroll") for (int k = 0; k < 2; ++k) dst[m][k] = *(const LAS bf16x8*)(lds + PG8_SA(b, h) + aoff + m * 2048 + k * 1024); } while (0)
; #define PG8_LDB(dst, b, h) do { _Pragma("unroll") for (int n = 0; n < 2; ++n) _Pragma("unroll") for (int k = 0; k < 2; ++k) dst[n][k] = *(const LAS bf16x8*)(lds + PG8_SB(b, h) + boff + n * 2048 + k * 1024); } while (0)
; #define PG8_WAIT_V(n) asm volatile("s_waitcnt vmcnt(" #n ")" ::: "memory")
; #define PG8_WAIT_L(n) asm volatile("s_waitcnt lgkmcnt(" #n ")" ::: "memory")
; #define PG8_BAR __builtin_amdgcn_s_barrier()
; #define PG8_SCHED __builtin_amdgcn_sched_barrier(0)
; template <class Epi, int LDA, int LDB, int KK>
; __device__ __forceinline__ void gemm_phase(int wv, LAS unsigned char* lds, const Gemm g, const StaticOrder& S, const Epi& E) {
;     ...
;             PG8_LDB(B0, 1, 0); PG8_SCHED; PG8_LDA(At, 1, 0); PG8_STAGE(PG8_SA(0, 1), a2 + hstepA, voffA);
;             PG8_WAIT_L(8); PG8_BAR; PG8_WAIT_L(0); PG8_MMA(0, 0, At, B0); PG8_BAR; PG8_SCHED;
;             PG8_LDB(B1, 1, 1); PG8_STAGE(PG8_SB(1, 0), b3, voffB);
;             PG8_BAR; PG8_WAIT_L(0); PG8_MMA(0, 1, At, B1); PG8_BAR;
;             PG8_LDA(At, 1, 1); PG8_STAGE(PG8_SA(1, 0), a3, voffA);
;             PG8_BAR; PG8_WAIT_L(0); PG8_MMA(1, 0, At, B0); PG8_BAR; PG8_SCHED;
;             PG8_STAGE(PG8_SB(1, 1), b3 + hstepB, voffB);
;             PG8_WAIT_V(6); PG8_BAR; PG8_MMA(1, 1, At, B1); PG8_BAR;
;           }
;           if constexpr (Epi::HAS_MID) { if (seg < Epi::NSEG - 1) E.mid(acc, cur, seg, wr, wc, fr, fq); }
;         }
;         E(acc, cur, wr, wc, fr, fq, (const LAS float*)(lds + 131072 + (ui % 3) * 1024));
;         if (!has_next) break;
;     __device__ __forceinline__ void operator()(AccT& acc, const pg8::Unit& u, int wr, int wc, int fr, int fq, const LAS float* rs) const {
;         int row0 = u.pm * 256 + wr * 64 + fr; asm volatile("" : "+v"(row0)); const int cb = wc * 32 + 8 * fq;
;         if (u.pn < 52) {
	v_mfma_f32_16x16x32_bf16 v[128:131], v[202:205], v[180:183], v[128:131]
	ds_read_b128 v[164:167], v151 offset:49152
	v_mfma_f32_16x16x32_bf16 v[124:127], v[206:209], v[180:183], v[124:127]
	ds_read_b128 v[168:171], v151 offset:51200
	v_mfma_f32_16x16x32_bf16 v[120:123], v[210:213], v[180:183], v[120:123]
	ds_read_b128 v[172:175], v151 offset:53248
	v_mfma_f32_16x16x32_bf16 v[116:119], v[214:217], v[180:183], v[116:119]
	ds_read_b128 v[176:179], v151 offset:55296
	v_mfma_f32_16x16x32_bf16 v[112:115], v[202:205], v[184:187], v[112:115]
	v_lshl_add_u64 v[218:219], s[34:35], 0, v[132:133]
	s_add_i32 m0, s31, 0x18000
	v_mfma_f32_16x16x32_bf16 v[108:111], v[206:209], v[184:187], v[108:111]
	global_load_lds_dwordx4 v[218:219], off
	v_mfma_f32_16x16x32_bf16 v[104:107], v[210:213], v[184:187], v[104:107]
	v_mfma_f32_16x16x32_bf16 v[96:99], v[214:217], v[184:187], v[96:99]
	v_lshl_add_u64 v[218:219], s[34:35], 0, v[136:137]
	s_add_i32 m0, s31, 0x1a000
	v_mfma_f32_16x16x32_bf16 v[100:103], v[202:205], v[188:191], v[100:103]
	global_load_lds_dwordx4 v[218:219], off
	v_mfma_f32_16x16x32_bf16 v[92:95], v[206:209], v[188:191], v[92:95]
	v_mfma_f32_16x16x32_bf16 v[88:91], v[210:213], v[188:191], v[88:91]
	v_lshl_add_u64 v[218:219], s[36:37], 0, v[0:1]
	s_add_i32 m0, s31, 0x8000
	v_mfma_f32_16x16x32_bf16 v[84:87], v[214:217], v[188:191], v[84:87]
	global_load_lds_dwordx4 v[218:219], off
	v_mfma_f32_16x16x32_bf16 v[80:83], v[202:205], v[192:195], v[80:83]
	v_mfma_f32_16x16x32_bf16 v[76:79], v[206:209], v[192:195], v[76:79]
	v_mfma_f32_16x16x32_bf16 v[72:75], v[210:213], v[192:195], v[72:75]
	v_mfma_f32_16x16x32_bf16 v[68:71], v[214:217], v[192:195], v[68:71]
	s_waitcnt lgkmcnt(0)
	v_mfma_f32_16x16x32_bf16 v[64:67], v[144:147], v[164:167], v[64:67]
	ds_read_b128 v[180:183], v151 offset:50176
	v_mfma_f32_16x16x32_bf16 v[60:63], v[152:155], v[164:167], v[60:63]
	ds_read_b128 v[184:187], v151 offset:52224
	v_mfma_f32_16x16x32_bf16 v[56:59], v[156:159], v[164:167], v[56:59]
	ds_read_b128 v[188:191], v151 offset:54272
	v_mfma_f32_16x16x32_bf16 v[52:55], v[160:163], v[164:167], v[52:55]
	ds_read_b128 v[192:195], v151 offset:56320
	v_mfma_f32_16x16x32_bf16 v[48:51], v[144:147], v[168:171], v[48:51]
	v_lshl_add_u64 v[218:219], s[36:37], 0, v[134:135]
	s_add_i32 m0, s31, 0xa000
	v_mfma_f32_16x16x32_bf16 v[44:47], v[152:155], v[168:171], v[44:47]
	global_load_lds_dwordx4 v[218:219], off
	v_mfma_f32_16x16x32_bf16 v[40:43], v[156:159], v[168:171], v[40:43]
	v_mfma_f32_16x16x32_bf16 v[32:35], v[160:163], v[168:171], v[32:35]
	s_add_u32 s98, s34, 0x80000
	s_addc_u32 s99, s35, 0
	v_lshl_add_u64 v[218:219], s[98:99], 0, v[132:133]
	s_add_i32 m0, s31, 0x1c000
	v_mfma_f32_16x16x32_bf16 v[36:39], v[144:147], v[172:175], v[36:39]
	global_load_lds_dwordx4 v[218:219], off
	v_mfma_f32_16x16x32_bf16 v[28:31], v[152:155], v[172:175], v[28:31]
	v_mfma_f32_16x16x32_bf16 v[24:27], v[156:159], v[172:175], v[24:27]
	v_lshl_add_u64 v[218:219], s[98:99], 0, v[136:137]
	s_add_i32 m0, s31, 0x1e000
	v_mfma_f32_16x16x32_bf16 v[20:23], v[160:163], v[172:175], v[20:23]
	global_load_lds_dwordx4 v[218:219], off
	v_mfma_f32_16x16x32_bf16 v[16:19], v[144:147], v[176:179], v[16:19]
	v_mfma_f32_16x16x32_bf16 v[12:15], v[152:155], v[176:179], v[12:15]
	v_mfma_f32_16x16x32_bf16 v[8:11], v[156:159], v[176:179], v[8:11]
	v_mfma_f32_16x16x32_bf16 v[4:7], v[160:163], v[176:179], v[4:7]
	s_waitcnt vmcnt(8) lgkmcnt(0)
	s_barrier
	v_mfma_f32_16x16x32_bf16 v[64:67], v[202:205], v[180:183], v[64:67]
	ds_read_b128 v[144:147], v197 offset:0
	v_mfma_f32_16x16x32_bf16 v[60:63], v[206:209], v[180:183], v[60:63]
	ds_read_b128 v[152:155], v197 offset:2048
	v_mfma_f32_16x16x32_bf16 v[56:59], v[210:213], v[180:183], v[56:59]
	ds_read_b128 v[156:159], v197 offset:16384
	v_mfma_f32_16x16x32_bf16 v[52:55], v[214:217], v[180:183], v[52:55]
	ds_read_b128 v[160:163], v197 offset:18432
	v_mfma_f32_16x16x32_bf16 v[48:51], v[202:205], v[184:187], v[48:51]
	ds_read_b128 v[164:167], v151 offset:0
	v_mfma_f32_16x16x32_bf16 v[44:47], v[206:209], v[184:187], v[44:47]
	ds_read_b128 v[168:171], v151 offset:2048
	v_mfma_f32_16x16x32_bf16 v[40:43], v[210:213], v[184:187], v[40:43]
	ds_read_b128 v[172:175], v151 offset:4096
	v_mfma_f32_16x16x32_bf16 v[32:35], v[214:217], v[184:187], v[32:35]
	ds_read_b128 v[176:179], v151 offset:6144
	v_mfma_f32_16x16x32_bf16 v[36:39], v[202:205], v[188:191], v[36:39]
	s_add_u32 s98, s36, 0x80000
	s_addc_u32 s99, s37, 0
	v_lshl_add_u64 v[218:219], s[98:99], 0, v[0:1]
	s_add_i32 m0, s31, 0xc000
	v_mfma_f32_16x16x32_bf16 v[28:31], v[206:209], v[188:191], v[28:31]
	global_load_lds_dwordx4 v[218:219], off
	v_mfma_f32_16x16x32_bf16 v[24:27], v[210:213], v[188:191], v[24:27]
	v_mfma_f32_16x16x32_bf16 v[20:23], v[214:217], v[188:191], v[20:23]
	v_lshl_add_u64 v[218:219], s[98:99], 0, v[134:135]
	s_add_i32 m0, s31, 0xe000
	v_mfma_f32_16x16x32_bf16 v[16:19], v[202:205], v[192:195], v[16:19]
	global_load_lds_dwordx4 v[218:219], off
	v_mfma_f32_16x16x32_bf16 v[12:15], v[206:209], v[192:195], v[12:15]
	v_mfma_f32_16x16x32_bf16 v[8:11], v[210:213], v[192:195], v[8:11]
	v_mfma_f32_16x16x32_bf16 v[4:7], v[214:217], v[192:195], v[4:7]
	s_add_i32 s77, s77, 2
	s_add_u32 s75, s75, 0x100
	s_addc_u32 s76, s76, 0
	s_add_u32 s6, s6, 0x100
	s_addc_u32 s7, s7, 0
	s_cmp_gt_u32 s77, 29
	s_cbranch_scc0 .Lin_loop
	s_waitcnt lgkmcnt(0)
	s_mul_hi_u32 s6, s71, 0xaaaaaaab
	s_lshr_b32 s6, s6, 1
	s_mul_i32 s6, s6, 3
	s_sub_i32 s6, s71, s6
	s_lshl_b32 s6, s6, 10
	s_add_i32 s21, s6, 0
	s_add_i32 s21, s21, 0x20000
	v_lshl_add_u32 v144, s30, 8, v149
	s_cmp_gt_i32 s28, 51
	s_mov_b64 s[6:7], -1
	s_cbranch_scc0 .LBB0_187
;     __device__ __forceinline__ void operator()(AccT& acc, const pg8::Unit& u, int wr, int wc, int fr, int fq, const LAS float* rs) const {
;     ...
;         } else if (wc == 0 && fq == 0) {
; #pragma unroll
;             for (int ai = 0; ai < 2; ++ai)
; #pragma unroll
;                 for (int m = 0; m < 4; ++m) {
;                     const int row = row0 + ai * 128 + m * 16; const float sc = rsqrtf(rs[ai * 128 + wr * 64 + m * 16 + fr] * (1.0f / D) + EPS);
;                     *(f32x4*)(gates + (size_t)row * 8) = acc[ai][0][m][0] * sc; *(f32x4*)(gates + (size_t)row * 8 + 4) = acc[ai][0][m][1] * sc;
;                 }
	s_and_saveexec_b64 s[6:7], s[8:9]
	s_cbranch_execz .LBB0_186
	s_lshl_b32 s23, s55, 2
	s_add_i32 s23, s21, s23
	v_lshl_add_u32 v162, v148, 2, s23
	ds_read2_b32 v[146:147], v162 offset1:16
	v_ashrrev_i32_e32 v145, 31, v144
	v_lshlrev_b64 v[152:153], 5, v[144:145]
	v_lshl_add_u64 v[156:157], s[18:19], 0, v[152:153]
	s_mov_b64 s[34:35], 0x1000
	s_waitcnt lgkmcnt(0)
	v_fmamk_f32 v145, v146, 0x3a000000, v220
	v_mul_f32_e32 v146, 0x4b800000, v145
	v_cmp_gt_f32_e32 vcc, s96, v145
	v_fmamk_f32 v147, v147, 0x3a000000, v220
	v_mul_f32_e32 v158, 0x4b800000, v147
	v_cndmask_b32_e32 v145, v145, v146, vcc
	v_rsq_f32_e32 v145, v145
	s_nop 0
	v_mul_f32_e32 v146, 0x45800000, v145
	v_cndmask_b32_e32 v146, v145, v146, vcc
	v_cmp_gt_f32_e32 vcc, s96, v147
	v_pk_mul_f32 v[154:155], v[130:131], v[146:147] op_sel_hi:[1,0]
	v_pk_mul_f32 v[152:153], v[128:129], v[146:147] op_sel_hi:[1,0]
	v_cndmask_b32_e32 v145, v147, v158, vcc
	global_store_dwordx4 v[156:157], v[152:155], off
	v_rsq_f32_e32 v145, v145
	s_nop 0
	v_pk_mul_f32 v[154:155], v[126:127], v[146:147] op_sel_hi:[1,0]
	v_pk_mul_f32 v[152:153], v[124:125], v[146:147] op_sel_hi:[1,0]
	ds_read2_b32 v[146:147], v162 offset0:32 offset1:48
	global_store_dwordx4 v[156:157], v[152:155], off offset:16
	s_nop 1
	v_mul_f32_e32 v152, 0x45800000, v145
	v_cndmask_b32_e32 v158, v145, v152, vcc
	s_waitcnt lgkmcnt(0)
	v_fmamk_f32 v145, v146, 0x3a000000, v220
	v_mul_f32_e32 v146, 0x4b800000, v145
	v_cmp_gt_f32_e32 vcc, s96, v145
	v_pk_mul_f32 v[154:155], v[114:115], v[158:159] op_sel_hi:[1,0]
	v_pk_mul_f32 v[152:153], v[112:113], v[158:159] op_sel_hi:[1,0]
	v_cndmask_b32_e32 v145, v145, v146, vcc
	v_rsq_f32_e32 v145, v145
	global_store_dwordx4 v[156:157], v[152:155], off offset:512
	v_mul_f32_e32 v146, 0x45800000, v145
	s_nop 0
	v_pk_mul_f32 v[154:155], v[110:111], v[158:159] op_sel_hi:[1,0]
	v_pk_mul_f32 v[152:153], v[108:109], v[158:159] op_sel_hi:[1,0]
	v_cndmask_b32_e32 v146, v145, v146, vcc
	v_fmamk_f32 v145, v147, 0x3a000000, v220
	global_store_dwordx4 v[156:157], v[152:155], off offset:528
	v_cmp_gt_f32_e32 vcc, s96, v145
	s_nop 0
	v_pk_mul_f32 v[154:155], v[102:103], v[146:147] op_sel_hi:[1,0]
	v_pk_mul_f32 v[152:153], v[100:101], v[146:147] op_sel_hi:[1,0]
	v_mul_f32_e32 v147, 0x4b800000, v145
	v_cndmask_b32_e32 v145, v145, v147, vcc
	global_store_dwordx4 v[156:157], v[152:155], off offset:1024
	v_rsq_f32_e32 v145, v145
	s_nop 0
	v_pk_mul_f32 v[154:155], v[94:95], v[146:147] op_sel_hi:[1,0]
	v_pk_mul_f32 v[152:153], v[92:93], v[146:147] op_sel_hi:[1,0]
	ds_read2_b32 v[146:147], v162 offset0:128 offset1:144
	global_store_dwordx4 v[156:157], v[152:155], off offset:1040
	s_nop 1
	v_mul_f32_e32 v152, 0x45800000, v145
	v_cndmask_b32_e32 v158, v145, v152, vcc
	s_waitcnt lgkmcnt(0)
	v_fmamk_f32 v145, v146, 0x3a000000, v220
	v_mul_f32_e32 v146, 0x4b800000, v145
	v_cmp_gt_f32_e32 vcc, s96, v145
	v_pk_mul_f32 v[154:155], v[82:83], v[158:159] op_sel_hi:[1,0]
	v_pk_mul_f32 v[152:153], v[80:81], v[158:159] op_sel_hi:[1,0]
	v_cndmask_b32_e32 v145, v145, v146, vcc
	v_rsq_f32_e32 v145, v145
	global_store_dwordx4 v[156:157], v[152:155], off offset:1536
	v_mul_f32_e32 v146, 0x45800000, v145
	v_cndmask_b32_e32 v146, v145, v146, vcc
	v_add_co_u32_e32 v160, vcc, s94, v156
	v_pk_mul_f32 v[154:155], v[78:79], v[158:159] op_sel_hi:[1,0]
	v_pk_mul_f32 v[152:153], v[76:77], v[158:159] op_sel_hi:[1,0]
	v_addc_co_u32_e32 v161, vcc, 0, v157, vcc
	v_fmamk_f32 v145, v147, 0x3a000000, v220
	global_store_dwordx4 v[156:157], v[152:155], off offset:1552
	v_cmp_gt_f32_e32 vcc, s96, v145
	v_lshl_add_u64 v[158:159], v[156:157], 0, s[34:35]
	v_pk_mul_f32 v[154:155], v[66:67], v[146:147] op_sel_hi:[1,0]
	v_pk_mul_f32 v[152:153], v[64:65], v[146:147] op_sel_hi:[1,0]
	v_mul_f32_e32 v147, 0x4b800000, v145
	global_store_dwordx4 v[160:161], v[152:155], off
	v_cndmask_b32_e32 v145, v145, v147, vcc
	v_rsq_f32_e32 v145, v145
	v_pk_mul_f32 v[154:155], v[62:63], v[146:147] op_sel_hi:[1,0]
	v_pk_mul_f32 v[152:153], v[60:61], v[146:147] op_sel_hi:[1,0]
	global_store_dwordx4 v[158:159], v[152:155], off offset:16
	ds_read2_b32 v[158:159], v162 offset0:160 offset1:176
	v_mul_f32_e32 v146, 0x45800000, v145
	v_cndmask_b32_e32 v146, v145, v146, vcc
	v_pk_mul_f32 v[154:155], v[50:51], v[146:147] op_sel_hi:[1,0]
	v_pk_mul_f32 v[152:153], v[48:49], v[146:147] op_sel_hi:[1,0]
	s_waitcnt lgkmcnt(0)
	v_fmamk_f32 v145, v158, 0x3a000000, v220
	v_mul_f32_e32 v147, 0x4b800000, v145
	v_cmp_gt_f32_e32 vcc, s96, v145
	s_mov_b64 s[34:35], 0x1200
	global_store_dwordx4 v[160:161], v[152:155], off offset:512
	v_cndmask_b32_e32 v145, v145, v147, vcc
	v_rsq_f32_e32 v145, v145
	v_pk_mul_f32 v[154:155], v[46:47], v[146:147] op_sel_hi:[1,0]
	v_pk_mul_f32 v[152:153], v[44:45], v[146:147] op_sel_hi:[1,0]
	v_lshl_add_u64 v[162:163], v[156:157], 0, s[34:35]
	v_mul_f32_e32 v146, 0x45800000, v145
	v_cndmask_b32_e32 v146, v145, v146, vcc
	v_fmamk_f32 v145, v159, 0x3a000000, v220
	global_store_dwordx4 v[162:163], v[152:155], off offset:16
	v_cmp_gt_f32_e32 vcc, s96, v145
	s_mov_b64 s[34:35], 0x1400
	v_pk_mul_f32 v[154:155], v[38:39], v[146:147] op_sel_hi:[1,0]
	v_pk_mul_f32 v[152:153], v[36:37], v[146:147] op_sel_hi:[1,0]
	v_mul_f32_e32 v147, 0x4b800000, v145
	v_cndmask_b32_e32 v145, v145, v147, vcc
	v_rsq_f32_e32 v145, v145
	global_store_dwordx4 v[160:161], v[152:155], off offset:1024
	v_lshl_add_u64 v[162:163], v[156:157], 0, s[34:35]
	s_mov_b64 s[34:35], 0x1600
	v_pk_mul_f32 v[154:155], v[30:31], v[146:147] op_sel_hi:[1,0]
	v_pk_mul_f32 v[152:153], v[28:29], v[146:147] op_sel_hi:[1,0]
	v_mul_f32_e32 v146, 0x45800000, v145
	v_cndmask_b32_e32 v146, v145, v146, vcc
	global_store_dwordx4 v[162:163], v[152:155], off offset:16
	v_lshl_add_u64 v[156:157], v[156:157], 0, s[34:35]
	s_nop 0
	v_pk_mul_f32 v[154:155], v[18:19], v[146:147] op_sel_hi:[1,0]
	v_pk_mul_f32 v[152:153], v[16:17], v[146:147] op_sel_hi:[1,0]
	global_store_dwordx4 v[160:161], v[152:155], off offset:1536
	s_nop 1
	v_pk_mul_f32 v[154:155], v[14:15], v[146:147] op_sel_hi:[1,0]
	v_pk_mul_f32 v[152:153], v[12:13], v[146:147] op_sel_hi:[1,0]
	global_store_dwordx4 v[156:157], v[152:155], off offset:16

; #define PG8_WAIT_V(n) asm volatile("s_waitcnt vmcnt(" #n ")" ::: "memory")
; #define PG8_BAR __builtin_amdgcn_s_barrier()
; template <class Epi, int LDA, int LDB, int KK>
; __device__ __forceinline__ void gemm_phase(int wv, LAS unsigned char* lds, const Gemm g, const StaticOrder& S, const Epi& E) {
;     ...
;     PG8_WAIT_V(0);
;     if (wr == 0) PG8_BAR;
;     PG8_BAR;
.LBB0_189:
	s_waitcnt vmcnt(0)
	s_cmpk_gt_u32 s39, 0xff
	s_cbranch_scc1 .LBB0_191
.LBB0_191:
	s_mov_b32 s34, s2
	s_barrier

; #define LAS __attribute__((address_space(3)))
; #define PG8_STAGE(bufoff, gbase, voff) do { _Pragma("unroll") for (int _i = 0; _i < 2; ++_i) \
;         __builtin_amdgcn_global_load_lds((const unsigned*)((const char*)(gbase) + (voff)[_i]), (LAS unsigned*)(lds + (bufoff) + ldsw + _i * 8192), 16, 0, 0); } while (0)
; #define PG8_WAIT_V(n) asm volatile("s_waitcnt vmcnt(" #n ")" ::: "memory")
; #define PG8_BAR __builtin_amdgcn_s_barrier()
; template <class Epi, int LDA, int LDB, int KK>
; __device__ __forceinline__ void gemm_phase(int wv, LAS unsigned char* lds, const Gemm g, const StaticOrder& S, const Epi& E) {
;     ...
;     const char* cA = (const char*)g.A + (size_t)cur.pm * tstepA; const char* cB = (const char*)g.Bt + (size_t)cur.pn * tstepB;
;     if constexpr (Epi::ROWSCALE) { if (wid < 4) __builtin_amdgcn_global_load_lds((const unsigned*)(E.rsq + cur.pm * 256 + wid * 64 + lane), (LAS unsigned*)(lds + 131072 + wid * 256), 4, 0, 0); }
;     PG8_STAGE(PG8_SB(0, 0), cB, voffB); PG8_STAGE(PG8_SA(0, 0), cA, voffA); PG8_STAGE(PG8_SB(0, 1), cB + hstepB, voffB); PG8_STAGE(PG8_SA(0, 1), cA + hstepA, voffA);
;     if (wr == 1) PG8_BAR;
;     PG8_WAIT_V(4); PG8_BAR;
;     PG8_STAGE(PG8_SB(1, 0), cB + kstep, voffB); PG8_STAGE(PG8_SA(1, 0), cA + kstep, voffA); PG8_STAGE(PG8_SB(1, 1), cB + hstepB + kstep, voffB);
;     PG8_WAIT_V(6); PG8_BAR;
.LBB0_515:
	s_add_u32 s6, s10, 0x16b00000
	v_lshrrev_b32_e32 v11, 1, v2
	s_addc_u32 s7, s11, 0
	v_and_b32_e32 v11, 24, v11
	s_add_u32 s10, s10, 0x8400000
	v_and_b32_e32 v10, 15, v2
	v_lshlrev_b32_e32 v12, 1, v11
	v_lshlrev_b32_e32 v2, 2, v2
	s_sext_i32_i8 s23, s4
	s_addc_u32 s11, s11, 0
	v_lshl_or_b32 v197, s12, 6, v10
	v_lshl_or_b32 v10, v10, 6, v12
	s_lshl_b32 s4, s12, 13
	v_and_b32_e32 v2, 32, v2
	v_bitop3_b32 v12, v10, s4, v2 bitop3:0xde
	s_lshl_b32 s4, s5, 5
	s_and_b32 s12, s4, 0x60
	s_add_i32 m0, s36, 0x18000
	v_lshl_add_u64 v[8:9], v[8:9], 0, s[58:59]
	s_lshl_b32 s4, s12, 7
	s_waitcnt vmcnt(4)
	s_barrier
	global_load_lds_dwordx4 v[8:9], off
	v_lshl_add_u64 v[6:7], v[6:7], 0, s[58:59]
	s_add_i32 m0, s36, 0x1a000
	s_add_i32 s40, s36, 0x8000
	s_add_i32 s41, s36, 0xa000
	v_bitop3_b32 v216, v10, s4, v2 bitop3:0xde
	global_load_lds_dwordx4 v[6:7], off
	v_lshl_add_u64 v[4:5], v[4:5], 0, s[58:59]
	s_mov_b32 m0, s40
	s_add_u32 s4, s24, 0x80080
	global_load_lds_dwordx4 v[4:5], off
	v_lshl_add_u64 v[0:1], v[0:1], 0, s[58:59]
	s_mov_b32 m0, s41
	s_addc_u32 s5, s25, 0
	global_load_lds_dwordx4 v[0:1], off
	s_add_i32 m0, s36, 0x1c000
	v_lshl_add_u64 v[0:1], s[4:5], 0, v[206:207]
	global_load_lds_dwordx4 v[0:1], off
	v_lshl_add_u64 v[0:1], s[4:5], 0, v[202:203]
	s_add_i32 m0, s36, 0x1e000
	v_or_b32_e32 v217, s12, v11
	global_load_lds_dwordx4 v[0:1], off
	s_add_u32 s98, s20, 0x80080
	s_addc_u32 s99, s21, 0
	v_lshl_add_u64 v[230:231], s[98:99], 0, v[208:209]
	s_add_i32 m0, s36, 0xc000
	s_nop 0
	global_load_lds_dwordx4 v[230:231], off
	v_lshl_add_u64 v[230:231], s[98:99], 0, v[204:205]
	s_add_i32 m0, s36, 0xe000
	s_nop 0
	global_load_lds_dwordx4 v[230:231], off
	s_waitcnt vmcnt(8)
	s_mov_b32 s42, 0
	v_add_u32_e32 v218, 0, v12
	s_barrier
	s_branch .LBB0_517

; #define PG8_STAGE(bufoff, gbase, voff) do { _Pragma("unroll") for (int _i = 0; _i < 2; ++_i) \
;         __builtin_amdgcn_global_load_lds((const unsigned*)((const char*)(gbase) + (voff)[_i]), (LAS unsigned*)(lds + (bufoff) + ldsw + _i * 8192), 16, 0, 0); } while (0)
; #define PG8_LDA(dst, b, h) do { _Pragma("unroll") for (int m = 0; m < 4; ++m) _Pragma("unroll") for (int k = 0; k < 2; ++k) dst[m][k] = *(const LAS bf16x8*)(lds + PG8_SA(b, h) + aoff + m * 2048 + k * 1024); } while (0)
; #define PG8_LDB(dst, b, h) do { _Pragma("unroll") for (int n = 0; n < 2; ++n) _Pragma("unroll") for (int k = 0; k < 2; ++k) dst[n][k] = *(const LAS bf16x8*)(lds + PG8_SB(b, h) + boff + n * 2048 + k * 1024); } while (0)
; #define PG8_MMA(ai, bj, At, Bt) do { __builtin_amdgcn_s_setprio(1); _Pragma("unroll") for (int m = 0; m < 4; ++m) _Pragma("unroll") for (int n = 0; n < 2; ++n) _Pragma("unroll") for (int k = 0; k < 2; ++k) \
;         acc[ai][bj][m][n] = __builtin_amdgcn_mfma_f32_16x16x32_bf16(Bt[n][k], At[m][k], acc[ai][bj][m][n], 0, 0, 0); __builtin_amdgcn_s_setprio(0); } while (0)
; template <class Epi, int LDA, int LDB, int KK>
; __device__ __forceinline__ void gemm_phase(int wv, LAS unsigned char* lds, const Gemm g, const StaticOrder& S, const Epi& E) {
;     ...
;         for (int seg = 0, t = 0; seg < Epi::NSEG; ++seg) {
;           const int tend = Epi::HAS_MID ? (seg == 0 ? Epi::MID1 : (seg == 1 ? Epi::MID2 : nt)) : nt;
;           for (; t < tend; t += 2) {
;             const bool last = (t == nt - 2);
;             const char* a1 = cA + (size_t)(t + 1) * kstep;
;             const char* a2 = last ? nA : cA + (size_t)(t + 2) * kstep; const char* b2 = last ? nB : cB + (size_t)(t + 2) * kstep;
;             const char* a3 = a2 + kstep; const char* b3 = b2 + kstep;
;             PG8_LDB(B0, 0, 0); PG8_SCHED; PG8_LDA(At, 0, 0); PG8_STAGE(PG8_SA(1, 1), a1 + hstepA, voffA);
;             PG8_WAIT_L(8); PG8_BAR; PG8_WAIT_L(0); PG8_MMA(0, 0, At, B0); PG8_BAR; PG8_SCHED;
;             PG8_LDB(B1, 0, 1); PG8_STAGE(PG8_SB(0, 0), b2, voffB);
;             PG8_BAR; PG8_WAIT_L(0); PG8_MMA(0, 1, At, B1); PG8_BAR;
;             PG8_LDA(At, 0, 1); PG8_STAGE(PG8_SA(0, 0), a2, voffA);
;             PG8_BAR; PG8_WAIT_L(0); PG8_MMA(1, 0, At, B0); PG8_BAR; PG8_SCHED;
;             PG8_STAGE(PG8_SB(0, 1), b2 + hstepB, voffB);
;             PG8_WAIT_V(6); PG8_BAR; PG8_MMA(1, 1, At, B1); PG8_BAR;
.LBB0_521:
	s_cmp_eq_u32 s74, 1
	s_cselect_b32 s23, 24, 32
	s_cmp_lg_u32 s74, 0
	s_cselect_b32 s46, s23, 8
	s_cmp_ge_i32 s22, s46
	s_cbranch_scc1 .LBB0_524
	s_ashr_i32 s23, s22, 31
	s_lshl_b64 s[24:25], s[22:23], 7
	s_add_u32 s23, s45, s24
	s_addc_u32 s47, s70, s25
	s_add_u32 s55, s71, s24
	s_addc_u32 s56, s73, s25
	v_add_u32_e32 v0, 0x10000, v216
	ds_read_b128 v[132:135], v0 offset:0
	ds_read_b128 v[136:139], v0 offset:2048
	ds_read_b128 v[140:143], v0 offset:16384
	ds_read_b128 v[144:147], v0 offset:18432
	ds_read_b128 v[148:151], v218 offset:0
	ds_read_b128 v[152:155], v218 offset:2048
	ds_read_b128 v[156:159], v218 offset:4096
	ds_read_b128 v[160:163], v218 offset:6144
.Lmerge_loop:
	s_mov_b32 s26, s22
	s_add_i32 s22, s22, 2
	s_cmp_eq_u32 s26, 30
	s_cselect_b32 s27, s15, s56
	s_cselect_b32 s26, s43, s55
	s_cselect_b32 s25, s13, s47
	s_cselect_b32 s24, s44, s23
	s_waitcnt lgkmcnt(0)
	v_mfma_f32_16x16x32_bf16 v[128:131], v[132:135], v[148:151], v[128:131]
	ds_read_b128 v[180:183], v0 offset:1024
	v_mfma_f32_16x16x32_bf16 v[124:127], v[136:139], v[148:151], v[124:127]
	ds_read_b128 v[184:187], v0 offset:3072
	v_mfma_f32_16x16x32_bf16 v[120:123], v[140:143], v[148:151], v[120:123]
	ds_read_b128 v[188:191], v0 offset:17408
	v_mfma_f32_16x16x32_bf16 v[116:119], v[144:147], v[148:151], v[116:119]
	ds_read_b128 v[192:195], v0 offset:19456
	v_mfma_f32_16x16x32_bf16 v[112:115], v[132:135], v[152:155], v[112:115]
	ds_read_b128 v[164:167], v218 offset:1024
	v_mfma_f32_16x16x32_bf16 v[108:111], v[136:139], v[152:155], v[108:111]
	ds_read_b128 v[168:171], v218 offset:3072
	v_mfma_f32_16x16x32_bf16 v[104:107], v[140:143], v[152:155], v[104:107]
	ds_read_b128 v[172:175], v218 offset:5120
	v_mfma_f32_16x16x32_bf16 v[100:103], v[144:147], v[152:155], v[100:103]
	ds_read_b128 v[176:179], v218 offset:7168
	v_mfma_f32_16x16x32_bf16 v[96:99], v[132:135], v[156:159], v[96:99]
	v_mfma_f32_16x16x32_bf16 v[92:95], v[136:139], v[156:159], v[92:95]
	v_mfma_f32_16x16x32_bf16 v[88:91], v[140:143], v[156:159], v[88:91]
	v_mfma_f32_16x16x32_bf16 v[84:87], v[144:147], v[156:159], v[84:87]
	v_mfma_f32_16x16x32_bf16 v[80:83], v[132:135], v[160:163], v[80:83]
	v_mfma_f32_16x16x32_bf16 v[76:79], v[136:139], v[160:163], v[76:79]
	v_mfma_f32_16x16x32_bf16 v[72:75], v[140:143], v[160:163], v[72:75]
	v_mfma_f32_16x16x32_bf16 v[68:71], v[144:147], v[160:163], v[68:71]
	s_waitcnt vmcnt(8) lgkmcnt(0)
	s_barrier
	v_mfma_f32_16x16x32_bf16 v[128:131], v[180:183], v[164:167], v[128:131]
	ds_read_b128 v[148:151], v218 offset:16384
	v_mfma_f32_16x16x32_bf16 v[124:127], v[184:187], v[164:167], v[124:127]
	ds_read_b128 v[152:155], v218 offset:18432
	v_mfma_f32_16x16x32_bf16 v[120:123], v[188:191], v[164:167], v[120:123]
	ds_read_b128 v[156:159], v218 offset:20480
	v_mfma_f32_16x16x32_bf16 v[116:119], v[192:195], v[164:167], v[116:119]
	ds_read_b128 v[160:163], v218 offset:22528
	v_mfma_f32_16x16x32_bf16 v[112:115], v[180:183], v[168:171], v[112:115]
	v_lshl_add_u64 v[230:231], s[24:25], 0, v[206:207]
	s_add_i32 m0, s36, 0x10000
	v_mfma_f32_16x16x32_bf16 v[108:111], v[184:187], v[168:171], v[108:111]
	global_load_lds_dwordx4 v[230:231], off
	v_mfma_f32_16x16x32_bf16 v[104:107], v[188:191], v[168:171], v[104:107]
	v_mfma_f32_16x16x32_bf16 v[100:103], v[192:195], v[168:171], v[100:103]
	v_lshl_add_u64 v[230:231], s[24:25], 0, v[202:203]
	s_add_i32 m0, s36, 0x12000
	v_mfma_f32_16x16x32_bf16 v[96:99], v[180:183], v[172:175], v[96:99]
	global_load_lds_dwordx4 v[230:231], off
	v_mfma_f32_16x16x32_bf16 v[92:95], v[184:187], v[172:175], v[92:95]
	v_mfma_f32_16x16x32_bf16 v[88:91], v[188:191], v[172:175], v[88:91]
	v_lshl_add_u64 v[230:231], s[26:27], 0, v[208:209]
	s_mov_b32 m0, s36
	v_mfma_f32_16x16x32_bf16 v[84:87], v[192:195], v[172:175], v[84:87]
	global_load_lds_dwordx4 v[230:231], off
	v_mfma_f32_16x16x32_bf16 v[80:83], v[180:183], v[176:179], v[80:83]
	v_mfma_f32_16x16x32_bf16 v[76:79], v[184:187], v[176:179], v[76:79]
	v_mfma_f32_16x16x32_bf16 v[72:75], v[188:191], v[176:179], v[72:75]
	v_mfma_f32_16x16x32_bf16 v[68:71], v[192:195], v[176:179], v[68:71]
	s_waitcnt lgkmcnt(0)
	v_mfma_f32_16x16x32_bf16 v[64:67], v[132:135], v[148:151], v[64:67]
	ds_read_b128 v[164:167], v218 offset:17408
	v_mfma_f32_16x16x32_bf16 v[60:63], v[136:139], v[148:151], v[60:63]
	ds_read_b128 v[168:171], v218 offset:19456
	v_mfma_f32_16x16x32_bf16 v[56:59], v[140:143], v[148:151], v[56:59]
	ds_read_b128 v[172:175], v218 offset:21504
	v_mfma_f32_16x16x32_bf16 v[52:55], v[144:147], v[148:151], v[52:55]
	ds_read_b128 v[176:179], v218 offset:23552
	v_mfma_f32_16x16x32_bf16 v[48:51], v[132:135], v[152:155], v[48:51]
	v_lshl_add_u64 v[230:231], s[26:27], 0, v[204:205]
	s_add_i32 m0, s36, 0x2000
	v_mfma_f32_16x16x32_bf16 v[44:47], v[136:139], v[152:155], v[44:47]
	global_load_lds_dwordx4 v[230:231], off
	v_mfma_f32_16x16x32_bf16 v[40:43], v[140:143], v[152:155], v[40:43]
	v_mfma_f32_16x16x32_bf16 v[36:39], v[144:147], v[152:155], v[36:39]
	s_add_u32 s98, s24, 0x80000
	s_addc_u32 s99, s25, 0
	v_lshl_add_u64 v[230:231], s[98:99], 0, v[206:207]
	s_add_i32 m0, s36, 0x14000
	v_mfma_f32_16x16x32_bf16 v[32:35], v[132:135], v[156:159], v[32:35]
	global_load_lds_dwordx4 v[230:231], off
	v_mfma_f32_16x16x32_bf16 v[28:31], v[136:139], v[156:159], v[28:31]
	v_mfma_f32_16x16x32_bf16 v[24:27], v[140:143], v[156:159], v[24:27]
	v_lshl_add_u64 v[230:231], s[98:99], 0, v[202:203]
	s_add_i32 m0, s36, 0x16000
	v_mfma_f32_16x16x32_bf16 v[20:23], v[144:147], v[156:159], v[20:23]
	global_load_lds_dwordx4 v[230:231], off
	v_mfma_f32_16x16x32_bf16 v[16:19], v[132:135], v[160:163], v[16:19]
	v_mfma_f32_16x16x32_bf16 v[12:15], v[136:139], v[160:163], v[12:15]
	v_mfma_f32_16x16x32_bf16 v[8:11], v[140:143], v[160:163], v[8:11]
	v_mfma_f32_16x16x32_bf16 v[4:7], v[144:147], v[160:163], v[4:7]
	s_waitcnt vmcnt(8) lgkmcnt(0)
	s_barrier
; #define PG8_STAGE(bufoff, gbase, voff) do { _Pragma("unroll") for (int _i = 0; _i < 2; ++_i) \
;         __builtin_amdgcn_global_load_lds((const unsigned*)((const char*)(gbase) + (voff)[_i]), (LAS unsigned*)(lds + (bufoff) + ldsw + _i * 8192), 16, 0, 0); } while (0)
; #define PG8_LDA(dst, b, h) do { _Pragma("unroll") for (int m = 0; m < 4; ++m) _Pragma("unroll") for (int k = 0; k < 2; ++k) dst[m][k] = *(const LAS bf16x8*)(lds + PG8_SA(b, h) + aoff + m * 2048 + k * 1024); } while (0)
; #define PG8_LDB(dst, b, h) do { _Pragma("unroll") for (int n = 0; n < 2; ++n) _Pragma("unroll") for (int k = 0; k < 2; ++k) dst[n][k] = *(const LAS bf16x8*)(lds + PG8_SB(b, h) + boff + n * 2048 + k * 1024); } while (0)
; #define PG8_MMA(ai, bj, At, Bt) do { __builtin_amdgcn_s_setprio(1); _Pragma("unroll") for (int m = 0; m < 4; ++m) _Pragma("unroll") for (int n = 0; n < 2; ++n) _Pragma("unroll") for (int k = 0; k < 2; ++k) \
;         acc[ai][bj][m][n] = __builtin_amdgcn_mfma_f32_16x16x32_bf16(Bt[n][k], At[m][k], acc[ai][bj][m][n], 0, 0, 0); __builtin_amdgcn_s_setprio(0); } while (0)
; #define PG8_WAIT_V(n) asm volatile("s_waitcnt vmcnt(" #n ")" ::: "memory")
; #define PG8_WAIT_L(n) asm volatile("s_waitcnt lgkmcnt(" #n ")" ::: "memory")
; #define PG8_BAR __builtin_amdgcn_s_barrier()
; #define PG8_SCHED __builtin_amdgcn_sched_barrier(0)
; template <class Epi, int LDA, int LDB, int KK>
; __device__ __forceinline__ void gemm_phase(int wv, LAS unsigned char* lds, const Gemm g, const StaticOrder& S, const Epi& E) {
;     ...
;             PG8_WAIT_V(6); PG8_BAR; PG8_MMA(1, 1, At, B1); PG8_BAR;
;             PG8_LDB(B0, 1, 0); PG8_SCHED; PG8_LDA(At, 1, 0); PG8_STAGE(PG8_SA(0, 1), a2 + hstepA, voffA);
;             PG8_WAIT_L(8); PG8_BAR; PG8_WAIT_L(0); PG8_MMA(0, 0, At, B0); PG8_BAR; PG8_SCHED;
;             PG8_LDB(B1, 1, 1); PG8_STAGE(PG8_SB(1, 0), b3, voffB);
;             PG8_BAR; PG8_WAIT_L(0); PG8_MMA(0, 1, At, B1); PG8_BAR;
	v_mfma_f32_16x16x32_bf16 v[64:67], v[180:183], v[164:167], v[64:67]
	ds_read_b128 v[132:135], v0 offset:32768
	v_mfma_f32_16x16x32_bf16 v[60:63], v[184:187], v[164:167], v[60:63]
	ds_read_b128 v[136:139], v0 offset:34816
	v_mfma_f32_16x16x32_bf16 v[56:59], v[188:191], v[164:167], v[56:59]
	ds_read_b128 v[140:143], v0 offset:49152
	v_mfma_f32_16x16x32_bf16 v[52:55], v[192:195], v[164:167], v[52:55]
	ds_read_b128 v[144:147], v0 offset:51200
	v_mfma_f32_16x16x32_bf16 v[48:51], v[180:183], v[168:171], v[48:51]
	ds_read_b128 v[148:151], v218 offset:32768
	v_mfma_f32_16x16x32_bf16 v[44:47], v[184:187], v[168:171], v[44:47]
	ds_read_b128 v[152:155], v218 offset:34816
	v_mfma_f32_16x16x32_bf16 v[40:43], v[188:191], v[168:171], v[40:43]
	ds_read_b128 v[156:159], v218 offset:36864
	v_mfma_f32_16x16x32_bf16 v[36:39], v[192:195], v[168:171], v[36:39]
	ds_read_b128 v[160:163], v218 offset:38912
	v_mfma_f32_16x16x32_bf16 v[32:35], v[180:183], v[172:175], v[32:35]
	s_add_u32 s98, s26, 0x80000
	s_addc_u32 s99, s27, 0
	v_lshl_add_u64 v[230:231], s[98:99], 0, v[208:209]
	s_add_i32 m0, s36, 0x4000
	v_mfma_f32_16x16x32_bf16 v[28:31], v[184:187], v[172:175], v[28:31]
	global_load_lds_dwordx4 v[230:231], off
	v_mfma_f32_16x16x32_bf16 v[24:27], v[188:191], v[172:175], v[24:27]
	v_mfma_f32_16x16x32_bf16 v[20:23], v[192:195], v[172:175], v[20:23]
	v_lshl_add_u64 v[230:231], s[98:99], 0, v[204:205]
	s_add_i32 m0, s36, 0x6000
	v_mfma_f32_16x16x32_bf16 v[16:19], v[180:183], v[176:179], v[16:19]
	global_load_lds_dwordx4 v[230:231], off
	v_mfma_f32_16x16x32_bf16 v[12:15], v[184:187], v[176:179], v[12:15]
	v_mfma_f32_16x16x32_bf16 v[8:11], v[188:191], v[176:179], v[8:11]
	v_mfma_f32_16x16x32_bf16 v[4:7], v[192:195], v[176:179], v[4:7]
	s_add_u32 s24, s24, 0x80
	s_addc_u32 s25, s25, 0
	s_add_u32 s26, s26, 0x80
	s_addc_u32 s27, s27, 0
	s_waitcnt lgkmcnt(0)
	v_mfma_f32_16x16x32_bf16 v[128:131], v[132:135], v[148:151], v[128:131]
	ds_read_b128 v[180:183], v0 offset:33792
	v_mfma_f32_16x16x32_bf16 v[124:127], v[136:139], v[148:151], v[124:127]
	ds_read_b128 v[184:187], v0 offset:35840
	v_mfma_f32_16x16x32_bf16 v[120:123], v[140:143], v[148:151], v[120:123]
	ds_read_b128 v[188:191], v0 offset:50176
	v_mfma_f32_16x16x32_bf16 v[116:119], v[144:147], v[148:151], v[116:119]
	ds_read_b128 v[192:195], v0 offset:52224
	v_mfma_f32_16x16x32_bf16 v[112:115], v[132:135], v[152:155], v[112:115]
	ds_read_b128 v[164:167], v218 offset:33792
	v_mfma_f32_16x16x32_bf16 v[108:111], v[136:139], v[152:155], v[108:111]
	ds_read_b128 v[168:171], v218 offset:35840
	v_mfma_f32_16x16x32_bf16 v[104:107], v[140:143], v[152:155], v[104:107]
	ds_read_b128 v[172:175], v218 offset:37888
	v_mfma_f32_16x16x32_bf16 v[100:103], v[144:147], v[152:155], v[100:103]
	ds_read_b128 v[176:179], v218 offset:39936
	v_mfma_f32_16x16x32_bf16 v[96:99], v[132:135], v[156:159], v[96:99]
	v_mfma_f32_16x16x32_bf16 v[92:95], v[136:139], v[156:159], v[92:95]
	v_mfma_f32_16x16x32_bf16 v[88:91], v[140:143], v[156:159], v[88:91]
	v_mfma_f32_16x16x32_bf16 v[84:87], v[144:147], v[156:159], v[84:87]
	v_mfma_f32_16x16x32_bf16 v[80:83], v[132:135], v[160:163], v[80:83]
	v_mfma_f32_16x16x32_bf16 v[76:79], v[136:139], v[160:163], v[76:79]
	v_mfma_f32_16x16x32_bf16 v[72:75], v[140:143], v[160:163], v[72:75]
	v_mfma_f32_16x16x32_bf16 v[68:71], v[144:147], v[160:163], v[68:71]
	s_waitcnt vmcnt(8) lgkmcnt(0)
	s_barrier
; #define PG8_STAGE(bufoff, gbase, voff) do { _Pragma("unroll") for (int _i = 0; _i < 2; ++_i) \
;         __builtin_amdgcn_global_load_lds((const unsigned*)((const char*)(gbase) + (voff)[_i]), (LAS unsigned*)(lds + (bufoff) + ldsw + _i * 8192), 16, 0, 0); } while (0)
; #define PG8_LDA(dst, b, h) do { _Pragma("unroll") for (int m = 0; m < 4; ++m) _Pragma("unroll") for (int k = 0; k < 2; ++k) dst[m][k] = *(const LAS bf16x8*)(lds + PG8_SA(b, h) + aoff + m * 2048 + k * 1024); } while (0)
; #define PG8_LDB(dst, b, h) do { _Pragma("unroll") for (int n = 0; n < 2; ++n) _Pragma("unroll") for (int k = 0; k < 2; ++k) dst[n][k] = *(const LAS bf16x8*)(lds + PG8_SB(b, h) + boff + n * 2048 + k * 1024); } while (0)
; #define PG8_MMA(ai, bj, At, Bt) do { __builtin_amdgcn_s_setprio(1); _Pragma("unroll") for (int m = 0; m < 4; ++m) _Pragma("unroll") for (int n = 0; n < 2; ++n) _Pragma("unroll") for (int k = 0; k < 2; ++k) \
;         acc[ai][bj][m][n] = __builtin_amdgcn_mfma_f32_16x16x32_bf16(Bt[n][k], At[m][k], acc[ai][bj][m][n], 0, 0, 0); __builtin_amdgcn_s_setprio(0); } while (0)
; #define PG8_WAIT_V(n) asm volatile("s_waitcnt vmcnt(" #n ")" ::: "memory")
; #define PG8_WAIT_L(n) asm volatile("s_waitcnt lgkmcnt(" #n ")" ::: "memory")
; #define PG8_BAR __builtin_amdgcn_s_barrier()
; #define PG8_SCHED __builtin_amdgcn_sched_barrier(0)
; template <class Epi, int LDA, int LDB, int KK>
; __device__ __forceinline__ void gemm_phase(int wv, LAS unsigned char* lds, const Gemm g, const StaticOrder& S, const Epi& E) {
;     ...
;             PG8_WAIT_L(8); PG8_BAR; PG8_WAIT_L(0); PG8_MMA(0, 0, At, B0); PG8_BAR; PG8_SCHED;
;             PG8_LDB(B1, 1, 1); PG8_STAGE(PG8_SB(1, 0), b3, voffB);
;             PG8_BAR; PG8_WAIT_L(0); PG8_MMA(0, 1, At, B1); PG8_BAR;
;             PG8_LDA(At, 1, 1); PG8_STAGE(PG8_SA(1, 0), a3, voffA);
;             PG8_BAR; PG8_WAIT_L(0); PG8_MMA(1, 0, At, B0); PG8_BAR; PG8_SCHED;
;             PG8_STAGE(PG8_SB(1, 1), b3 + hstepB, voffB);
;             PG8_WAIT_V(6); PG8_BAR; PG8_MMA(1, 1, At, B1); PG8_BAR;
;           }
;           if constexpr (Epi::HAS_MID) { if (seg < Epi::NSEG - 1) E.mid(acc, cur, seg, wr, wc, fr, fq); }
;         }
	v_mfma_f32_16x16x32_bf16 v[128:131], v[180:183], v[164:167], v[128:131]
	ds_read_b128 v[148:151], v218 offset:49152
	v_mfma_f32_16x16x32_bf16 v[124:127], v[184:187], v[164:167], v[124:127]
	ds_read_b128 v[152:155], v218 offset:51200
	v_mfma_f32_16x16x32_bf16 v[120:123], v[188:191], v[164:167], v[120:123]
	ds_read_b128 v[156:159], v218 offset:53248
	v_mfma_f32_16x16x32_bf16 v[116:119], v[192:195], v[164:167], v[116:119]
	ds_read_b128 v[160:163], v218 offset:55296
	v_mfma_f32_16x16x32_bf16 v[112:115], v[180:183], v[168:171], v[112:115]
	v_lshl_add_u64 v[230:231], s[24:25], 0, v[206:207]
	s_add_i32 m0, s36, 0x18000
	v_mfma_f32_16x16x32_bf16 v[108:111], v[184:187], v[168:171], v[108:111]
	global_load_lds_dwordx4 v[230:231], off
	v_mfma_f32_16x16x32_bf16 v[104:107], v[188:191], v[168:171], v[104:107]
	v_mfma_f32_16x16x32_bf16 v[100:103], v[192:195], v[168:171], v[100:103]
	v_lshl_add_u64 v[230:231], s[24:25], 0, v[202:203]
	s_add_i32 m0, s36, 0x1a000
	v_mfma_f32_16x16x32_bf16 v[96:99], v[180:183], v[172:175], v[96:99]
	global_load_lds_dwordx4 v[230:231], off
	v_mfma_f32_16x16x32_bf16 v[92:95], v[184:187], v[172:175], v[92:95]
	v_mfma_f32_16x16x32_bf16 v[88:91], v[188:191], v[172:175], v[88:91]
	v_lshl_add_u64 v[230:231], s[26:27], 0, v[208:209]
	s_add_i32 m0, s36, 0x8000
	v_mfma_f32_16x16x32_bf16 v[84:87], v[192:195], v[172:175], v[84:87]
	global_load_lds_dwordx4 v[230:231], off
	v_mfma_f32_16x16x32_bf16 v[80:83], v[180:183], v[176:179], v[80:83]
	v_mfma_f32_16x16x32_bf16 v[76:79], v[184:187], v[176:179], v[76:79]
	v_mfma_f32_16x16x32_bf16 v[72:75], v[188:191], v[176:179], v[72:75]
	v_mfma_f32_16x16x32_bf16 v[68:71], v[192:195], v[176:179], v[68:71]
	s_waitcnt lgkmcnt(0)
	v_mfma_f32_16x16x32_bf16 v[64:67], v[132:135], v[148:151], v[64:67]
	ds_read_b128 v[164:167], v218 offset:50176
	v_mfma_f32_16x16x32_bf16 v[60:63], v[136:139], v[148:151], v[60:63]
	ds_read_b128 v[168:171], v218 offset:52224
	v_mfma_f32_16x16x32_bf16 v[56:59], v[140:143], v[148:151], v[56:59]
	ds_read_b128 v[172:175], v218 offset:54272
	v_mfma_f32_16x16x32_bf16 v[52:55], v[144:147], v[148:151], v[52:55]
	ds_read_b128 v[176:179], v218 offset:56320
	v_mfma_f32_16x16x32_bf16 v[48:51], v[132:135], v[152:155], v[48:51]
	v_lshl_add_u64 v[230:231], s[26:27], 0, v[204:205]
	s_add_i32 m0, s36, 0xa000
	v_mfma_f32_16x16x32_bf16 v[44:47], v[136:139], v[152:155], v[44:47]
	global_load_lds_dwordx4 v[230:231], off
	v_mfma_f32_16x16x32_bf16 v[40:43], v[140:143], v[152:155], v[40:43]
	v_mfma_f32_16x16x32_bf16 v[36:39], v[144:147], v[152:155], v[36:39]
	s_add_u32 s98, s24, 0x80000
	s_addc_u32 s99, s25, 0
	v_lshl_add_u64 v[230:231], s[98:99], 0, v[206:207]
	s_add_i32 m0, s36, 0x1c000
	v_mfma_f32_16x16x32_bf16 v[32:35], v[132:135], v[156:159], v[32:35]
	global_load_lds_dwordx4 v[230:231], off
	v_mfma_f32_16x16x32_bf16 v[28:31], v[136:139], v[156:159], v[28:31]
	v_mfma_f32_16x16x32_bf16 v[24:27], v[140:143], v[156:159], v[24:27]
	v_lshl_add_u64 v[230:231], s[98:99], 0, v[202:203]
	s_add_i32 m0, s36, 0x1e000
	v_mfma_f32_16x16x32_bf16 v[20:23], v[144:147], v[156:159], v[20:23]
	global_load_lds_dwordx4 v[230:231], off
	v_mfma_f32_16x16x32_bf16 v[16:19], v[132:135], v[160:163], v[16:19]
	v_mfma_f32_16x16x32_bf16 v[12:15], v[136:139], v[160:163], v[12:15]
	v_mfma_f32_16x16x32_bf16 v[8:11], v[140:143], v[160:163], v[8:11]
	v_mfma_f32_16x16x32_bf16 v[4:7], v[144:147], v[160:163], v[4:7]
	s_waitcnt vmcnt(8) lgkmcnt(0)
	s_barrier
	v_mfma_f32_16x16x32_bf16 v[64:67], v[180:183], v[164:167], v[64:67]
	ds_read_b128 v[132:135], v0 offset:0
	v_mfma_f32_16x16x32_bf16 v[60:63], v[184:187], v[164:167], v[60:63]
	ds_read_b128 v[136:139], v0 offset:2048
	v_mfma_f32_16x16x32_bf16 v[56:59], v[188:191], v[164:167], v[56:59]
	ds_read_b128 v[140:143], v0 offset:16384
	v_mfma_f32_16x16x32_bf16 v[52:55], v[192:195], v[164:167], v[52:55]
	ds_read_b128 v[144:147], v0 offset:18432
	v_mfma_f32_16x16x32_bf16 v[48:51], v[180:183], v[168:171], v[48:51]
	ds_read_b128 v[148:151], v218 offset:0
	v_mfma_f32_16x16x32_bf16 v[44:47], v[184:187], v[168:171], v[44:47]
	ds_read_b128 v[152:155], v218 offset:2048
	v_mfma_f32_16x16x32_bf16 v[40:43], v[188:191], v[168:171], v[40:43]
	ds_read_b128 v[156:159], v218 offset:4096
	v_mfma_f32_16x16x32_bf16 v[36:39], v[192:195], v[168:171], v[36:39]
	ds_read_b128 v[160:163], v218 offset:6144
	v_mfma_f32_16x16x32_bf16 v[32:35], v[180:183], v[172:175], v[32:35]
	s_add_u32 s98, s26, 0x80000
	s_addc_u32 s99, s27, 0
	v_lshl_add_u64 v[230:231], s[98:99], 0, v[208:209]
	s_add_i32 m0, s36, 0xc000
	v_mfma_f32_16x16x32_bf16 v[28:31], v[184:187], v[172:175], v[28:31]
	global_load_lds_dwordx4 v[230:231], off
	v_mfma_f32_16x16x32_bf16 v[24:27], v[188:191], v[172:175], v[24:27]
	v_mfma_f32_16x16x32_bf16 v[20:23], v[192:195], v[172:175], v[20:23]
	v_lshl_add_u64 v[230:231], s[98:99], 0, v[204:205]
	s_add_i32 m0, s36, 0xe000
	v_mfma_f32_16x16x32_bf16 v[16:19], v[180:183], v[176:179], v[16:19]
	global_load_lds_dwordx4 v[230:231], off
	v_mfma_f32_16x16x32_bf16 v[12:15], v[184:187], v[176:179], v[12:15]
	v_mfma_f32_16x16x32_bf16 v[8:11], v[188:191], v[176:179], v[8:11]
	v_mfma_f32_16x16x32_bf16 v[4:7], v[192:195], v[176:179], v[4:7]
	s_add_u32 s23, s23, 0x100
	s_addc_u32 s47, s47, 0
	s_add_u32 s55, s55, 0x100
	s_addc_u32 s56, s56, 0
	s_cmp_lt_i32 s22, s46
	s_cbranch_scc1 .Lmerge_loop
	s_waitcnt lgkmcnt(0)

; #define PG8_WAIT_V(n) asm volatile("s_waitcnt vmcnt(" #n ")" ::: "memory")
; #define PG8_BAR __builtin_amdgcn_s_barrier()
; template <class Epi, int LDA, int LDB, int KK>
; __device__ __forceinline__ void gemm_phase(int wv, LAS unsigned char* lds, const Gemm g, const StaticOrder& S, const Epi& E) {
;     ...
;     PG8_WAIT_V(0);
;     if (wr == 0) PG8_BAR;
;     PG8_BAR;
.LBB0_526:
	s_waitcnt vmcnt(0)
	s_cmpk_gt_u32 s29, 0xff
	s_cbranch_scc1 .LBB0_528
.LBB0_528:
	s_mov_b32 s34, s2
	s_barrier

; #define LAS __attribute__((address_space(3)))
; #define PG8_STAGE(bufoff, gbase, voff) do { _Pragma("unroll") for (int _i = 0; _i < 2; ++_i) \
;         __builtin_amdgcn_global_load_lds((const unsigned*)((const char*)(gbase) + (voff)[_i]), (LAS unsigned*)(lds + (bufoff) + ldsw + _i * 8192), 16, 0, 0); } while (0)
; #define PG8_WAIT_V(n) asm volatile("s_waitcnt vmcnt(" #n ")" ::: "memory")
; #define PG8_BAR __builtin_amdgcn_s_barrier()
; template <class Epi, int LDA, int LDB, int KK>
; __device__ __forceinline__ void gemm_phase(int wv, LAS unsigned char* lds, const Gemm g, const StaticOrder& S, const Epi& E) {
;     ...
;     const char* cA = (const char*)g.A + (size_t)cur.pm * tstepA; const char* cB = (const char*)g.Bt + (size_t)cur.pn * tstepB;
;     if constexpr (Epi::ROWSCALE) { if (wid < 4) __builtin_amdgcn_global_load_lds((const unsigned*)(E.rsq + cur.pm * 256 + wid * 64 + lane), (LAS unsigned*)(lds + 131072 + wid * 256), 4, 0, 0); }
;     PG8_STAGE(PG8_SB(0, 0), cB, voffB); PG8_STAGE(PG8_SA(0, 0), cA, voffA); PG8_STAGE(PG8_SB(0, 1), cB + hstepB, voffB); PG8_STAGE(PG8_SA(0, 1), cA + hstepA, voffA);
;     if (wr == 1) PG8_BAR;
;     PG8_WAIT_V(4); PG8_BAR;
;     PG8_STAGE(PG8_SB(1, 0), cB + kstep, voffB); PG8_STAGE(PG8_SA(1, 0), cA + kstep, voffA); PG8_STAGE(PG8_SB(1, 1), cB + hstepB + kstep, voffB);
;     PG8_WAIT_V(6); PG8_BAR;
.LBB0_617:
	v_readlane_b32 s12, v254, 28
	v_readlane_b32 s13, v254, 29
	s_lshl_b64 s[12:13], s[12:13], 2
	s_sext_i32_i8 s23, s4
	s_add_u32 s4, s10, s12
	v_and_b32_e32 v19, 15, v18
	v_bfe_u32 v18, v18, 4, 2
	s_addc_u32 s7, s11, s13
	v_lshlrev_b32_e32 v20, 4, v18
	s_add_u32 s12, s4, 0x27c94800
	v_lshl_or_b32 v197, s6, 6, v19
	v_lshl_or_b32 v20, v19, 6, v20
	v_lshlrev_b32_e32 v19, 2, v19
	s_addc_u32 s13, s7, 0
	s_lshl_b32 s4, s6, 13
	v_and_b32_e32 v21, 32, v19
	v_bitop3_b32 v22, v20, s4, v21 bitop3:0xde
	s_lshl_b32 s4, s5, 5
	s_and_b32 s6, s4, 0x60
	s_add_i32 m0, s40, 0x18000
	v_lshl_add_u64 v[10:11], v[10:11], 0, s[58:59]
	s_lshl_b32 s4, s6, 7
	s_waitcnt vmcnt(4)
	s_barrier
	global_load_lds_dwordx4 v[10:11], off
	v_lshl_add_u64 v[8:9], v[8:9], 0, s[58:59]
	s_add_i32 m0, s40, 0x1a000
	s_add_i32 s44, s40, 0x8000
	s_add_i32 s45, s40, 0xa000
	v_bitop3_b32 v230, v20, s4, v21 bitop3:0xde
	global_load_lds_dwordx4 v[8:9], off
	v_lshl_add_u64 v[6:7], v[6:7], 0, s[58:59]
	s_mov_b32 m0, s44
	s_add_u32 s4, s24, 0x80080
	global_load_lds_dwordx4 v[6:7], off
	v_lshl_add_u64 v[4:5], v[4:5], 0, s[58:59]
	s_mov_b32 m0, s45
	s_addc_u32 s5, s25, 0
	global_load_lds_dwordx4 v[4:5], off
	s_add_i32 m0, s40, 0x1c000
	v_lshl_add_u64 v[4:5], s[4:5], 0, v[2:3]
	global_load_lds_dwordx4 v[4:5], off
	v_lshl_add_u64 v[4:5], s[4:5], 0, v[0:1]
	s_add_i32 m0, s40, 0x1e000
	s_movk_i32 s4, 0x80
	global_load_lds_dwordx4 v[4:5], off
	s_add_u32 s98, s26, 0x80080
	s_addc_u32 s99, s27, 0
	v_lshl_add_u64 v[182:183], s[98:99], 0, v[190:191]
	s_add_i32 m0, s40, 0xc000
	s_nop 0
	global_load_lds_dwordx4 v[182:183], off
	v_lshl_add_u64 v[182:183], s[98:99], 0, v[188:189]
	s_add_i32 m0, s40, 0xe000
	s_nop 0
	global_load_lds_dwordx4 v[182:183], off
	v_lshlrev_b32_e32 v4, 6, v18
	v_bitop3_b32 v231, v4, 64, v19 bitop3:0x36
	v_bitop3_b32 v232, v4, s4, v19 bitop3:0x36
	v_lshlrev_b32_e32 v4, 15, v12
	v_and_b32_e32 v4, 0xffff0000, v4
	v_lshl_add_u32 v4, v13, 12, v4
	v_and_b32_e32 v5, 1, v12
	v_lshl_or_b32 v4, v5, 6, v4
	v_lshl_add_u32 v192, v14, 1, v4
	v_lshlrev_b32_e32 v4, 15, v16
	v_and_b32_e32 v4, 0xffff0000, v4
	s_waitcnt vmcnt(8)
	v_lshl_add_u32 v4, v15, 12, v4
	v_and_b32_e32 v5, 1, v16
	v_lshl_or_b32 v4, v5, 6, v4
	s_mov_b32 s46, 0
	v_cmp_eq_u32_e64 s[4:5], 0, v18
	v_lshl_or_b32 v233, v18, 3, s6
	v_mov_b32_e32 v193, v3
	v_lshl_add_u32 v194, v17, 1, v4
	v_mov_b32_e32 v195, v3
	v_add_u32_e32 v234, 0, v22
	s_barrier
	s_branch .LBB0_619

; #define LAS __attribute__((address_space(3)))
; #define PG8_STAGE(bufoff, gbase, voff) do { _Pragma("unroll") for (int _i = 0; _i < 2; ++_i) \
;         __builtin_amdgcn_global_load_lds((const unsigned*)((const char*)(gbase) + (voff)[_i]), (LAS unsigned*)(lds + (bufoff) + ldsw + _i * 8192), 16, 0, 0); } while (0)
; #define PG8_LDA(dst, b, h) do { _Pragma("unroll") for (int m = 0; m < 4; ++m) _Pragma("unroll") for (int k = 0; k < 2; ++k) dst[m][k] = *(const LAS bf16x8*)(lds + PG8_SA(b, h) + aoff + m * 2048 + k * 1024); } while (0)
; #define PG8_WAIT_L(n) asm volatile("s_waitcnt lgkmcnt(" #n ")" ::: "memory")
; #define PG8_BAR __builtin_amdgcn_s_barrier()
; template <class Epi, int LDA, int LDB, int KK>
; __device__ __forceinline__ void gemm_phase(int wv, LAS unsigned char* lds, const Gemm g, const StaticOrder& S, const Epi& E) {
;     ...
;     for (;;) {
;         const bool has_next = S.next(ui + 1, nxt);
;         const char* nA = has_next ? (const char*)g.A + (size_t)nxt.pm * tstepA : cA; const char* nB = has_next ? (const char*)g.Bt + (size_t)nxt.pn * tstepB : cB;
;         if constexpr (Epi::ROWSCALE) { if (has_next && wid < 4) __builtin_amdgcn_global_load_lds((const unsigned*)(E.rsq + nxt.pm * 256 + wid * 64 + lane), (LAS unsigned*)(lds + 131072 + ((ui + 1) % 3) * 1024 + wid * 256), 4, 0, 0); }
;         for (int seg = 0, t = 0; seg < Epi::NSEG; ++seg) {
;           const int tend = Epi::HAS_MID ? (seg == 0 ? Epi::MID1 : (seg == 1 ? Epi::MID2 : nt)) : nt;
;           for (; t < tend; t += 2) {
;             const bool last = (t == nt - 2);
;             const char* a1 = cA + (size_t)(t + 1) * kstep;
;             const char* a2 = last ? nA : cA + (size_t)(t + 2) * kstep; const char* b2 = last ? nB : cB + (size_t)(t + 2) * kstep;
;             const char* a3 = a2 + kstep; const char* b3 = b2 + kstep;
;             PG8_LDB(B0, 0, 0); PG8_SCHED; PG8_LDA(At, 0, 0); PG8_STAGE(PG8_SA(1, 1), a1 + hstepA, voffA);
;             PG8_WAIT_L(8); PG8_BAR; PG8_WAIT_L(0); PG8_MMA(0, 0, At, B0); PG8_BAR; PG8_SCHED;
;     ...
; #pragma unroll
;         for (int a = 0; a < 2; ++a)
; #pragma unroll
;             for (int b = 0; b < 2; ++b)
; #pragma unroll
;                 for (int m = 0; m < 4; ++m)
; #pragma unroll
;                     for (int n = 0; n < 2; ++n) acc[a][b][m][n] = (f32x4){0.f, 0.f, 0.f, 0.f};
;         cur = nxt; cA = nA; cB = nB; ++ui;
.LBB0_621:
	s_ashr_i32 s17, s16, 31
	v_cmp_lt_i64_e32 vcc, s[18:19], v[200:201]
	s_lshl_b64 s[18:19], s[16:17], 20
	s_add_u32 s18, s34, s18
	s_addc_u32 s19, s35, s19
	s_and_b64 s[20:21], vcc, exec
	s_cselect_b32 s17, s19, s27
	s_cselect_b32 s47, s18, s26
	s_ashr_i32 s15, s14, 31
	s_lshl_b64 s[20:21], s[14:15], 20
	s_add_u32 s20, s36, s20
	s_addc_u32 s21, s37, s21
	s_and_b64 s[28:29], vcc, exec
	s_cselect_b32 s15, s21, s25
	s_cselect_b32 s55, s20, s24
	s_add_u32 s56, s24, 0x100
	s_addc_u32 s68, s25, 0
	s_add_u32 s24, s26, 0x80080
	v_mov_b32_e32 v4, 0
	s_addc_u32 s25, s27, 0
	s_mov_b32 s69, -2
	s_waitcnt lgkmcnt(0)
	v_mov_b32_e32 v5, v4
	v_mov_b32_e32 v6, v4
	v_mov_b32_e32 v7, v4
	v_mov_b32_e32 v8, v4
	v_mov_b32_e32 v9, v4
	v_mov_b32_e32 v10, v4
	v_mov_b32_e32 v11, v4
	v_mov_b32_e32 v20, v4
	v_mov_b32_e32 v21, v4
	v_mov_b32_e32 v22, v4
	v_mov_b32_e32 v23, v4
	v_mov_b32_e32 v24, v4
	v_mov_b32_e32 v25, v4
	v_mov_b32_e32 v26, v4
	v_mov_b32_e32 v27, v4
	v_mov_b32_e32 v36, v4
	v_mov_b32_e32 v37, v4
	v_mov_b32_e32 v38, v4
	v_mov_b32_e32 v39, v4
	v_mov_b32_e32 v40, v4
	v_mov_b32_e32 v41, v4
	v_mov_b32_e32 v42, v4
	v_mov_b32_e32 v43, v4
	v_mov_b32_e32 v52, v4
	v_mov_b32_e32 v53, v4
	v_mov_b32_e32 v54, v4
	v_mov_b32_e32 v55, v4
	v_mov_b32_e32 v56, v4
	v_mov_b32_e32 v57, v4
	v_mov_b32_e32 v58, v4
	v_mov_b32_e32 v59, v4
	v_mov_b32_e32 v12, v4
	v_mov_b32_e32 v13, v4
	v_mov_b32_e32 v14, v4
	v_mov_b32_e32 v15, v4
	v_mov_b32_e32 v16, v4
	v_mov_b32_e32 v17, v4
	v_mov_b32_e32 v18, v4
	v_mov_b32_e32 v19, v4
	v_mov_b32_e32 v28, v4
	v_mov_b32_e32 v29, v4
	v_mov_b32_e32 v30, v4
	v_mov_b32_e32 v31, v4
	v_mov_b32_e32 v32, v4
	v_mov_b32_e32 v33, v4
	v_mov_b32_e32 v34, v4
	v_mov_b32_e32 v35, v4
	v_mov_b32_e32 v44, v4
	v_mov_b32_e32 v45, v4
	v_mov_b32_e32 v46, v4
	v_mov_b32_e32 v47, v4
	v_mov_b32_e32 v48, v4
	v_mov_b32_e32 v49, v4
	v_mov_b32_e32 v50, v4
	v_mov_b32_e32 v51, v4
	v_mov_b32_e32 v60, v4
	v_mov_b32_e32 v61, v4
	v_mov_b32_e32 v62, v4
	v_mov_b32_e32 v63, v4
	v_mov_b32_e32 v64, v4
	v_mov_b32_e32 v65, v4
	v_mov_b32_e32 v66, v4
	v_mov_b32_e32 v67, v4
	v_mov_b32_e32 v68, v4
	v_mov_b32_e32 v69, v4
	v_mov_b32_e32 v70, v4
	v_mov_b32_e32 v71, v4
	v_mov_b32_e32 v72, v4
	v_mov_b32_e32 v73, v4
	v_mov_b32_e32 v74, v4
	v_mov_b32_e32 v75, v4
	v_mov_b32_e32 v84, v4
	v_mov_b32_e32 v85, v4
	v_mov_b32_e32 v86, v4
	v_mov_b32_e32 v87, v4
	v_mov_b32_e32 v88, v4
	v_mov_b32_e32 v89, v4
	v_mov_b32_e32 v90, v4
	v_mov_b32_e32 v91, v4
	v_mov_b32_e32 v100, v4
	v_mov_b32_e32 v101, v4
	v_mov_b32_e32 v102, v4
	v_mov_b32_e32 v103, v4
	v_mov_b32_e32 v104, v4
	v_mov_b32_e32 v105, v4
	v_mov_b32_e32 v106, v4
	v_mov_b32_e32 v107, v4
	v_mov_b32_e32 v116, v4
	v_mov_b32_e32 v117, v4
	v_mov_b32_e32 v118, v4
	v_mov_b32_e32 v119, v4
	v_mov_b32_e32 v120, v4
	v_mov_b32_e32 v121, v4
	v_mov_b32_e32 v122, v4
	v_mov_b32_e32 v123, v4
	v_mov_b32_e32 v76, v4
	v_mov_b32_e32 v77, v4
	v_mov_b32_e32 v78, v4
	v_mov_b32_e32 v79, v4
	v_mov_b32_e32 v80, v4
	v_mov_b32_e32 v81, v4
	v_mov_b32_e32 v82, v4
	v_mov_b32_e32 v83, v4
	v_mov_b32_e32 v92, v4
	v_mov_b32_e32 v93, v4
	v_mov_b32_e32 v94, v4
	v_mov_b32_e32 v95, v4
	v_mov_b32_e32 v96, v4
	v_mov_b32_e32 v97, v4
	v_mov_b32_e32 v98, v4
	v_mov_b32_e32 v99, v4
	v_mov_b32_e32 v108, v4
	v_mov_b32_e32 v109, v4
	v_mov_b32_e32 v110, v4
	v_mov_b32_e32 v111, v4
	v_mov_b32_e32 v112, v4
	v_mov_b32_e32 v113, v4
	v_mov_b32_e32 v114, v4
	v_mov_b32_e32 v115, v4
	v_mov_b32_e32 v124, v4
	v_mov_b32_e32 v125, v4
	v_mov_b32_e32 v126, v4
	v_mov_b32_e32 v127, v4
	v_mov_b32_e32 v128, v4
	v_mov_b32_e32 v129, v4
	v_mov_b32_e32 v130, v4
	v_mov_b32_e32 v131, v4
	v_add_u32_e32 v180, 0x10000, v230
	ds_read_b128 v[132:135], v180 offset:0
	ds_read_b128 v[136:139], v180 offset:2048
	ds_read_b128 v[140:143], v180 offset:16384
	ds_read_b128 v[144:147], v180 offset:18432
	ds_read_b128 v[148:151], v234 offset:0
	ds_read_b128 v[152:155], v234 offset:2048
	ds_read_b128 v[156:159], v234 offset:4096
	ds_read_b128 v[160:163], v234 offset:6144
.Lout_loop:
	s_add_u32 s26, s24, 0xfff80080
	s_addc_u32 s27, s25, -1
	s_cmp_eq_u32 s69, 28
	s_cselect_b32 s29, s17, s27
	s_cselect_b32 s28, s47, s26
	s_cselect_b32 s27, s15, s68
	s_cselect_b32 s26, s55, s56
	s_waitcnt lgkmcnt(0)
	v_mfma_f32_16x16x32_bf16 v[128:131], v[132:135], v[148:151], v[128:131]
	ds_read_b128 v[202:205], v180 offset:1024
	v_mfma_f32_16x16x32_bf16 v[124:127], v[136:139], v[148:151], v[124:127]
	ds_read_b128 v[206:209], v180 offset:3072
	v_mfma_f32_16x16x32_bf16 v[120:123], v[140:143], v[148:151], v[120:123]
	ds_read_b128 v[210:213], v180 offset:17408
	v_mfma_f32_16x16x32_bf16 v[116:119], v[144:147], v[148:151], v[116:119]
	ds_read_b128 v[214:217], v180 offset:19456
	v_mfma_f32_16x16x32_bf16 v[112:115], v[132:135], v[152:155], v[112:115]
	ds_read_b128 v[164:167], v234 offset:1024
	v_mfma_f32_16x16x32_bf16 v[108:111], v[136:139], v[152:155], v[108:111]
	ds_read_b128 v[168:171], v234 offset:3072
	v_mfma_f32_16x16x32_bf16 v[104:107], v[140:143], v[152:155], v[104:107]
	ds_read_b128 v[172:175], v234 offset:5120
	v_mfma_f32_16x16x32_bf16 v[100:103], v[144:147], v[152:155], v[100:103]
	ds_read_b128 v[176:179], v234 offset:7168
	v_mfma_f32_16x16x32_bf16 v[96:99], v[132:135], v[156:159], v[96:99]
	v_mfma_f32_16x16x32_bf16 v[92:95], v[136:139], v[156:159], v[92:95]
	v_mfma_f32_16x16x32_bf16 v[88:91], v[140:143], v[156:159], v[88:91]
	v_mfma_f32_16x16x32_bf16 v[84:87], v[144:147], v[156:159], v[84:87]
	v_mfma_f32_16x16x32_bf16 v[80:83], v[132:135], v[160:163], v[80:83]
	v_mfma_f32_16x16x32_bf16 v[76:79], v[136:139], v[160:163], v[76:79]
	v_mfma_f32_16x16x32_bf16 v[72:75], v[140:143], v[160:163], v[72:75]
	v_mfma_f32_16x16x32_bf16 v[68:71], v[144:147], v[160:163], v[68:71]
	s_waitcnt vmcnt(8) lgkmcnt(0)
	s_barrier
; #define PG8_STAGE(bufoff, gbase, voff) do { _Pragma("unroll") for (int _i = 0; _i < 2; ++_i) \
;         __builtin_amdgcn_global_load_lds((const unsigned*)((const char*)(gbase) + (voff)[_i]), (LAS unsigned*)(lds + (bufoff) + ldsw + _i * 8192), 16, 0, 0); } while (0)
; #define PG8_LDA(dst, b, h) do { _Pragma("unroll") for (int m = 0; m < 4; ++m) _Pragma("unroll") for (int k = 0; k < 2; ++k) dst[m][k] = *(const LAS bf16x8*)(lds + PG8_SA(b, h) + aoff + m * 2048 + k * 1024); } while (0)
; #define PG8_LDB(dst, b, h) do { _Pragma("unroll") for (int n = 0; n < 2; ++n) _Pragma("unroll") for (int k = 0; k < 2; ++k) dst[n][k] = *(const LAS bf16x8*)(lds + PG8_SB(b, h) + boff + n * 2048 + k * 1024); } while (0)
; #define PG8_MMA(ai, bj, At, Bt) do { __builtin_amdgcn_s_setprio(1); _Pragma("unroll") for (int m = 0; m < 4; ++m) _Pragma("unroll") for (int n = 0; n < 2; ++n) _Pragma("unroll") for (int k = 0; k < 2; ++k) \
;         acc[ai][bj][m][n] = __builtin_amdgcn_mfma_f32_16x16x32_bf16(Bt[n][k], At[m][k], acc[ai][bj][m][n], 0, 0, 0); __builtin_amdgcn_s_setprio(0); } while (0)
; #define PG8_WAIT_V(n) asm volatile("s_waitcnt vmcnt(" #n ")" ::: "memory")
; #define PG8_WAIT_L(n) asm volatile("s_waitcnt lgkmcnt(" #n ")" ::: "memory")
; #define PG8_BAR __builtin_amdgcn_s_barrier()
; #define PG8_SCHED __builtin_amdgcn_sched_barrier(0)
; template <class Epi, int LDA, int LDB, int KK>
; __device__ __forceinline__ void gemm_phase(int wv, LAS unsigned char* lds, const Gemm g, const StaticOrder& S, const Epi& E) {
;     ...
;             PG8_LDB(B1, 0, 1); PG8_STAGE(PG8_SB(0, 0), b2, voffB);
;             PG8_BAR; PG8_WAIT_L(0); PG8_MMA(0, 1, At, B1); PG8_BAR;
;             PG8_LDA(At, 0, 1); PG8_STAGE(PG8_SA(0, 0), a2, voffA);
;             PG8_BAR; PG8_WAIT_L(0); PG8_MMA(1, 0, At, B0); PG8_BAR; PG8_SCHED;
;             PG8_STAGE(PG8_SB(0, 1), b2 + hstepB, voffB);
;             PG8_WAIT_V(6); PG8_BAR; PG8_MMA(1, 1, At, B1); PG8_BAR;
;             PG8_LDB(B0, 1, 0); PG8_SCHED; PG8_LDA(At, 1, 0); PG8_STAGE(PG8_SA(0, 1), a2 + hstepA, voffA);
;             PG8_WAIT_L(8); PG8_BAR; PG8_WAIT_L(0); PG8_MMA(0, 0, At, B0); PG8_BAR; PG8_SCHED;
;             PG8_LDB(B1, 1, 1); PG8_STAGE(PG8_SB(1, 0), b3, voffB);
;             PG8_BAR; PG8_WAIT_L(0); PG8_MMA(0, 1, At, B1); PG8_BAR;
	v_mfma_f32_16x16x32_bf16 v[128:131], v[202:205], v[164:167], v[128:131]
	ds_read_b128 v[148:151], v234 offset:16384
	v_mfma_f32_16x16x32_bf16 v[124:127], v[206:209], v[164:167], v[124:127]
	ds_read_b128 v[152:155], v234 offset:18432
	v_mfma_f32_16x16x32_bf16 v[120:123], v[210:213], v[164:167], v[120:123]
	ds_read_b128 v[156:159], v234 offset:20480
	v_mfma_f32_16x16x32_bf16 v[116:119], v[214:217], v[164:167], v[116:119]
	ds_read_b128 v[160:163], v234 offset:22528
	v_mfma_f32_16x16x32_bf16 v[112:115], v[202:205], v[168:171], v[112:115]
	v_lshl_add_u64 v[182:183], s[26:27], 0, v[2:3]
	s_add_i32 m0, s40, 0x10000
	v_mfma_f32_16x16x32_bf16 v[108:111], v[206:209], v[168:171], v[108:111]
	global_load_lds_dwordx4 v[182:183], off
	v_mfma_f32_16x16x32_bf16 v[104:107], v[210:213], v[168:171], v[104:107]
	v_mfma_f32_16x16x32_bf16 v[100:103], v[214:217], v[168:171], v[100:103]
	v_lshl_add_u64 v[182:183], s[26:27], 0, v[0:1]
	s_add_i32 m0, s40, 0x12000
	v_mfma_f32_16x16x32_bf16 v[96:99], v[202:205], v[172:175], v[96:99]
	global_load_lds_dwordx4 v[182:183], off
	v_mfma_f32_16x16x32_bf16 v[92:95], v[206:209], v[172:175], v[92:95]
	v_mfma_f32_16x16x32_bf16 v[88:91], v[210:213], v[172:175], v[88:91]
	v_lshl_add_u64 v[182:183], s[28:29], 0, v[190:191]
	s_mov_b32 m0, s40
	v_mfma_f32_16x16x32_bf16 v[84:87], v[214:217], v[172:175], v[84:87]
	global_load_lds_dwordx4 v[182:183], off
	v_mfma_f32_16x16x32_bf16 v[80:83], v[202:205], v[176:179], v[80:83]
	v_mfma_f32_16x16x32_bf16 v[76:79], v[206:209], v[176:179], v[76:79]
	v_mfma_f32_16x16x32_bf16 v[72:75], v[210:213], v[176:179], v[72:75]
	v_mfma_f32_16x16x32_bf16 v[68:71], v[214:217], v[176:179], v[68:71]
	s_waitcnt lgkmcnt(0)
	v_mfma_f32_16x16x32_bf16 v[64:67], v[132:135], v[148:151], v[64:67]
	ds_read_b128 v[164:167], v234 offset:17408
	v_mfma_f32_16x16x32_bf16 v[60:63], v[136:139], v[148:151], v[60:63]
	ds_read_b128 v[168:171], v234 offset:19456
	v_mfma_f32_16x16x32_bf16 v[56:59], v[140:143], v[148:151], v[56:59]
	ds_read_b128 v[172:175], v234 offset:21504
	v_mfma_f32_16x16x32_bf16 v[52:55], v[144:147], v[148:151], v[52:55]
	ds_read_b128 v[176:179], v234 offset:23552
	v_mfma_f32_16x16x32_bf16 v[48:51], v[132:135], v[152:155], v[48:51]
	v_lshl_add_u64 v[182:183], s[28:29], 0, v[188:189]
	s_add_i32 m0, s40, 0x2000
	v_mfma_f32_16x16x32_bf16 v[44:47], v[136:139], v[152:155], v[44:47]
	global_load_lds_dwordx4 v[182:183], off
	v_mfma_f32_16x16x32_bf16 v[40:43], v[140:143], v[152:155], v[40:43]
	v_mfma_f32_16x16x32_bf16 v[36:39], v[144:147], v[152:155], v[36:39]
	s_add_u32 s98, s26, 0x80000
	s_addc_u32 s99, s27, 0
	v_lshl_add_u64 v[182:183], s[98:99], 0, v[2:3]
	s_add_i32 m0, s40, 0x14000
	v_mfma_f32_16x16x32_bf16 v[32:35], v[132:135], v[156:159], v[32:35]
	global_load_lds_dwordx4 v[182:183], off
	v_mfma_f32_16x16x32_bf16 v[28:31], v[136:139], v[156:159], v[28:31]
	v_mfma_f32_16x16x32_bf16 v[24:27], v[140:143], v[156:159], v[24:27]
	v_lshl_add_u64 v[182:183], s[98:99], 0, v[0:1]
	s_add_i32 m0, s40, 0x16000
	v_mfma_f32_16x16x32_bf16 v[20:23], v[144:147], v[156:159], v[20:23]
	global_load_lds_dwordx4 v[182:183], off
	v_mfma_f32_16x16x32_bf16 v[16:19], v[132:135], v[160:163], v[16:19]
	v_mfma_f32_16x16x32_bf16 v[12:15], v[136:139], v[160:163], v[12:15]
	v_mfma_f32_16x16x32_bf16 v[8:11], v[140:143], v[160:163], v[8:11]
	v_mfma_f32_16x16x32_bf16 v[4:7], v[144:147], v[160:163], v[4:7]
	s_waitcnt vmcnt(8) lgkmcnt(0)
	s_barrier
	v_mfma_f32_16x16x32_bf16 v[64:67], v[202:205], v[164:167], v[64:67]
	ds_read_b128 v[132:135], v180 offset:32768
	v_mfma_f32_16x16x32_bf16 v[60:63], v[206:209], v[164:167], v[60:63]
	ds_read_b128 v[136:139], v180 offset:34816
	v_mfma_f32_16x16x32_bf16 v[56:59], v[210:213], v[164:167], v[56:59]
	ds_read_b128 v[140:143], v180 offset:49152
	v_mfma_f32_16x16x32_bf16 v[52:55], v[214:217], v[164:167], v[52:55]
	ds_read_b128 v[144:147], v180 offset:51200
	v_mfma_f32_16x16x32_bf16 v[48:51], v[202:205], v[168:171], v[48:51]
	ds_read_b128 v[148:151], v234 offset:32768
	v_mfma_f32_16x16x32_bf16 v[44:47], v[206:209], v[168:171], v[44:47]
	ds_read_b128 v[152:155], v234 offset:34816
	v_mfma_f32_16x16x32_bf16 v[40:43], v[210:213], v[168:171], v[40:43]
	ds_read_b128 v[156:159], v234 offset:36864
	v_mfma_f32_16x16x32_bf16 v[36:39], v[214:217], v[168:171], v[36:39]
	ds_read_b128 v[160:163], v234 offset:38912
	v_mfma_f32_16x16x32_bf16 v[32:35], v[202:205], v[172:175], v[32:35]
	s_add_u32 s98, s28, 0x80000
	s_addc_u32 s99, s29, 0
	v_lshl_add_u64 v[182:183], s[98:99], 0, v[190:191]
	s_add_i32 m0, s40, 0x4000
	v_mfma_f32_16x16x32_bf16 v[28:31], v[206:209], v[172:175], v[28:31]
	global_load_lds_dwordx4 v[182:183], off
	v_mfma_f32_16x16x32_bf16 v[24:27], v[210:213], v[172:175], v[24:27]
	v_mfma_f32_16x16x32_bf16 v[20:23], v[214:217], v[172:175], v[20:23]
	v_lshl_add_u64 v[182:183], s[98:99], 0, v[188:189]
	s_add_i32 m0, s40, 0x6000
	v_mfma_f32_16x16x32_bf16 v[16:19], v[202:205], v[176:179], v[16:19]
	global_load_lds_dwordx4 v[182:183], off
	v_mfma_f32_16x16x32_bf16 v[12:15], v[206:209], v[176:179], v[12:15]
	v_mfma_f32_16x16x32_bf16 v[8:11], v[210:213], v[176:179], v[8:11]
	v_mfma_f32_16x16x32_bf16 v[4:7], v[214:217], v[176:179], v[4:7]
	s_add_u32 s26, s26, 0x80
	s_addc_u32 s27, s27, 0
	s_add_u32 s28, s28, 0x80
	s_addc_u32 s29, s29, 0
	s_waitcnt lgkmcnt(0)
	v_mfma_f32_16x16x32_bf16 v[128:131], v[132:135], v[148:151], v[128:131]
	ds_read_b128 v[202:205], v180 offset:33792
	v_mfma_f32_16x16x32_bf16 v[124:127], v[136:139], v[148:151], v[124:127]
	ds_read_b128 v[206:209], v180 offset:35840
	v_mfma_f32_16x16x32_bf16 v[120:123], v[140:143], v[148:151], v[120:123]
	ds_read_b128 v[210:213], v180 offset:50176
	v_mfma_f32_16x16x32_bf16 v[116:119], v[144:147], v[148:151], v[116:119]
	ds_read_b128 v[214:217], v180 offset:52224
	v_mfma_f32_16x16x32_bf16 v[112:115], v[132:135], v[152:155], v[112:115]
	ds_read_b128 v[164:167], v234 offset:33792
	v_mfma_f32_16x16x32_bf16 v[108:111], v[136:139], v[152:155], v[108:111]
	ds_read_b128 v[168:171], v234 offset:35840
	v_mfma_f32_16x16x32_bf16 v[104:107], v[140:143], v[152:155], v[104:107]
	ds_read_b128 v[172:175], v234 offset:37888
	v_mfma_f32_16x16x32_bf16 v[100:103], v[144:147], v[152:155], v[100:103]
	ds_read_b128 v[176:179], v234 offset:39936
	v_mfma_f32_16x16x32_bf16 v[96:99], v[132:135], v[156:159], v[96:99]
	v_mfma_f32_16x16x32_bf16 v[92:95], v[136:139], v[156:159], v[92:95]
	v_mfma_f32_16x16x32_bf16 v[88:91], v[140:143], v[156:159], v[88:91]
	v_mfma_f32_16x16x32_bf16 v[84:87], v[144:147], v[156:159], v[84:87]
	v_mfma_f32_16x16x32_bf16 v[80:83], v[132:135], v[160:163], v[80:83]
	v_mfma_f32_16x16x32_bf16 v[76:79], v[136:139], v[160:163], v[76:79]
	v_mfma_f32_16x16x32_bf16 v[72:75], v[140:143], v[160:163], v[72:75]
	v_mfma_f32_16x16x32_bf16 v[68:71], v[144:147], v[160:163], v[68:71]
	s_waitcnt vmcnt(8) lgkmcnt(0)
	s_barrier
; #define PG8_STAGE(bufoff, gbase, voff) do { _Pragma("unroll") for (int _i = 0; _i < 2; ++_i) \
;         __builtin_amdgcn_global_load_lds((const unsigned*)((const char*)(gbase) + (voff)[_i]), (LAS unsigned*)(lds + (bufoff) + ldsw + _i * 8192), 16, 0, 0); } while (0)
; #define PG8_LDA(dst, b, h) do { _Pragma("unroll") for (int m = 0; m < 4; ++m) _Pragma("unroll") for (int k = 0; k < 2; ++k) dst[m][k] = *(const LAS bf16x8*)(lds + PG8_SA(b, h) + aoff + m * 2048 + k * 1024); } while (0)
; #define PG8_LDB(dst, b, h) do { _Pragma("unroll") for (int n = 0; n < 2; ++n) _Pragma("unroll") for (int k = 0; k < 2; ++k) dst[n][k] = *(const LAS bf16x8*)(lds + PG8_SB(b, h) + boff + n * 2048 + k * 1024); } while (0)
; #define PG8_MMA(ai, bj, At, Bt) do { __builtin_amdgcn_s_setprio(1); _Pragma("unroll") for (int m = 0; m < 4; ++m) _Pragma("unroll") for (int n = 0; n < 2; ++n) _Pragma("unroll") for (int k = 0; k < 2; ++k) \
;         acc[ai][bj][m][n] = __builtin_amdgcn_mfma_f32_16x16x32_bf16(Bt[n][k], At[m][k], acc[ai][bj][m][n], 0, 0, 0); __builtin_amdgcn_s_setprio(0); } while (0)
; #define PG8_WAIT_V(n) asm volatile("s_waitcnt vmcnt(" #n ")" ::: "memory")
; #define PG8_WAIT_L(n) asm volatile("s_waitcnt lgkmcnt(" #n ")" ::: "memory")
; #define PG8_BAR __builtin_amdgcn_s_barrier()
; #define PG8_SCHED __builtin_amdgcn_sched_barrier(0)
; template <class Epi, int LDA, int LDB, int KK>
; __device__ __forceinline__ void gemm_phase(int wv, LAS unsigned char* lds, const Gemm g, const StaticOrder& S, const Epi& E) {
;     ...
;             PG8_WAIT_L(8); PG8_BAR; PG8_WAIT_L(0); PG8_MMA(0, 0, At, B0); PG8_BAR; PG8_SCHED;
;             PG8_LDB(B1, 1, 1); PG8_STAGE(PG8_SB(1, 0), b3, voffB);
;             PG8_BAR; PG8_WAIT_L(0); PG8_MMA(0, 1, At, B1); PG8_BAR;
;             PG8_LDA(At, 1, 1); PG8_STAGE(PG8_SA(1, 0), a3, voffA);
;             PG8_BAR; PG8_WAIT_L(0); PG8_MMA(1, 0, At, B0); PG8_BAR; PG8_SCHED;
;             PG8_STAGE(PG8_SB(1, 1), b3 + hstepB, voffB);
;             PG8_WAIT_V(6); PG8_BAR; PG8_MMA(1, 1, At, B1); PG8_BAR;
;           }
	v_mfma_f32_16x16x32_bf16 v[128:131], v[202:205], v[164:167], v[128:131]
	ds_read_b128 v[148:151], v234 offset:49152
	v_mfma_f32_16x16x32_bf16 v[124:127], v[206:209], v[164:167], v[124:127]
	ds_read_b128 v[152:155], v234 offset:51200
	v_mfma_f32_16x16x32_bf16 v[120:123], v[210:213], v[164:167], v[120:123]
	ds_read_b128 v[156:159], v234 offset:53248
	v_mfma_f32_16x16x32_bf16 v[116:119], v[214:217], v[164:167], v[116:119]
	ds_read_b128 v[160:163], v234 offset:55296
	v_mfma_f32_16x16x32_bf16 v[112:115], v[202:205], v[168:171], v[112:115]
	v_lshl_add_u64 v[182:183], s[26:27], 0, v[2:3]
	s_add_i32 m0, s40, 0x18000
	v_mfma_f32_16x16x32_bf16 v[108:111], v[206:209], v[168:171], v[108:111]
	global_load_lds_dwordx4 v[182:183], off
	v_mfma_f32_16x16x32_bf16 v[104:107], v[210:213], v[168:171], v[104:107]
	v_mfma_f32_16x16x32_bf16 v[100:103], v[214:217], v[168:171], v[100:103]
	v_lshl_add_u64 v[182:183], s[26:27], 0, v[0:1]
	s_add_i32 m0, s40, 0x1a000
	v_mfma_f32_16x16x32_bf16 v[96:99], v[202:205], v[172:175], v[96:99]
	global_load_lds_dwordx4 v[182:183], off
	v_mfma_f32_16x16x32_bf16 v[92:95], v[206:209], v[172:175], v[92:95]
	v_mfma_f32_16x16x32_bf16 v[88:91], v[210:213], v[172:175], v[88:91]
	v_lshl_add_u64 v[182:183], s[28:29], 0, v[190:191]
	s_add_i32 m0, s40, 0x8000
	v_mfma_f32_16x16x32_bf16 v[84:87], v[214:217], v[172:175], v[84:87]
	global_load_lds_dwordx4 v[182:183], off
	v_mfma_f32_16x16x32_bf16 v[80:83], v[202:205], v[176:179], v[80:83]
	v_mfma_f32_16x16x32_bf16 v[76:79], v[206:209], v[176:179], v[76:79]
	v_mfma_f32_16x16x32_bf16 v[72:75], v[210:213], v[176:179], v[72:75]
	v_mfma_f32_16x16x32_bf16 v[68:71], v[214:217], v[176:179], v[68:71]
	s_waitcnt lgkmcnt(0)
	v_mfma_f32_16x16x32_bf16 v[64:67], v[132:135], v[148:151], v[64:67]
	ds_read_b128 v[164:167], v234 offset:50176
	v_mfma_f32_16x16x32_bf16 v[60:63], v[136:139], v[148:151], v[60:63]
	ds_read_b128 v[168:171], v234 offset:52224
	v_mfma_f32_16x16x32_bf16 v[56:59], v[140:143], v[148:151], v[56:59]
	ds_read_b128 v[172:175], v234 offset:54272
	v_mfma_f32_16x16x32_bf16 v[52:55], v[144:147], v[148:151], v[52:55]
	ds_read_b128 v[176:179], v234 offset:56320
	v_mfma_f32_16x16x32_bf16 v[48:51], v[132:135], v[152:155], v[48:51]
	v_lshl_add_u64 v[182:183], s[28:29], 0, v[188:189]
	s_add_i32 m0, s40, 0xa000
	v_mfma_f32_16x16x32_bf16 v[44:47], v[136:139], v[152:155], v[44:47]
	global_load_lds_dwordx4 v[182:183], off
	v_mfma_f32_16x16x32_bf16 v[40:43], v[140:143], v[152:155], v[40:43]
	v_mfma_f32_16x16x32_bf16 v[36:39], v[144:147], v[152:155], v[36:39]
	s_add_u32 s98, s26, 0x80000
	s_addc_u32 s99, s27, 0
	v_lshl_add_u64 v[182:183], s[98:99], 0, v[2:3]
	s_add_i32 m0, s40, 0x1c000
	v_mfma_f32_16x16x32_bf16 v[32:35], v[132:135], v[156:159], v[32:35]
	global_load_lds_dwordx4 v[182:183], off
	v_mfma_f32_16x16x32_bf16 v[28:31], v[136:139], v[156:159], v[28:31]
	v_mfma_f32_16x16x32_bf16 v[24:27], v[140:143], v[156:159], v[24:27]
	v_lshl_add_u64 v[182:183], s[98:99], 0, v[0:1]
	s_add_i32 m0, s40, 0x1e000
	v_mfma_f32_16x16x32_bf16 v[20:23], v[144:147], v[156:159], v[20:23]
	global_load_lds_dwordx4 v[182:183], off
	v_mfma_f32_16x16x32_bf16 v[16:19], v[132:135], v[160:163], v[16:19]
	v_mfma_f32_16x16x32_bf16 v[12:15], v[136:139], v[160:163], v[12:15]
	v_mfma_f32_16x16x32_bf16 v[8:11], v[140:143], v[160:163], v[8:11]
	v_mfma_f32_16x16x32_bf16 v[4:7], v[144:147], v[160:163], v[4:7]
	s_waitcnt vmcnt(8) lgkmcnt(0)
	s_barrier
	v_mfma_f32_16x16x32_bf16 v[64:67], v[202:205], v[164:167], v[64:67]
	ds_read_b128 v[132:135], v180 offset:0
	v_mfma_f32_16x16x32_bf16 v[60:63], v[206:209], v[164:167], v[60:63]
	ds_read_b128 v[136:139], v180 offset:2048
	v_mfma_f32_16x16x32_bf16 v[56:59], v[210:213], v[164:167], v[56:59]
	ds_read_b128 v[140:143], v180 offset:16384
	v_mfma_f32_16x16x32_bf16 v[52:55], v[214:217], v[164:167], v[52:55]
	ds_read_b128 v[144:147], v180 offset:18432
	v_mfma_f32_16x16x32_bf16 v[48:51], v[202:205], v[168:171], v[48:51]
	ds_read_b128 v[148:151], v234 offset:0
	v_mfma_f32_16x16x32_bf16 v[44:47], v[206:209], v[168:171], v[44:47]
	ds_read_b128 v[152:155], v234 offset:2048
	v_mfma_f32_16x16x32_bf16 v[40:43], v[210:213], v[168:171], v[40:43]
	ds_read_b128 v[156:159], v234 offset:4096
	v_mfma_f32_16x16x32_bf16 v[36:39], v[214:217], v[168:171], v[36:39]
	ds_read_b128 v[160:163], v234 offset:6144
	v_mfma_f32_16x16x32_bf16 v[32:35], v[202:205], v[172:175], v[32:35]
	s_add_u32 s98, s28, 0x80000
	s_addc_u32 s99, s29, 0
	v_lshl_add_u64 v[182:183], s[98:99], 0, v[190:191]
	s_add_i32 m0, s40, 0xc000
	v_mfma_f32_16x16x32_bf16 v[28:31], v[206:209], v[172:175], v[28:31]
	global_load_lds_dwordx4 v[182:183], off
	v_mfma_f32_16x16x32_bf16 v[24:27], v[210:213], v[172:175], v[24:27]
	v_mfma_f32_16x16x32_bf16 v[20:23], v[214:217], v[172:175], v[20:23]
	v_lshl_add_u64 v[182:183], s[98:99], 0, v[188:189]
	s_add_i32 m0, s40, 0xe000
	v_mfma_f32_16x16x32_bf16 v[16:19], v[202:205], v[176:179], v[16:19]
	global_load_lds_dwordx4 v[182:183], off
	v_mfma_f32_16x16x32_bf16 v[12:15], v[206:209], v[176:179], v[12:15]
	v_mfma_f32_16x16x32_bf16 v[8:11], v[210:213], v[176:179], v[8:11]
	v_mfma_f32_16x16x32_bf16 v[4:7], v[214:217], v[176:179], v[4:7]
	s_add_i32 s69, s69, 2
	s_add_u32 s56, s56, 0x100
	s_addc_u32 s68, s68, 0
	s_add_u32 s24, s24, 0x100
	s_addc_u32 s25, s25, 0
	s_cmp_gt_u32 s69, 29
	s_cbranch_scc0 .Lout_loop
; #define LAS __attribute__((address_space(3)))
; __device__ __forceinline__ float shx(float v, int mask, int lane) { return __int_as_float(__builtin_amdgcn_ds_bpermute((lane ^ mask) << 2, __float_as_int(v))); }
; __device__ __forceinline__ u32x4 pack8(const f32x4& a, const f32x4& b) { u32x4 w; w.x = pack2(a[0], a[1]); w.y = pack2(a[2], a[3]); w.z = pack2(b[0], b[1]); w.w = pack2(b[2], b[3]); return w; }
;     __device__ __forceinline__ void operator()(AccT& acc, const pg8::Unit& u, int wr, int wc, int fr, int fq, const LAS float* rs) const {
;         int row0 = u.pm * 256 + wr * 64 + fr; asm volatile("" : "+v"(row0)); const int cb = u.pn * 256 + wc * 32 + 8 * fq, lane = fr + 16 * fq;
; #pragma unroll
;         for (int ai = 0; ai < 2; ++ai) {
;             f32x4 hv[4][2][2];
; #pragma unroll
;             for (int m = 0; m < 4; ++m)
; #pragma unroll
;                 for (int bj = 0; bj < 2; ++bj) { const float* hp = h + (size_t)(row0 + ai * 128 + m * 16) * D + cb + bj * 128; hv[m][bj][0] = *(const f32x4*)hp; hv[m][bj][1] = *(const f32x4*)(hp + 4); }
; #pragma unroll
;             for (int m = 0; m < 4; ++m) {
;                 const int row = row0 + ai * 128 + m * 16; float ss = 0.f;
; #pragma unroll
;                 for (int bj = 0; bj < 2; ++bj) {
;                     const int col = cb + bj * 128; float* hp = h + (size_t)row * D + col;
;                     const f32x4 o0 = hv[m][bj][0] + acc[ai][bj][m][0], o1 = hv[m][bj][1] + acc[ai][bj][m][1];
;                     *(f32x4*)hp = o0; *(f32x4*)(hp + 4) = o1;
;                     *(u32x4*)(hb + (size_t)row * D + col) = pack8(o0, o1);
;                     ss += o0[0] * o0[0] + o0[1] * o0[1] + o0[2] * o0[2] + o0[3] * o0[3] + o1[0] * o1[0] + o1[1] * o1[1] + o1[2] * o1[2] + o1[3] * o1[3];
;                 }
;                 ss += shx(ss, 16, lane); ss += shx(ss, 32, lane);
;                 if (fq == 0) atomicAdd(rsqn + row, ss);
	s_waitcnt lgkmcnt(0)
	v_lshl_or_b32 v202, s23, 8, v233
	v_lshl_add_u32 v206, s22, 8, v197
	v_ashrrev_i32_e32 v203, 31, v202
	v_lshlrev_b64 v[244:245], 2, v[202:203]
	v_ashrrev_i32_e32 v207, 31, v206
	v_lshl_add_u64 v[204:205], s[10:11], 0, v[244:245]
	v_lshlrev_b64 v[246:247], 13, v[206:207]
	v_lshl_add_u64 v[132:133], v[204:205], 0, v[246:247]
	global_load_dwordx4 v[236:239], v[132:133], off offset:16
	global_load_dwordx4 v[240:243], v[132:133], off
	global_load_dwordx4 v[180:183], v[132:133], off offset:528
	global_load_dwordx4 v[184:187], v[132:133], off offset:512
	v_add_u32_e32 v214, 16, v206
	v_ashrrev_i32_e32 v215, 31, v214
	v_add_u32_e32 v210, 32, v206
	v_add_u32_e32 v208, 48, v206
	v_lshlrev_b64 v[218:219], 13, v[214:215]
	v_ashrrev_i32_e32 v211, 31, v210
	v_ashrrev_i32_e32 v209, 31, v208
	v_lshl_add_u64 v[132:133], v[204:205], 0, v[218:219]
	v_lshlrev_b64 v[216:217], 13, v[210:211]
	v_lshlrev_b64 v[212:213], 13, v[208:209]
	global_load_dwordx4 v[172:175], v[132:133], off offset:16
	global_load_dwordx4 v[176:179], v[132:133], off
	global_load_dwordx4 v[164:167], v[132:133], off offset:528
	global_load_dwordx4 v[168:171], v[132:133], off offset:512
	v_lshl_add_u64 v[132:133], v[204:205], 0, v[216:217]
	v_lshl_add_u64 v[136:137], v[204:205], 0, v[212:213]
	global_load_dwordx4 v[156:159], v[132:133], off offset:16
	global_load_dwordx4 v[160:163], v[132:133], off
	global_load_dwordx4 v[140:143], v[132:133], off offset:528
	global_load_dwordx4 v[148:151], v[132:133], off offset:512
	global_load_dwordx4 v[144:147], v[136:137], off offset:16
	global_load_dwordx4 v[152:155], v[136:137], off
	s_nop 0
	global_load_dwordx4 v[132:135], v[136:137], off offset:528
	s_nop 0
	global_load_dwordx4 v[136:139], v[136:137], off offset:512
	v_lshl_add_u64 v[246:247], s[10:11], 0, v[246:247]
	v_lshl_add_u64 v[244:245], v[246:247], 0, v[244:245]
	s_waitcnt vmcnt(0)
	v_pk_add_f32 v[126:127], v[126:127], v[238:239]
	v_pk_add_f32 v[130:131], v[130:131], v[242:243]
	v_pk_add_f32 v[128:129], v[128:129], v[240:241]
	v_pk_add_f32 v[124:125], v[124:125], v[236:237]
	global_store_dwordx4 v[244:245], v[128:131], off
	global_store_dwordx4 v[244:245], v[124:127], off offset:16
	v_cvt_pk_bf16_f32 v236, v128, v129
	v_lshlrev_b64 v[240:241], 12, v[206:207]
	v_mul_f32_e32 v129, v129, v129
	v_fmac_f32_e32 v129, v128, v128
	v_lshl_add_u64 v[240:241], s[8:9], 0, v[240:241]
	v_fmac_f32_e32 v129, v130, v130
	v_lshl_add_u64 v[240:241], v[202:203], 1, v[240:241]
	v_fmac_f32_e32 v129, v131, v131
	v_pk_add_f32 v[122:123], v[122:123], v[186:187]
	v_pk_add_f32 v[120:121], v[120:121], v[184:185]
	v_cvt_pk_bf16_f32 v237, v130, v131
	v_cvt_pk_bf16_f32 v238, v124, v125
	v_cvt_pk_bf16_f32 v239, v126, v127
	global_store_dwordx4 v[240:241], v[236:239], off
	v_fmac_f32_e32 v129, v124, v124
	v_pk_add_f32 v[118:119], v[118:119], v[182:183]
	v_pk_add_f32 v[116:117], v[116:117], v[180:181]
	global_store_dwordx4 v[244:245], v[120:123], off offset:512
	global_store_dwordx4 v[244:245], v[116:119], off offset:528
	v_cvt_pk_bf16_f32 v124, v120, v121
	v_fmac_f32_e32 v129, v125, v125
	v_mul_f32_e32 v121, v121, v121
	v_fmac_f32_e32 v121, v120, v120
	v_fmac_f32_e32 v121, v122, v122
	v_fmac_f32_e32 v121, v123, v123
	v_fmac_f32_e32 v121, v116, v116
	v_fmac_f32_e32 v121, v117, v117
	v_fmac_f32_e32 v129, v126, v126
	v_fmac_f32_e32 v121, v118, v118
	v_fmac_f32_e32 v129, v127, v127
	v_fmac_f32_e32 v121, v119, v119
	v_cvt_pk_bf16_f32 v126, v116, v117
	v_add_f32_e32 v116, v129, v121
	ds_bpermute_b32 v117, v231, v116
	v_cvt_pk_bf16_f32 v125, v122, v123
	v_cvt_pk_bf16_f32 v127, v118, v119
	global_store_dwordx4 v[240:241], v[124:127], off offset:256
	s_waitcnt lgkmcnt(0)
	v_add_f32_e32 v116, v116, v117
	ds_bpermute_b32 v117, v232, v116
	s_and_saveexec_b64 s[22:23], s[4:5]
	s_cbranch_execz .LBB0_625
	s_waitcnt lgkmcnt(0)
	v_add_f32_e32 v118, v116, v117
	v_lshl_add_u64 v[116:117], v[206:207], 2, s[12:13]
	global_atomic_add_f32 v[116:117], v118, off

; #define PG8_WAIT_V(n) asm volatile("s_waitcnt vmcnt(" #n ")" ::: "memory")
; #define PG8_BAR __builtin_amdgcn_s_barrier()
; template <class Epi, int LDA, int LDB, int KK>
; __device__ __forceinline__ void gemm_phase(int wv, LAS unsigned char* lds, const Gemm g, const StaticOrder& S, const Epi& E) {
;     ...
;     PG8_WAIT_V(0);
;     if (wr == 0) PG8_BAR;
;     PG8_BAR;
.LBB0_639:
	s_waitcnt vmcnt(0)
	s_cmpk_gt_u32 s31, 0xff
	s_mov_b32 s34, s2
	s_cbranch_scc1 .LBB0_641
.LBB0_641:
	s_barrier

; #define LAS __attribute__((address_space(3)))
; #define PG8_STAGE(bufoff, gbase, voff) do { _Pragma("unroll") for (int _i = 0; _i < 2; ++_i) \
;         __builtin_amdgcn_global_load_lds((const unsigned*)((const char*)(gbase) + (voff)[_i]), (LAS unsigned*)(lds + (bufoff) + ldsw + _i * 8192), 16, 0, 0); } while (0)
; #define PG8_WAIT_V(n) asm volatile("s_waitcnt vmcnt(" #n ")" ::: "memory")
; #define PG8_BAR __builtin_amdgcn_s_barrier()
; template <class Epi, int LDA, int LDB, int KK>
; __device__ __forceinline__ void gemm_phase(int wv, LAS unsigned char* lds, const Gemm g, const StaticOrder& S, const Epi& E) {
;     ...
;     const char* cA = (const char*)g.A + (size_t)cur.pm * tstepA; const char* cB = (const char*)g.Bt + (size_t)cur.pn * tstepB;
;     if constexpr (Epi::ROWSCALE) { if (wid < 4) __builtin_amdgcn_global_load_lds((const unsigned*)(E.rsq + cur.pm * 256 + wid * 64 + lane), (LAS unsigned*)(lds + 131072 + wid * 256), 4, 0, 0); }
;     PG8_STAGE(PG8_SB(0, 0), cB, voffB); PG8_STAGE(PG8_SA(0, 0), cA, voffA); PG8_STAGE(PG8_SB(0, 1), cB + hstepB, voffB); PG8_STAGE(PG8_SA(0, 1), cA + hstepA, voffA);
;     if (wr == 1) PG8_BAR;
;     PG8_WAIT_V(4); PG8_BAR;
;     PG8_STAGE(PG8_SB(1, 0), cB + kstep, voffB); PG8_STAGE(PG8_SA(1, 0), cA + kstep, voffA); PG8_STAGE(PG8_SB(1, 1), cB + hstepB + kstep, voffB);
;     PG8_WAIT_V(6); PG8_BAR;
.LBB0_760:
	v_and_b32_e32 v20, 15, v5
	v_lshrrev_b32_e32 v5, 1, v5
	v_and_b32_e32 v21, 24, v5
	v_lshlrev_b32_e32 v5, 1, v21
	s_add_u32 s10, s10, 0x8400000
	v_lshl_or_b32 v142, s7, 6, v20
	v_lshl_or_b32 v5, v20, 6, v5
	v_lshlrev_b32_e32 v20, 2, v20
	s_addc_u32 s11, s11, 0
	s_lshl_b32 s14, s7, 13
	v_and_b32_e32 v22, 32, v20
	v_bitop3_b32 v23, v5, s14, v22 bitop3:0xde
	s_lshl_b32 s14, s6, 5
	s_and_b32 s16, s14, 0x60
	s_add_i32 m0, s25, 0x18000
	v_lshl_add_u64 v[12:13], v[12:13], 0, s[58:59]
	s_lshl_b32 s14, s16, 7
	s_waitcnt vmcnt(4)
	s_barrier
	global_load_lds_dwordx4 v[12:13], off
	v_lshl_add_u64 v[10:11], v[10:11], 0, s[58:59]
	s_add_i32 m0, s25, 0x1a000
	s_add_i32 s40, s25, 0x8000
	s_add_i32 s41, s25, 0xa000
	v_bitop3_b32 v143, v5, s14, v22 bitop3:0xde
	global_load_lds_dwordx4 v[10:11], off
	v_lshl_add_u64 v[8:9], v[8:9], 0, s[58:59]
	s_mov_b32 m0, s40
	s_add_u32 s14, s28, 0x80080
	global_load_lds_dwordx4 v[8:9], off
	v_lshl_add_u64 v[6:7], v[6:7], 0, s[58:59]
	s_mov_b32 m0, s41
	s_addc_u32 s15, s29, 0
	global_load_lds_dwordx4 v[6:7], off
	s_add_i32 m0, s25, 0x1c000
	v_lshl_add_u64 v[6:7], s[14:15], 0, v[2:3]
	global_load_lds_dwordx4 v[6:7], off
	v_lshl_add_u64 v[6:7], s[14:15], 0, v[134:135]
	s_add_i32 m0, s25, 0x1e000
	s_lshl_b32 s7, s7, 8
	global_load_lds_dwordx4 v[6:7], off
	s_add_u32 s98, s26, 0x80080
	s_addc_u32 s99, s27, 0
	v_lshl_add_u64 v[218:219], s[98:99], 0, v[0:1]
	s_add_i32 m0, s25, 0xc000
	s_nop 0
	global_load_lds_dwordx4 v[218:219], off
	v_lshl_add_u64 v[218:219], s[98:99], 0, v[132:133]
	s_add_i32 m0, s25, 0xe000
	s_nop 0
	global_load_lds_dwordx4 v[218:219], off
	s_add_i32 s42, 0, 0x20000
	s_and_b32 s14, s31, 0xffffffc0
	s_add_i32 s7, s42, s7
	s_ashr_i32 s15, s14, 31
	s_lshl_b32 s6, s6, 8
	v_add_u32_e32 v144, s7, v20
	s_add_i32 s42, s42, s6
	s_lshl_b64 s[6:7], s[14:15], 2
	s_add_u32 s4, s4, s6
	s_addc_u32 s5, s5, s7
	v_mov_b32_e32 v5, v3
	v_lshl_add_u64 v[136:137], s[4:5], 0, v[4:5]
	v_lshlrev_b32_e32 v4, 15, v17
	v_and_b32_e32 v4, 0xffff0000, v4
	v_lshl_add_u32 v4, v18, 12, v4
	v_and_b32_e32 v5, 1, v17
	v_lshl_or_b32 v4, v5, 6, v4
	v_lshl_add_u32 v138, v19, 1, v4
	v_lshlrev_b32_e32 v4, 15, v14
	v_and_b32_e32 v4, 0xffff0000, v4
	s_waitcnt vmcnt(8)
	v_lshl_add_u32 v4, v15, 12, v4
	v_and_b32_e32 v5, 1, v14
	v_lshl_or_b32 v4, v5, 6, v4
	v_or_b32_e32 v145, s16, v21
	v_mov_b32_e32 v139, v3
	v_lshl_add_u32 v140, v16, 1, v4
	v_mov_b32_e32 v141, v3
	s_mov_b32 s44, 0
	v_add_u32_e32 v146, 0, v23
	s_barrier

; #define LAS __attribute__((address_space(3)))
; #define PG8_STAGE(bufoff, gbase, voff) do { _Pragma("unroll") for (int _i = 0; _i < 2; ++_i) \
;         __builtin_amdgcn_global_load_lds((const unsigned*)((const char*)(gbase) + (voff)[_i]), (LAS unsigned*)(lds + (bufoff) + ldsw + _i * 8192), 16, 0, 0); } while (0)
; #define PG8_LDA(dst, b, h) do { _Pragma("unroll") for (int m = 0; m < 4; ++m) _Pragma("unroll") for (int k = 0; k < 2; ++k) dst[m][k] = *(const LAS bf16x8*)(lds + PG8_SA(b, h) + aoff + m * 2048 + k * 1024); } while (0)
; #define PG8_WAIT_L(n) asm volatile("s_waitcnt lgkmcnt(" #n ")" ::: "memory")
; #define PG8_BAR __builtin_amdgcn_s_barrier()
; template <class Epi, int LDA, int LDB, int KK>
; __device__ __forceinline__ void gemm_phase(int wv, LAS unsigned char* lds, const Gemm g, const StaticOrder& S, const Epi& E) {
;     ...
;     for (;;) {
;         const bool has_next = S.next(ui + 1, nxt);
;         const char* nA = has_next ? (const char*)g.A + (size_t)nxt.pm * tstepA : cA; const char* nB = has_next ? (const char*)g.Bt + (size_t)nxt.pn * tstepB : cB;
;         if constexpr (Epi::ROWSCALE) { if (has_next && wid < 4) __builtin_amdgcn_global_load_lds((const unsigned*)(E.rsq + nxt.pm * 256 + wid * 64 + lane), (LAS unsigned*)(lds + 131072 + ((ui + 1) % 3) * 1024 + wid * 256), 4, 0, 0); }
;         for (int seg = 0, t = 0; seg < Epi::NSEG; ++seg) {
;           const int tend = Epi::HAS_MID ? (seg == 0 ? Epi::MID1 : (seg == 1 ? Epi::MID2 : nt)) : nt;
;           for (; t < tend; t += 2) {
;             const bool last = (t == nt - 2);
;             const char* a1 = cA + (size_t)(t + 1) * kstep;
;             const char* a2 = last ? nA : cA + (size_t)(t + 2) * kstep; const char* b2 = last ? nB : cB + (size_t)(t + 2) * kstep;
;             const char* a3 = a2 + kstep; const char* b3 = b2 + kstep;
;             PG8_LDB(B0, 0, 0); PG8_SCHED; PG8_LDA(At, 0, 0); PG8_STAGE(PG8_SA(1, 1), a1 + hstepA, voffA);
;             PG8_WAIT_L(8); PG8_BAR; PG8_WAIT_L(0); PG8_MMA(0, 0, At, B0); PG8_BAR; PG8_SCHED;
;     ...
; #pragma unroll
;         for (int a = 0; a < 2; ++a)
; #pragma unroll
;             for (int b = 0; b < 2; ++b)
; #pragma unroll
;                 for (int m = 0; m < 4; ++m)
; #pragma unroll
;                     for (int n = 0; n < 2; ++n) acc[a][b][m][n] = (f32x4){0.f, 0.f, 0.f, 0.f};
;         cur = nxt; cA = nA; cB = nB; ++ui;
.LBB0_765:
	s_ashr_i32 s17, s16, 31
	s_lshl_b64 s[18:19], s[16:17], 20
	s_add_u32 s18, s8, s18
	s_addc_u32 s19, s9, s19
	s_and_b64 s[20:21], s[6:7], exec
	s_cselect_b32 s17, s19, s27
	s_cselect_b32 s45, s18, s26
	s_ashr_i32 s15, s14, 31
	s_lshl_b64 s[20:21], s[14:15], 20
	s_add_u32 s20, s35, s20
	s_addc_u32 s21, s36, s21
	s_and_b64 s[6:7], s[6:7], exec
	s_cselect_b32 s15, s21, s29
	s_cselect_b32 s46, s20, s28
	s_add_u32 s47, s28, 0x100
	s_addc_u32 s55, s29, 0
	s_add_u32 s6, s26, 0x80080
	v_mov_b32_e32 v4, 0
	s_addc_u32 s7, s27, 0
	s_mov_b32 s56, -2
	v_mov_b32_e32 v5, v4
	v_mov_b32_e32 v6, v4
	v_mov_b32_e32 v7, v4
	v_mov_b32_e32 v8, v4
	v_mov_b32_e32 v9, v4
	v_mov_b32_e32 v10, v4
	v_mov_b32_e32 v11, v4
	v_mov_b32_e32 v20, v4
	v_mov_b32_e32 v21, v4
	v_mov_b32_e32 v22, v4
	v_mov_b32_e32 v23, v4
	v_mov_b32_e32 v24, v4
	v_mov_b32_e32 v25, v4
	v_mov_b32_e32 v26, v4
	v_mov_b32_e32 v27, v4
	v_mov_b32_e32 v36, v4
	v_mov_b32_e32 v37, v4
	v_mov_b32_e32 v38, v4
	v_mov_b32_e32 v39, v4
	v_mov_b32_e32 v40, v4
	v_mov_b32_e32 v41, v4
	v_mov_b32_e32 v42, v4
	v_mov_b32_e32 v43, v4
	v_mov_b32_e32 v52, v4
	v_mov_b32_e32 v53, v4
	v_mov_b32_e32 v54, v4
	v_mov_b32_e32 v55, v4
	v_mov_b32_e32 v56, v4
	v_mov_b32_e32 v57, v4
	v_mov_b32_e32 v58, v4
	v_mov_b32_e32 v59, v4
	v_mov_b32_e32 v12, v4
	v_mov_b32_e32 v13, v4
	v_mov_b32_e32 v14, v4
	v_mov_b32_e32 v15, v4
	v_mov_b32_e32 v16, v4
	v_mov_b32_e32 v17, v4
	v_mov_b32_e32 v18, v4
	v_mov_b32_e32 v19, v4
	v_mov_b32_e32 v28, v4
	v_mov_b32_e32 v29, v4
	v_mov_b32_e32 v30, v4
	v_mov_b32_e32 v31, v4
	v_mov_b32_e32 v32, v4
	v_mov_b32_e32 v33, v4
	v_mov_b32_e32 v34, v4
	v_mov_b32_e32 v35, v4
	v_mov_b32_e32 v44, v4
	v_mov_b32_e32 v45, v4
	v_mov_b32_e32 v46, v4
	v_mov_b32_e32 v47, v4
	v_mov_b32_e32 v48, v4
	v_mov_b32_e32 v49, v4
	v_mov_b32_e32 v50, v4
	v_mov_b32_e32 v51, v4
	v_mov_b32_e32 v60, v4
	v_mov_b32_e32 v61, v4
	v_mov_b32_e32 v62, v4
	v_mov_b32_e32 v63, v4
	v_mov_b32_e32 v64, v4
	v_mov_b32_e32 v65, v4
	v_mov_b32_e32 v66, v4
	v_mov_b32_e32 v67, v4
	v_mov_b32_e32 v68, v4
	v_mov_b32_e32 v69, v4
	v_mov_b32_e32 v70, v4
	v_mov_b32_e32 v71, v4
	v_mov_b32_e32 v72, v4
	v_mov_b32_e32 v73, v4
	v_mov_b32_e32 v74, v4
	v_mov_b32_e32 v75, v4
	v_mov_b32_e32 v84, v4
	v_mov_b32_e32 v85, v4
	v_mov_b32_e32 v86, v4
	v_mov_b32_e32 v87, v4
	v_mov_b32_e32 v88, v4
	v_mov_b32_e32 v89, v4
	v_mov_b32_e32 v90, v4
	v_mov_b32_e32 v91, v4
	v_mov_b32_e32 v100, v4
	v_mov_b32_e32 v101, v4
	v_mov_b32_e32 v102, v4
	v_mov_b32_e32 v103, v4
	v_mov_b32_e32 v104, v4
	v_mov_b32_e32 v105, v4
	v_mov_b32_e32 v106, v4
	v_mov_b32_e32 v107, v4
	v_mov_b32_e32 v116, v4
	v_mov_b32_e32 v117, v4
	v_mov_b32_e32 v118, v4
	v_mov_b32_e32 v119, v4
	v_mov_b32_e32 v120, v4
	v_mov_b32_e32 v121, v4
	v_mov_b32_e32 v122, v4
	v_mov_b32_e32 v123, v4
	v_mov_b32_e32 v76, v4
	v_mov_b32_e32 v77, v4
	v_mov_b32_e32 v78, v4
	v_mov_b32_e32 v79, v4
	v_mov_b32_e32 v80, v4
	v_mov_b32_e32 v81, v4
	v_mov_b32_e32 v82, v4
	v_mov_b32_e32 v83, v4
	v_mov_b32_e32 v92, v4
	v_mov_b32_e32 v93, v4
	v_mov_b32_e32 v94, v4
	v_mov_b32_e32 v95, v4
	v_mov_b32_e32 v96, v4
	v_mov_b32_e32 v97, v4
	v_mov_b32_e32 v98, v4
	v_mov_b32_e32 v99, v4
	v_mov_b32_e32 v108, v4
	v_mov_b32_e32 v109, v4
	v_mov_b32_e32 v110, v4
	v_mov_b32_e32 v111, v4
	v_mov_b32_e32 v112, v4
	v_mov_b32_e32 v113, v4
	v_mov_b32_e32 v114, v4
	v_mov_b32_e32 v115, v4
	v_mov_b32_e32 v124, v4
	v_mov_b32_e32 v125, v4
	v_mov_b32_e32 v126, v4
	v_mov_b32_e32 v127, v4
	v_mov_b32_e32 v128, v4
	v_mov_b32_e32 v129, v4
	v_mov_b32_e32 v130, v4
	v_mov_b32_e32 v131, v4
	v_add_u32_e32 v147, 0x10000, v143
	ds_read_b128 v[148:151], v147 offset:0
	ds_read_b128 v[152:155], v147 offset:2048
	ds_read_b128 v[156:159], v147 offset:16384
	ds_read_b128 v[160:163], v147 offset:18432
	ds_read_b128 v[164:167], v146 offset:0
	ds_read_b128 v[168:171], v146 offset:2048
	ds_read_b128 v[172:175], v146 offset:4096
	ds_read_b128 v[176:179], v146 offset:6144
.Lup_loop:
	s_add_u32 s26, s6, 0xfff80080
	s_addc_u32 s27, s7, -1
	s_cmp_eq_u32 s56, 28
	s_cselect_b32 s29, s17, s27
	s_cselect_b32 s28, s45, s26
	s_cselect_b32 s27, s15, s55
	s_cselect_b32 s26, s46, s47
	s_waitcnt lgkmcnt(0)
	v_mfma_f32_16x16x32_bf16 v[128:131], v[148:151], v[164:167], v[128:131]
	ds_read_b128 v[202:205], v147 offset:1024
	v_mfma_f32_16x16x32_bf16 v[124:127], v[152:155], v[164:167], v[124:127]
	ds_read_b128 v[206:209], v147 offset:3072
	v_mfma_f32_16x16x32_bf16 v[120:123], v[156:159], v[164:167], v[120:123]
	ds_read_b128 v[210:213], v147 offset:17408
	v_mfma_f32_16x16x32_bf16 v[116:119], v[160:163], v[164:167], v[116:119]
	ds_read_b128 v[214:217], v147 offset:19456
	v_mfma_f32_16x16x32_bf16 v[112:115], v[148:151], v[168:171], v[112:115]
	ds_read_b128 v[180:183], v146 offset:1024
	v_mfma_f32_16x16x32_bf16 v[108:111], v[152:155], v[168:171], v[108:111]
	ds_read_b128 v[184:187], v146 offset:3072
	v_mfma_f32_16x16x32_bf16 v[104:107], v[156:159], v[168:171], v[104:107]
	ds_read_b128 v[188:191], v146 offset:5120
	v_mfma_f32_16x16x32_bf16 v[100:103], v[160:163], v[168:171], v[100:103]
	ds_read_b128 v[192:195], v146 offset:7168
	v_mfma_f32_16x16x32_bf16 v[96:99], v[148:151], v[172:175], v[96:99]
	v_mfma_f32_16x16x32_bf16 v[92:95], v[152:155], v[172:175], v[92:95]
	v_mfma_f32_16x16x32_bf16 v[88:91], v[156:159], v[172:175], v[88:91]
	v_mfma_f32_16x16x32_bf16 v[84:87], v[160:163], v[172:175], v[84:87]
	v_mfma_f32_16x16x32_bf16 v[80:83], v[148:151], v[176:179], v[80:83]
	v_mfma_f32_16x16x32_bf16 v[76:79], v[152:155], v[176:179], v[76:79]
	v_mfma_f32_16x16x32_bf16 v[72:75], v[156:159], v[176:179], v[72:75]
	v_mfma_f32_16x16x32_bf16 v[68:71], v[160:163], v[176:179], v[68:71]
	s_waitcnt vmcnt(8) lgkmcnt(0)
	s_barrier
; #define PG8_STAGE(bufoff, gbase, voff) do { _Pragma("unroll") for (int _i = 0; _i < 2; ++_i) \
;         __builtin_amdgcn_global_load_lds((const unsigned*)((const char*)(gbase) + (voff)[_i]), (LAS unsigned*)(lds + (bufoff) + ldsw + _i * 8192), 16, 0, 0); } while (0)
; #define PG8_LDA(dst, b, h) do { _Pragma("unroll") for (int m = 0; m < 4; ++m) _Pragma("unroll") for (int k = 0; k < 2; ++k) dst[m][k] = *(const LAS bf16x8*)(lds + PG8_SA(b, h) + aoff + m * 2048 + k * 1024); } while (0)
; #define PG8_WAIT_V(n) asm volatile("s_waitcnt vmcnt(" #n ")" ::: "memory")
; #define PG8_BAR __builtin_amdgcn_s_barrier()
; template <class Epi, int LDA, int LDB, int KK>
; __device__ __forceinline__ void gemm_phase(int wv, LAS unsigned char* lds, const Gemm g, const StaticOrder& S, const Epi& E) {
;     ...
;           for (; t < tend; t += 2) {
;             const bool last = (t == nt - 2);
;             const char* a1 = cA + (size_t)(t + 1) * kstep;
;             const char* a2 = last ? nA : cA + (size_t)(t + 2) * kstep; const char* b2 = last ? nB : cB + (size_t)(t + 2) * kstep;
;             const char* a3 = a2 + kstep; const char* b3 = b2 + kstep;
;             PG8_LDB(B0, 0, 0); PG8_SCHED; PG8_LDA(At, 0, 0); PG8_STAGE(PG8_SA(1, 1), a1 + hstepA, voffA);
;             PG8_WAIT_L(8); PG8_BAR; PG8_WAIT_L(0); PG8_MMA(0, 0, At, B0); PG8_BAR; PG8_SCHED;
;             PG8_LDB(B1, 0, 1); PG8_STAGE(PG8_SB(0, 0), b2, voffB);
;             PG8_BAR; PG8_WAIT_L(0); PG8_MMA(0, 1, At, B1); PG8_BAR;
;             PG8_LDA(At, 0, 1); PG8_STAGE(PG8_SA(0, 0), a2, voffA);
;             PG8_BAR; PG8_WAIT_L(0); PG8_MMA(1, 0, At, B0); PG8_BAR; PG8_SCHED;
;             PG8_STAGE(PG8_SB(0, 1), b2 + hstepB, voffB);
;             PG8_WAIT_V(6); PG8_BAR; PG8_MMA(1, 1, At, B1); PG8_BAR;
;             PG8_LDB(B0, 1, 0); PG8_SCHED; PG8_LDA(At, 1, 0); PG8_STAGE(PG8_SA(0, 1), a2 + hstepA, voffA);
;             PG8_WAIT_L(8); PG8_BAR; PG8_WAIT_L(0); PG8_MMA(0, 0, At, B0); PG8_BAR; PG8_SCHED;
;             PG8_LDB(B1, 1, 1); PG8_STAGE(PG8_SB(1, 0), b3, voffB);
;             PG8_BAR; PG8_WAIT_L(0); PG8_MMA(0, 1, At, B1); PG8_BAR;
;             PG8_LDA(At, 1, 1); PG8_STAGE(PG8_SA(1, 0), a3, voffA);
;             PG8_BAR; PG8_WAIT_L(0); PG8_MMA(1, 0, At, B0); PG8_BAR; PG8_SCHED;
;             PG8_STAGE(PG8_SB(1, 1), b3 + hstepB, voffB);
;             PG8_WAIT_V(6); PG8_BAR; PG8_MMA(1, 1, At, B1); PG8_BAR;
	v_mfma_f32_16x16x32_bf16 v[128:131], v[202:205], v[180:183], v[128:131]
	ds_read_b128 v[164:167], v146 offset:16384
	v_mfma_f32_16x16x32_bf16 v[124:127], v[206:209], v[180:183], v[124:127]
	ds_read_b128 v[168:171], v146 offset:18432
	v_mfma_f32_16x16x32_bf16 v[120:123], v[210:213], v[180:183], v[120:123]
	ds_read_b128 v[172:175], v146 offset:20480
	v_mfma_f32_16x16x32_bf16 v[116:119], v[214:217], v[180:183], v[116:119]
	ds_read_b128 v[176:179], v146 offset:22528
	v_mfma_f32_16x16x32_bf16 v[112:115], v[202:205], v[184:187], v[112:115]
	v_lshl_add_u64 v[218:219], s[26:27], 0, v[2:3]
	s_add_i32 m0, s25, 0x10000
	v_mfma_f32_16x16x32_bf16 v[108:111], v[206:209], v[184:187], v[108:111]
	global_load_lds_dwordx4 v[218:219], off
	v_mfma_f32_16x16x32_bf16 v[104:107], v[210:213], v[184:187], v[104:107]
	v_mfma_f32_16x16x32_bf16 v[100:103], v[214:217], v[184:187], v[100:103]
	v_lshl_add_u64 v[218:219], s[26:27], 0, v[134:135]
	s_add_i32 m0, s25, 0x12000
	v_mfma_f32_16x16x32_bf16 v[96:99], v[202:205], v[188:191], v[96:99]
	global_load_lds_dwordx4 v[218:219], off
	v_mfma_f32_16x16x32_bf16 v[92:95], v[206:209], v[188:191], v[92:95]
	v_mfma_f32_16x16x32_bf16 v[88:91], v[210:213], v[188:191], v[88:91]
	v_lshl_add_u64 v[218:219], s[28:29], 0, v[0:1]
	s_mov_b32 m0, s25
	v_mfma_f32_16x16x32_bf16 v[84:87], v[214:217], v[188:191], v[84:87]
	global_load_lds_dwordx4 v[218:219], off
	v_mfma_f32_16x16x32_bf16 v[80:83], v[202:205], v[192:195], v[80:83]
	v_mfma_f32_16x16x32_bf16 v[76:79], v[206:209], v[192:195], v[76:79]
	v_mfma_f32_16x16x32_bf16 v[72:75], v[210:213], v[192:195], v[72:75]
	v_mfma_f32_16x16x32_bf16 v[68:71], v[214:217], v[192:195], v[68:71]
	s_waitcnt lgkmcnt(0)
	v_mfma_f32_16x16x32_bf16 v[64:67], v[148:151], v[164:167], v[64:67]
	ds_read_b128 v[180:183], v146 offset:17408
	v_mfma_f32_16x16x32_bf16 v[60:63], v[152:155], v[164:167], v[60:63]
	ds_read_b128 v[184:187], v146 offset:19456
	v_mfma_f32_16x16x32_bf16 v[56:59], v[156:159], v[164:167], v[56:59]
	ds_read_b128 v[188:191], v146 offset:21504
	v_mfma_f32_16x16x32_bf16 v[52:55], v[160:163], v[164:167], v[52:55]
	ds_read_b128 v[192:195], v146 offset:23552
	v_mfma_f32_16x16x32_bf16 v[48:51], v[148:151], v[168:171], v[48:51]
	v_lshl_add_u64 v[218:219], s[28:29], 0, v[132:133]
	s_add_i32 m0, s25, 0x2000
	v_mfma_f32_16x16x32_bf16 v[44:47], v[152:155], v[168:171], v[44:47]
	global_load_lds_dwordx4 v[218:219], off
	v_mfma_f32_16x16x32_bf16 v[40:43], v[156:159], v[168:171], v[40:43]
	v_mfma_f32_16x16x32_bf16 v[36:39], v[160:163], v[168:171], v[36:39]
	s_add_u32 s98, s26, 0x80000
	s_addc_u32 s99, s27, 0
	v_lshl_add_u64 v[218:219], s[98:99], 0, v[2:3]
	s_add_i32 m0, s25, 0x14000
	v_mfma_f32_16x16x32_bf16 v[32:35], v[148:151], v[172:175], v[32:35]
	global_load_lds_dwordx4 v[218:219], off
	v_mfma_f32_16x16x32_bf16 v[28:31], v[152:155], v[172:175], v[28:31]
	v_mfma_f32_16x16x32_bf16 v[24:27], v[156:159], v[172:175], v[24:27]
	v_lshl_add_u64 v[218:219], s[98:99], 0, v[134:135]
	s_add_i32 m0, s25, 0x16000
	v_mfma_f32_16x16x32_bf16 v[20:23], v[160:163], v[172:175], v[20:23]
	global_load_lds_dwordx4 v[218:219], off
	v_mfma_f32_16x16x32_bf16 v[16:19], v[148:151], v[176:179], v[16:19]
	v_mfma_f32_16x16x32_bf16 v[12:15], v[152:155], v[176:179], v[12:15]
	v_mfma_f32_16x16x32_bf16 v[8:11], v[156:159], v[176:179], v[8:11]
	v_mfma_f32_16x16x32_bf16 v[4:7], v[160:163], v[176:179], v[4:7]
	s_waitcnt vmcnt(8) lgkmcnt(0)
	s_barrier
	v_mfma_f32_16x16x32_bf16 v[64:67], v[202:205], v[180:183], v[64:67]
	ds_read_b128 v[148:151], v147 offset:32768
	v_mfma_f32_16x16x32_bf16 v[60:63], v[206:209], v[180:183], v[60:63]
	ds_read_b128 v[152:155], v147 offset:34816
	v_mfma_f32_16x16x32_bf16 v[56:59], v[210:213], v[180:183], v[56:59]
	ds_read_b128 v[156:159], v147 offset:49152
	v_mfma_f32_16x16x32_bf16 v[52:55], v[214:217], v[180:183], v[52:55]
	ds_read_b128 v[160:163], v147 offset:51200
	v_mfma_f32_16x16x32_bf16 v[48:51], v[202:205], v[184:187], v[48:51]
	ds_read_b128 v[164:167], v146 offset:32768
	v_mfma_f32_16x16x32_bf16 v[44:47], v[206:209], v[184:187], v[44:47]
	ds_read_b128 v[168:171], v146 offset:34816
	v_mfma_f32_16x16x32_bf16 v[40:43], v[210:213], v[184:187], v[40:43]
	ds_read_b128 v[172:175], v146 offset:36864
	v_mfma_f32_16x16x32_bf16 v[36:39], v[214:217], v[184:187], v[36:39]
	ds_read_b128 v[176:179], v146 offset:38912
	v_mfma_f32_16x16x32_bf16 v[32:35], v[202:205], v[188:191], v[32:35]
	s_add_u32 s98, s28, 0x80000
	s_addc_u32 s99, s29, 0
	v_lshl_add_u64 v[218:219], s[98:99], 0, v[0:1]
	s_add_i32 m0, s25, 0x4000
	v_mfma_f32_16x16x32_bf16 v[28:31], v[206:209], v[188:191], v[28:31]
	global_load_lds_dwordx4 v[218:219], off
	v_mfma_f32_16x16x32_bf16 v[24:27], v[210:213], v[188:191], v[24:27]
	v_mfma_f32_16x16x32_bf16 v[20:23], v[214:217], v[188:191], v[20:23]
	v_lshl_add_u64 v[218:219], s[98:99], 0, v[132:133]
	s_add_i32 m0, s25, 0x6000
	v_mfma_f32_16x16x32_bf16 v[16:19], v[202:205], v[192:195], v[16:19]
	global_load_lds_dwordx4 v[218:219], off
	v_mfma_f32_16x16x32_bf16 v[12:15], v[206:209], v[192:195], v[12:15]
	v_mfma_f32_16x16x32_bf16 v[8:11], v[210:213], v[192:195], v[8:11]
	v_mfma_f32_16x16x32_bf16 v[4:7], v[214:217], v[192:195], v[4:7]
	s_add_u32 s26, s26, 0x80
	s_addc_u32 s27, s27, 0
	s_add_u32 s28, s28, 0x80
	s_addc_u32 s29, s29, 0
	s_waitcnt lgkmcnt(0)
	v_mfma_f32_16x16x32_bf16 v[128:131], v[148:151], v[164:167], v[128:131]
	ds_read_b128 v[202:205], v147 offset:33792
	v_mfma_f32_16x16x32_bf16 v[124:127], v[152:155], v[164:167], v[124:127]
	ds_read_b128 v[206:209], v147 offset:35840
	v_mfma_f32_16x16x32_bf16 v[120:123], v[156:159], v[164:167], v[120:123]
	ds_read_b128 v[210:213], v147 offset:50176
	v_mfma_f32_16x16x32_bf16 v[116:119], v[160:163], v[164:167], v[116:119]
	ds_read_b128 v[214:217], v147 offset:52224
	v_mfma_f32_16x16x32_bf16 v[112:115], v[148:151], v[168:171], v[112:115]
	ds_read_b128 v[180:183], v146 offset:33792
	v_mfma_f32_16x16x32_bf16 v[108:111], v[152:155], v[168:171], v[108:111]
	ds_read_b128 v[184:187], v146 offset:35840
	v_mfma_f32_16x16x32_bf16 v[104:107], v[156:159], v[168:171], v[104:107]
	ds_read_b128 v[188:191], v146 offset:37888
	v_mfma_f32_16x16x32_bf16 v[100:103], v[160:163], v[168:171], v[100:103]
	ds_read_b128 v[192:195], v146 offset:39936
	v_mfma_f32_16x16x32_bf16 v[96:99], v[148:151], v[172:175], v[96:99]
	v_mfma_f32_16x16x32_bf16 v[92:95], v[152:155], v[172:175], v[92:95]
	v_mfma_f32_16x16x32_bf16 v[88:91], v[156:159], v[172:175], v[88:91]
	v_mfma_f32_16x16x32_bf16 v[84:87], v[160:163], v[172:175], v[84:87]
	v_mfma_f32_16x16x32_bf16 v[80:83], v[148:151], v[176:179], v[80:83]
	v_mfma_f32_16x16x32_bf16 v[76:79], v[152:155], v[176:179], v[76:79]
	v_mfma_f32_16x16x32_bf16 v[72:75], v[156:159], v[176:179], v[72:75]
	v_mfma_f32_16x16x32_bf16 v[68:71], v[160:163], v[176:179], v[68:71]
	s_waitcnt vmcnt(8) lgkmcnt(0)
	s_barrier
; #define PG8_STAGE(bufoff, gbase, voff) do { _Pragma("unroll") for (int _i = 0; _i < 2; ++_i) \
;         __builtin_amdgcn_global_load_lds((const unsigned*)((const char*)(gbase) + (voff)[_i]), (LAS unsigned*)(lds + (bufoff) + ldsw + _i * 8192), 16, 0, 0); } while (0)
; #define PG8_LDA(dst, b, h) do { _Pragma("unroll") for (int m = 0; m < 4; ++m) _Pragma("unroll") for (int k = 0; k < 2; ++k) dst[m][k] = *(const LAS bf16x8*)(lds + PG8_SA(b, h) + aoff + m * 2048 + k * 1024); } while (0)
; #define PG8_WAIT_V(n) asm volatile("s_waitcnt vmcnt(" #n ")" ::: "memory")
; template <class Epi, int LDA, int LDB, int KK>
; __device__ __forceinline__ void gemm_phase(int wv, LAS unsigned char* lds, const Gemm g, const StaticOrder& S, const Epi& E) {
;     ...
;           for (; t < tend; t += 2) {
;             const bool last = (t == nt - 2);
;             const char* a1 = cA + (size_t)(t + 1) * kstep;
;             const char* a2 = last ? nA : cA + (size_t)(t + 2) * kstep; const char* b2 = last ? nB : cB + (size_t)(t + 2) * kstep;
;             const char* a3 = a2 + kstep; const char* b3 = b2 + kstep;
;             PG8_LDB(B0, 0, 0); PG8_SCHED; PG8_LDA(At, 0, 0); PG8_STAGE(PG8_SA(1, 1), a1 + hstepA, voffA);
;             PG8_WAIT_L(8); PG8_BAR; PG8_WAIT_L(0); PG8_MMA(0, 0, At, B0); PG8_BAR; PG8_SCHED;
;             PG8_LDB(B1, 0, 1); PG8_STAGE(PG8_SB(0, 0), b2, voffB);
;             PG8_BAR; PG8_WAIT_L(0); PG8_MMA(0, 1, At, B1); PG8_BAR;
;             PG8_LDA(At, 0, 1); PG8_STAGE(PG8_SA(0, 0), a2, voffA);
;             PG8_BAR; PG8_WAIT_L(0); PG8_MMA(1, 0, At, B0); PG8_BAR; PG8_SCHED;
;             PG8_STAGE(PG8_SB(0, 1), b2 + hstepB, voffB);
;             PG8_WAIT_V(6); PG8_BAR; PG8_MMA(1, 1, At, B1); PG8_BAR;
;             PG8_LDB(B0, 1, 0); PG8_SCHED; PG8_LDA(At, 1, 0); PG8_STAGE(PG8_SA(0, 1), a2 + hstepA, voffA);
;             PG8_WAIT_L(8); PG8_BAR; PG8_WAIT_L(0); PG8_MMA(0, 0, At, B0); PG8_BAR; PG8_SCHED;
;             PG8_LDB(B1, 1, 1); PG8_STAGE(PG8_SB(1, 0), b3, voffB);
;             PG8_BAR; PG8_WAIT_L(0); PG8_MMA(0, 1, At, B1); PG8_BAR;
;             PG8_LDA(At, 1, 1); PG8_STAGE(PG8_SA(1, 0), a3, voffA);
;             PG8_BAR; PG8_WAIT_L(0); PG8_MMA(1, 0, At, B0); PG8_BAR; PG8_SCHED;
;             PG8_STAGE(PG8_SB(1, 1), b3 + hstepB, voffB);
;             PG8_WAIT_V(6); PG8_BAR; PG8_MMA(1, 1, At, B1); PG8_BAR;
;           }
	v_mfma_f32_16x16x32_bf16 v[128:131], v[202:205], v[180:183], v[128:131]
	ds_read_b128 v[164:167], v146 offset:49152
	v_mfma_f32_16x16x32_bf16 v[124:127], v[206:209], v[180:183], v[124:127]
	ds_read_b128 v[168:171], v146 offset:51200
	v_mfma_f32_16x16x32_bf16 v[120:123], v[210:213], v[180:183], v[120:123]
	ds_read_b128 v[172:175], v146 offset:53248
	v_mfma_f32_16x16x32_bf16 v[116:119], v[214:217], v[180:183], v[116:119]
	ds_read_b128 v[176:179], v146 offset:55296
	v_mfma_f32_16x16x32_bf16 v[112:115], v[202:205], v[184:187], v[112:115]
	v_lshl_add_u64 v[218:219], s[26:27], 0, v[2:3]
	s_add_i32 m0, s25, 0x18000
	v_mfma_f32_16x16x32_bf16 v[108:111], v[206:209], v[184:187], v[108:111]
	global_load_lds_dwordx4 v[218:219], off
	v_mfma_f32_16x16x32_bf16 v[104:107], v[210:213], v[184:187], v[104:107]
	v_mfma_f32_16x16x32_bf16 v[100:103], v[214:217], v[184:187], v[100:103]
	v_lshl_add_u64 v[218:219], s[26:27], 0, v[134:135]
	s_add_i32 m0, s25, 0x1a000
	v_mfma_f32_16x16x32_bf16 v[96:99], v[202:205], v[188:191], v[96:99]
	global_load_lds_dwordx4 v[218:219], off
	v_mfma_f32_16x16x32_bf16 v[92:95], v[206:209], v[188:191], v[92:95]
	v_mfma_f32_16x16x32_bf16 v[88:91], v[210:213], v[188:191], v[88:91]
	v_lshl_add_u64 v[218:219], s[28:29], 0, v[0:1]
	s_add_i32 m0, s25, 0x8000
	v_mfma_f32_16x16x32_bf16 v[84:87], v[214:217], v[188:191], v[84:87]
	global_load_lds_dwordx4 v[218:219], off
	v_mfma_f32_16x16x32_bf16 v[80:83], v[202:205], v[192:195], v[80:83]
	v_mfma_f32_16x16x32_bf16 v[76:79], v[206:209], v[192:195], v[76:79]
	v_mfma_f32_16x16x32_bf16 v[72:75], v[210:213], v[192:195], v[72:75]
	v_mfma_f32_16x16x32_bf16 v[68:71], v[214:217], v[192:195], v[68:71]
	s_waitcnt lgkmcnt(0)
	v_mfma_f32_16x16x32_bf16 v[64:67], v[148:151], v[164:167], v[64:67]
	ds_read_b128 v[180:183], v146 offset:50176
	v_mfma_f32_16x16x32_bf16 v[60:63], v[152:155], v[164:167], v[60:63]
	ds_read_b128 v[184:187], v146 offset:52224
	v_mfma_f32_16x16x32_bf16 v[56:59], v[156:159], v[164:167], v[56:59]
	ds_read_b128 v[188:191], v146 offset:54272
	v_mfma_f32_16x16x32_bf16 v[52:55], v[160:163], v[164:167], v[52:55]
	ds_read_b128 v[192:195], v146 offset:56320
	v_mfma_f32_16x16x32_bf16 v[48:51], v[148:151], v[168:171], v[48:51]
	v_lshl_add_u64 v[218:219], s[28:29], 0, v[132:133]
	s_add_i32 m0, s25, 0xa000
	v_mfma_f32_16x16x32_bf16 v[44:47], v[152:155], v[168:171], v[44:47]
	global_load_lds_dwordx4 v[218:219], off
	v_mfma_f32_16x16x32_bf16 v[40:43], v[156:159], v[168:171], v[40:43]
	v_mfma_f32_16x16x32_bf16 v[36:39], v[160:163], v[168:171], v[36:39]
	s_add_u32 s98, s26, 0x80000
	s_addc_u32 s99, s27, 0
	v_lshl_add_u64 v[218:219], s[98:99], 0, v[2:3]
	s_add_i32 m0, s25, 0x1c000
	v_mfma_f32_16x16x32_bf16 v[32:35], v[148:151], v[172:175], v[32:35]
	global_load_lds_dwordx4 v[218:219], off
	v_mfma_f32_16x16x32_bf16 v[28:31], v[152:155], v[172:175], v[28:31]
	v_mfma_f32_16x16x32_bf16 v[24:27], v[156:159], v[172:175], v[24:27]
	v_lshl_add_u64 v[218:219], s[98:99], 0, v[134:135]
	s_add_i32 m0, s25, 0x1e000
	v_mfma_f32_16x16x32_bf16 v[20:23], v[160:163], v[172:175], v[20:23]
	global_load_lds_dwordx4 v[218:219], off
	v_mfma_f32_16x16x32_bf16 v[16:19], v[148:151], v[176:179], v[16:19]
	v_mfma_f32_16x16x32_bf16 v[12:15], v[152:155], v[176:179], v[12:15]
	v_mfma_f32_16x16x32_bf16 v[8:11], v[156:159], v[176:179], v[8:11]
	v_mfma_f32_16x16x32_bf16 v[4:7], v[160:163], v[176:179], v[4:7]
	s_waitcnt vmcnt(8) lgkmcnt(0)
	s_barrier
	v_mfma_f32_16x16x32_bf16 v[64:67], v[202:205], v[180:183], v[64:67]
	ds_read_b128 v[148:151], v147 offset:0
	v_mfma_f32_16x16x32_bf16 v[60:63], v[206:209], v[180:183], v[60:63]
	ds_read_b128 v[152:155], v147 offset:2048
	v_mfma_f32_16x16x32_bf16 v[56:59], v[210:213], v[180:183], v[56:59]
	ds_read_b128 v[156:159], v147 offset:16384
	v_mfma_f32_16x16x32_bf16 v[52:55], v[214:217], v[180:183], v[52:55]
	ds_read_b128 v[160:163], v147 offset:18432
	v_mfma_f32_16x16x32_bf16 v[48:51], v[202:205], v[184:187], v[48:51]
	ds_read_b128 v[164:167], v146 offset:0
	v_mfma_f32_16x16x32_bf16 v[44:47], v[206:209], v[184:187], v[44:47]
	ds_read_b128 v[168:171], v146 offset:2048
	v_mfma_f32_16x16x32_bf16 v[40:43], v[210:213], v[184:187], v[40:43]
	ds_read_b128 v[172:175], v146 offset:4096
	v_mfma_f32_16x16x32_bf16 v[36:39], v[214:217], v[184:187], v[36:39]
	ds_read_b128 v[176:179], v146 offset:6144
	v_mfma_f32_16x16x32_bf16 v[32:35], v[202:205], v[188:191], v[32:35]
	s_add_u32 s98, s28, 0x80000
	s_addc_u32 s99, s29, 0
	v_lshl_add_u64 v[218:219], s[98:99], 0, v[0:1]
	s_add_i32 m0, s25, 0xc000
	v_mfma_f32_16x16x32_bf16 v[28:31], v[206:209], v[188:191], v[28:31]
	global_load_lds_dwordx4 v[218:219], off
	v_mfma_f32_16x16x32_bf16 v[24:27], v[210:213], v[188:191], v[24:27]
	v_mfma_f32_16x16x32_bf16 v[20:23], v[214:217], v[188:191], v[20:23]
	v_lshl_add_u64 v[218:219], s[98:99], 0, v[132:133]
	s_add_i32 m0, s25, 0xe000
	v_mfma_f32_16x16x32_bf16 v[16:19], v[202:205], v[192:195], v[16:19]
	global_load_lds_dwordx4 v[218:219], off
	v_mfma_f32_16x16x32_bf16 v[12:15], v[206:209], v[192:195], v[12:15]
	v_mfma_f32_16x16x32_bf16 v[8:11], v[210:213], v[192:195], v[8:11]
	v_mfma_f32_16x16x32_bf16 v[4:7], v[214:217], v[192:195], v[4:7]
	s_add_i32 s56, s56, 2
	s_add_u32 s47, s47, 0x100
	s_addc_u32 s55, s55, 0
	s_add_u32 s6, s6, 0x100
	s_addc_u32 s7, s7, 0
	s_cmp_gt_u32 s56, 29
	s_cbranch_scc0 .Lup_loop
; #define LAS __attribute__((address_space(3)))
; __device__ __forceinline__ u32x4 pack8(const f32x4& a, const f32x4& b) { u32x4 w; w.x = pack2(a[0], a[1]); w.y = pack2(a[2], a[3]); w.z = pack2(b[0], b[1]); w.w = pack2(b[2], b[3]); return w; }
;     __device__ __forceinline__ void operator()(AccT& acc, const pg8::Unit& u, int wr, int wc, int fr, int fq, const LAS float* rs) const {
;         int row0 = u.pm * 256 + wr * 64 + fr; asm volatile("" : "+v"(row0)); const int cb = u.pn * 256 + wc * 32 + 8 * fq;
; #pragma unroll
;         for (int ai = 0; ai < 2; ++ai)
; #pragma unroll
;             for (int m = 0; m < 4; ++m) {
;                 const int row = row0 + ai * 128 + m * 16; const float sc = rsqrtf(rs[ai * 128 + wr * 64 + m * 16 + fr] * (1.0f / D) + EPS);
; #pragma unroll
;                 for (int bj = 0; bj < 2; ++bj) *(u32x4*)(z2 + (size_t)row * NUP + cb + bj * 128) = pack8(acc[ai][bj][m][0] * sc, acc[ai][bj][m][1] * sc);
;             }
	s_waitcnt lgkmcnt(0)
	s_mul_hi_u32 s6, s44, 0xaaaaaaab
	s_lshr_b32 s6, s6, 1
	s_mul_i32 s6, s6, 3
	s_sub_i32 s6, s44, s6
	v_lshl_add_u32 v147, s22, 8, v142
	v_lshl_add_u32 v148, s6, 10, v144
	ds_read2_b32 v[152:153], v148 offset1:16
	v_lshl_or_b32 v150, s24, 8, v145
	v_ashrrev_i32_e32 v151, 31, v150
	s_mov_b32 s24, s14
	s_mov_b32 s22, s16
	s_waitcnt lgkmcnt(0)
	v_fmamk_f32 v149, v152, 0x3a000000, v220
	v_cmp_gt_f32_e32 vcc, s96, v149
	v_mul_f32_e32 v152, 0x4b800000, v149
	s_mov_b64 s[28:29], s[20:21]
	v_cndmask_b32_e32 v149, v149, v152, vcc
	v_rsq_f32_e32 v149, v149
	s_mov_b64 s[26:27], s[18:19]
	s_mov_b32 s44, s43
	v_mul_f32_e32 v152, 0x45800000, v149
	v_cndmask_b32_e32 v152, v149, v152, vcc
	v_pk_mul_f32 v[130:131], v[130:131], v[152:153] op_sel_hi:[1,0]
	v_pk_mul_f32 v[128:129], v[128:129], v[152:153] op_sel_hi:[1,0]
	v_pk_mul_f32 v[124:125], v[124:125], v[152:153] op_sel_hi:[1,0]
	v_pk_mul_f32 v[126:127], v[126:127], v[152:153] op_sel_hi:[1,0]
	v_cvt_pk_bf16_f32 v128, v128, v129
	v_cvt_pk_bf16_f32 v129, v130, v131
	v_cvt_pk_bf16_f32 v130, v124, v125
	v_mov_b64_e32 v[124:125], s[10:11]
	v_cvt_pk_bf16_f32 v131, v126, v127
	v_mad_i64_i32 v[154:155], s[6:7], v147, s51, v[124:125]
	v_lshlrev_b64 v[126:127], 1, v[150:151]
	v_lshl_add_u64 v[150:151], v[154:155], 0, v[126:127]
	global_store_dwordx4 v[150:151], v[128:131], off
	v_pk_mul_f32 v[120:121], v[120:121], v[152:153] op_sel_hi:[1,0]
	v_pk_mul_f32 v[122:123], v[122:123], v[152:153] op_sel_hi:[1,0]
	v_pk_mul_f32 v[128:129], v[118:119], v[152:153] op_sel_hi:[1,0]
	v_pk_mul_f32 v[118:119], v[116:117], v[152:153] op_sel_hi:[1,0]
	v_cvt_pk_bf16_f32 v116, v120, v121
	v_cvt_pk_bf16_f32 v117, v122, v123
	s_nop 0
	v_cvt_pk_bf16_f32 v118, v118, v119
	v_cvt_pk_bf16_f32 v119, v128, v129
	global_store_dwordx4 v[150:151], v[116:119], off offset:256
	s_nop 1
	v_fmamk_f32 v116, v153, 0x3a000000, v220
	v_cmp_gt_f32_e32 vcc, s96, v116
	v_mul_f32_e32 v118, 0x4b800000, v116
	v_add_u32_e32 v117, 16, v147
	v_cndmask_b32_e32 v116, v116, v118, vcc
	v_rsq_f32_e32 v116, v116
	s_nop 0
	v_mul_f32_e32 v118, 0x45800000, v116
	v_cndmask_b32_e32 v116, v116, v118, vcc
	v_pk_mul_f32 v[112:113], v[112:113], v[116:117] op_sel_hi:[1,0]
	v_pk_mul_f32 v[118:119], v[110:111], v[116:117] op_sel_hi:[1,0]
	v_pk_mul_f32 v[110:111], v[108:109], v[116:117] op_sel_hi:[1,0]
	v_cvt_pk_bf16_f32 v108, v112, v113
	v_mad_i64_i32 v[112:113], s[6:7], v117, s51, v[124:125]
	v_pk_mul_f32 v[114:115], v[114:115], v[116:117] op_sel_hi:[1,0]
	v_lshl_add_u64 v[112:113], v[112:113], 0, v[126:127]
	v_cvt_pk_bf16_f32 v109, v114, v115
	v_cvt_pk_bf16_f32 v110, v110, v111
	v_cvt_pk_bf16_f32 v111, v118, v119
	global_store_dwordx4 v[112:113], v[108:111], off
	v_pk_mul_f32 v[106:107], v[106:107], v[116:117] op_sel_hi:[1,0]
	v_pk_mul_f32 v[104:105], v[104:105], v[116:117] op_sel_hi:[1,0]
	v_pk_mul_f32 v[108:109], v[102:103], v[116:117] op_sel_hi:[1,0]
	v_pk_mul_f32 v[102:103], v[100:101], v[116:117] op_sel_hi:[1,0]
	v_cvt_pk_bf16_f32 v100, v104, v105
	v_cvt_pk_bf16_f32 v101, v106, v107
	v_add_u32_e32 v104, 32, v147
	v_cvt_pk_bf16_f32 v102, v102, v103
	v_cvt_pk_bf16_f32 v103, v108, v109
	global_store_dwordx4 v[112:113], v[100:103], off offset:256
	ds_read2_b32 v[100:101], v148 offset0:32 offset1:48
	s_waitcnt lgkmcnt(0)
	v_fmamk_f32 v100, v100, 0x3a000000, v220
	v_cmp_gt_f32_e32 vcc, s96, v100
	v_mul_f32_e32 v102, 0x4b800000, v100
	s_nop 0
	v_cndmask_b32_e32 v100, v100, v102, vcc
	v_rsq_f32_e32 v100, v100
	s_nop 0
	v_mul_f32_e32 v102, 0x45800000, v100
	v_cndmask_b32_e32 v100, v100, v102, vcc
	v_pk_mul_f32 v[96:97], v[96:97], v[100:101] op_sel_hi:[1,0]
	v_pk_mul_f32 v[102:103], v[94:95], v[100:101] op_sel_hi:[1,0]
	v_pk_mul_f32 v[94:95], v[92:93], v[100:101] op_sel_hi:[1,0]
	v_cvt_pk_bf16_f32 v92, v96, v97
	v_mad_i64_i32 v[96:97], s[6:7], v104, s51, v[124:125]
	v_pk_mul_f32 v[98:99], v[98:99], v[100:101] op_sel_hi:[1,0]
	v_lshl_add_u64 v[96:97], v[96:97], 0, v[126:127]
	v_cvt_pk_bf16_f32 v93, v98, v99
	v_cvt_pk_bf16_f32 v94, v94, v95
	v_cvt_pk_bf16_f32 v95, v102, v103
	global_store_dwordx4 v[96:97], v[92:95], off
	v_pk_mul_f32 v[88:89], v[88:89], v[100:101] op_sel_hi:[1,0]
	v_pk_mul_f32 v[90:91], v[90:91], v[100:101] op_sel_hi:[1,0]
	v_pk_mul_f32 v[92:93], v[86:87], v[100:101] op_sel_hi:[1,0]
	v_pk_mul_f32 v[86:87], v[84:85], v[100:101] op_sel_hi:[1,0]
	v_cvt_pk_bf16_f32 v84, v88, v89
	v_cvt_pk_bf16_f32 v85, v90, v91
	s_nop 0
	v_cvt_pk_bf16_f32 v86, v86, v87
	v_cvt_pk_bf16_f32 v87, v92, v93
	global_store_dwordx4 v[96:97], v[84:87], off offset:256
	s_nop 1
	v_fmamk_f32 v84, v101, 0x3a000000, v220
	v_cmp_gt_f32_e32 vcc, s96, v84
	v_mul_f32_e32 v86, 0x4b800000, v84
	v_add_u32_e32 v85, 48, v147
	v_cndmask_b32_e32 v84, v84, v86, vcc
	v_rsq_f32_e32 v84, v84
	s_nop 0
	v_mul_f32_e32 v86, 0x45800000, v84
	v_cndmask_b32_e32 v84, v84, v86, vcc
	v_pk_mul_f32 v[80:81], v[80:81], v[84:85] op_sel_hi:[1,0]
	v_pk_mul_f32 v[86:87], v[78:79], v[84:85] op_sel_hi:[1,0]
	v_pk_mul_f32 v[78:79], v[76:77], v[84:85] op_sel_hi:[1,0]
	v_cvt_pk_bf16_f32 v76, v80, v81
	v_mad_i64_i32 v[80:81], s[6:7], v85, s51, v[124:125]
	v_pk_mul_f32 v[82:83], v[82:83], v[84:85] op_sel_hi:[1,0]
	v_lshl_add_u64 v[80:81], v[80:81], 0, v[126:127]
	v_cvt_pk_bf16_f32 v77, v82, v83
	v_cvt_pk_bf16_f32 v78, v78, v79
	v_cvt_pk_bf16_f32 v79, v86, v87
	global_store_dwordx4 v[80:81], v[76:79], off
	v_pk_mul_f32 v[74:75], v[74:75], v[84:85] op_sel_hi:[1,0]
	v_pk_mul_f32 v[72:73], v[72:73], v[84:85] op_sel_hi:[1,0]
	v_pk_mul_f32 v[76:77], v[70:71], v[84:85] op_sel_hi:[1,0]
	v_pk_mul_f32 v[70:71], v[68:69], v[84:85] op_sel_hi:[1,0]
	v_cvt_pk_bf16_f32 v68, v72, v73
	v_cvt_pk_bf16_f32 v69, v74, v75
	v_add_u32_e32 v72, 0x80, v147
	v_cvt_pk_bf16_f32 v70, v70, v71
	v_cvt_pk_bf16_f32 v71, v76, v77
	global_store_dwordx4 v[80:81], v[68:71], off offset:256
	ds_read2_b32 v[68:69], v148 offset0:128 offset1:144
	s_waitcnt lgkmcnt(0)
; #define LAS __attribute__((address_space(3)))
; #define PG8_WAIT_V(n) asm volatile("s_waitcnt vmcnt(" #n ")" ::: "memory")
; #define PG8_BAR __builtin_amdgcn_s_barrier()
; __device__ __forceinline__ u32x4 pack8(const f32x4& a, const f32x4& b) { u32x4 w; w.x = pack2(a[0], a[1]); w.y = pack2(a[2], a[3]); w.z = pack2(b[0], b[1]); w.w = pack2(b[2], b[3]); return w; }
; template <class Epi, int LDA, int LDB, int KK>
; __device__ __forceinline__ void gemm_phase(int wv, LAS unsigned char* lds, const Gemm g, const StaticOrder& S, const Epi& E) {
;     ...
;     PG8_WAIT_V(0);
;     if (wr == 0) PG8_BAR;
;     PG8_BAR;
;     __device__ __forceinline__ void operator()(AccT& acc, const pg8::Unit& u, int wr, int wc, int fr, int fq, const LAS float* rs) const {
;         int row0 = u.pm * 256 + wr * 64 + fr; asm volatile("" : "+v"(row0)); const int cb = u.pn * 256 + wc * 32 + 8 * fq;
; #pragma unroll
;         for (int ai = 0; ai < 2; ++ai)
; #pragma unroll
;             for (int m = 0; m < 4; ++m) {
;                 const int row = row0 + ai * 128 + m * 16; const float sc = rsqrtf(rs[ai * 128 + wr * 64 + m * 16 + fr] * (1.0f / D) + EPS);
; #pragma unroll
;                 for (int bj = 0; bj < 2; ++bj) *(u32x4*)(z2 + (size_t)row * NUP + cb + bj * 128) = pack8(acc[ai][bj][m][0] * sc, acc[ai][bj][m][1] * sc);
;             }
	v_fmamk_f32 v68, v68, 0x3a000000, v220
	v_cmp_gt_f32_e32 vcc, s96, v68
	v_mul_f32_e32 v70, 0x4b800000, v68
	s_nop 0
	v_cndmask_b32_e32 v68, v68, v70, vcc
	v_rsq_f32_e32 v68, v68
	s_nop 0
	v_mul_f32_e32 v70, 0x45800000, v68
	v_cndmask_b32_e32 v68, v68, v70, vcc
	v_pk_mul_f32 v[64:65], v[64:65], v[68:69] op_sel_hi:[1,0]
	v_pk_mul_f32 v[70:71], v[62:63], v[68:69] op_sel_hi:[1,0]
	v_pk_mul_f32 v[62:63], v[60:61], v[68:69] op_sel_hi:[1,0]
	v_cvt_pk_bf16_f32 v60, v64, v65
	v_mad_i64_i32 v[64:65], s[6:7], v72, s51, v[124:125]
	v_pk_mul_f32 v[66:67], v[66:67], v[68:69] op_sel_hi:[1,0]
	v_lshl_add_u64 v[64:65], v[64:65], 0, v[126:127]
	v_cvt_pk_bf16_f32 v61, v66, v67
	v_cvt_pk_bf16_f32 v62, v62, v63
	v_cvt_pk_bf16_f32 v63, v70, v71
	global_store_dwordx4 v[64:65], v[60:63], off
	v_pk_mul_f32 v[56:57], v[56:57], v[68:69] op_sel_hi:[1,0]
	v_pk_mul_f32 v[58:59], v[58:59], v[68:69] op_sel_hi:[1,0]
	v_pk_mul_f32 v[60:61], v[54:55], v[68:69] op_sel_hi:[1,0]
	v_pk_mul_f32 v[54:55], v[52:53], v[68:69] op_sel_hi:[1,0]
	v_cvt_pk_bf16_f32 v52, v56, v57
	v_cvt_pk_bf16_f32 v53, v58, v59
	s_nop 0
	v_cvt_pk_bf16_f32 v54, v54, v55
	v_cvt_pk_bf16_f32 v55, v60, v61
	global_store_dwordx4 v[64:65], v[52:55], off offset:256
	s_nop 1
	v_fmamk_f32 v52, v69, 0x3a000000, v220
	v_cmp_gt_f32_e32 vcc, s96, v52
	v_mul_f32_e32 v54, 0x4b800000, v52
	v_add_u32_e32 v53, 0x90, v147
	v_cndmask_b32_e32 v52, v52, v54, vcc
	v_rsq_f32_e32 v52, v52
	s_nop 0
	v_mul_f32_e32 v54, 0x45800000, v52
	v_cndmask_b32_e32 v52, v52, v54, vcc
	v_pk_mul_f32 v[48:49], v[48:49], v[52:53] op_sel_hi:[1,0]
	v_pk_mul_f32 v[54:55], v[46:47], v[52:53] op_sel_hi:[1,0]
	v_pk_mul_f32 v[46:47], v[44:45], v[52:53] op_sel_hi:[1,0]
	v_cvt_pk_bf16_f32 v44, v48, v49
	v_mad_i64_i32 v[48:49], s[6:7], v53, s51, v[124:125]
	v_pk_mul_f32 v[50:51], v[50:51], v[52:53] op_sel_hi:[1,0]
	v_lshl_add_u64 v[48:49], v[48:49], 0, v[126:127]
	v_cvt_pk_bf16_f32 v45, v50, v51
	v_cvt_pk_bf16_f32 v46, v46, v47
	v_cvt_pk_bf16_f32 v47, v54, v55
	global_store_dwordx4 v[48:49], v[44:47], off
	v_pk_mul_f32 v[42:43], v[42:43], v[52:53] op_sel_hi:[1,0]
	v_pk_mul_f32 v[40:41], v[40:41], v[52:53] op_sel_hi:[1,0]
	v_pk_mul_f32 v[44:45], v[38:39], v[52:53] op_sel_hi:[1,0]
	v_pk_mul_f32 v[38:39], v[36:37], v[52:53] op_sel_hi:[1,0]
	v_cvt_pk_bf16_f32 v36, v40, v41
	v_cvt_pk_bf16_f32 v37, v42, v43
	v_add_u32_e32 v40, 0xa0, v147
	v_cvt_pk_bf16_f32 v38, v38, v39
	v_cvt_pk_bf16_f32 v39, v44, v45
	global_store_dwordx4 v[48:49], v[36:39], off offset:256
	ds_read2_b32 v[36:37], v148 offset0:160 offset1:176
	s_waitcnt lgkmcnt(0)
	v_fmamk_f32 v36, v36, 0x3a000000, v220
	v_cmp_gt_f32_e32 vcc, s96, v36
	v_mul_f32_e32 v38, 0x4b800000, v36
	s_nop 0
	v_cndmask_b32_e32 v36, v36, v38, vcc
	v_rsq_f32_e32 v36, v36
	s_nop 0
	v_mul_f32_e32 v38, 0x45800000, v36
	v_cndmask_b32_e32 v36, v36, v38, vcc
	v_pk_mul_f32 v[32:33], v[32:33], v[36:37] op_sel_hi:[1,0]
	v_pk_mul_f32 v[38:39], v[30:31], v[36:37] op_sel_hi:[1,0]
	v_pk_mul_f32 v[30:31], v[28:29], v[36:37] op_sel_hi:[1,0]
	v_cvt_pk_bf16_f32 v28, v32, v33
	v_mad_i64_i32 v[32:33], s[6:7], v40, s51, v[124:125]
	v_pk_mul_f32 v[34:35], v[34:35], v[36:37] op_sel_hi:[1,0]
	v_lshl_add_u64 v[32:33], v[32:33], 0, v[126:127]
	v_cvt_pk_bf16_f32 v29, v34, v35
	v_cvt_pk_bf16_f32 v30, v30, v31
	v_cvt_pk_bf16_f32 v31, v38, v39
	global_store_dwordx4 v[32:33], v[28:31], off
	v_pk_mul_f32 v[24:25], v[24:25], v[36:37] op_sel_hi:[1,0]
	v_pk_mul_f32 v[26:27], v[26:27], v[36:37] op_sel_hi:[1,0]
	v_pk_mul_f32 v[28:29], v[22:23], v[36:37] op_sel_hi:[1,0]
	v_pk_mul_f32 v[22:23], v[20:21], v[36:37] op_sel_hi:[1,0]
	v_cvt_pk_bf16_f32 v20, v24, v25
	v_cvt_pk_bf16_f32 v21, v26, v27
	s_nop 0
	v_cvt_pk_bf16_f32 v22, v22, v23
	v_cvt_pk_bf16_f32 v23, v28, v29
	global_store_dwordx4 v[32:33], v[20:23], off offset:256
	s_nop 1
	v_fmamk_f32 v20, v37, 0x3a000000, v220
	v_cmp_gt_f32_e32 vcc, s96, v20
	v_mul_f32_e32 v22, 0x4b800000, v20
	v_add_u32_e32 v21, 0xb0, v147
	v_cndmask_b32_e32 v20, v20, v22, vcc
	v_rsq_f32_e32 v20, v20
	s_nop 0
	v_mul_f32_e32 v22, 0x45800000, v20
	v_cndmask_b32_e32 v20, v20, v22, vcc
	v_pk_mul_f32 v[16:17], v[16:17], v[20:21] op_sel_hi:[1,0]
	v_pk_mul_f32 v[22:23], v[14:15], v[20:21] op_sel_hi:[1,0]
	v_pk_mul_f32 v[14:15], v[12:13], v[20:21] op_sel_hi:[1,0]
	v_cvt_pk_bf16_f32 v12, v16, v17
	v_mad_i64_i32 v[16:17], s[6:7], v21, s51, v[124:125]
	v_pk_mul_f32 v[18:19], v[18:19], v[20:21] op_sel_hi:[1,0]
	v_lshl_add_u64 v[16:17], v[16:17], 0, v[126:127]
	v_cvt_pk_bf16_f32 v13, v18, v19
	v_cvt_pk_bf16_f32 v14, v14, v15
	v_cvt_pk_bf16_f32 v15, v22, v23
	global_store_dwordx4 v[16:17], v[12:15], off
	s_and_b64 vcc, exec, s[4:5]
	v_pk_mul_f32 v[10:11], v[10:11], v[20:21] op_sel_hi:[1,0]
	v_pk_mul_f32 v[12:13], v[6:7], v[20:21] op_sel_hi:[1,0]
	v_pk_mul_f32 v[6:7], v[4:5], v[20:21] op_sel_hi:[1,0]
	v_pk_mul_f32 v[8:9], v[8:9], v[20:21] op_sel_hi:[1,0]
	v_cvt_pk_bf16_f32 v5, v10, v11
	v_cvt_pk_bf16_f32 v6, v6, v7
	v_cvt_pk_bf16_f32 v7, v12, v13
	s_nop 0
	v_cvt_pk_bf16_f32 v4, v8, v9
	global_store_dwordx4 v[16:17], v[4:7], off offset:256
	s_cbranch_vccz .LBB0_761
	s_waitcnt vmcnt(0)
	s_cmpk_gt_u32 s31, 0xff
	s_cbranch_scc1 .LBB0_770

; #define LAS __attribute__((address_space(3)))
; #define PG8_WAIT_V(n) asm volatile("s_waitcnt vmcnt(" #n ")" ::: "memory")
; #define PG8_BAR __builtin_amdgcn_s_barrier()
; template <class Epi, int LDA, int LDB, int KK>
; __device__ __forceinline__ void gemm_phase(int wv, LAS unsigned char* lds, const Gemm g, const StaticOrder& S, const Epi& E) {
;     const int tid = opaque_tid(wv), wid = __builtin_amdgcn_readfirstlane(tid >> 6), lane = tid & 63, wr = wid >> 2, wc = wid & 3, fr = lane & 15, fq = lane >> 4;
;     constexpr int nt = KK / BK;
;     unsigned voffA[2], voffB[2];
; #pragma unroll
;     for (int i = 0; i < 2; ++i) { int R, C; stage_rc(tid * 16 + i * 8192, R, C); const int Rb = (R & ~31) + perm32(R & 31);
;         voffA[i] = (unsigned)(R * LDA + C) * 2u; voffB[i] = (unsigned)(Rb * LDB + C) * 2u; }
;     constexpr size_t kstep = (size_t)(BK * 2);
;     constexpr size_t hstepA = (size_t)HALF * LDA * 2, hstepB = (size_t)HALF * LDB * 2;
;     constexpr size_t tstepA = 2 * hstepA, tstepB = 2 * hstepB;
;     const unsigned ldsw = (unsigned)wid * 1024u;
;     const int aoff = lds_byte(wr * 64 + fr, fq * 8), boff = lds_byte(wc * 32 + fr, fq * 8);
;     ...
;     Unit cur, nxt; int ui = 0;
;     if (!S.next(0, cur)) return;
;     f32x4 acc[2][2][4][2];
; #pragma unroll
;     for (int a = 0; a < 2; ++a)
; #pragma unroll
;         for (int b = 0; b < 2; ++b)
; #pragma unroll
;             for (int m = 0; m < 4; ++m)
; #pragma unroll
;                 for (int n = 0; n < 2; ++n) acc[a][b][m][n] = (f32x4){0.f, 0.f, 0.f, 0.f};
;     bf16x8 At[4][2], B0[2][2], B1[2][2];
;     const char* cA = (const char*)g.A + (size_t)cur.pm * tstepA; const char* cB = (const char*)g.Bt + (size_t)cur.pn * tstepB;
;     if constexpr (Epi::ROWSCALE) { if (wid < 4) __builtin_amdgcn_global_load_lds((const unsigned*)(E.rsq + cur.pm * 256 + wid * 64 + lane), (LAS unsigned*)(lds + 131072 + wid * 256), 4, 0, 0); }
;     PG8_STAGE(PG8_SB(0, 0), cB, voffB); PG8_STAGE(PG8_SA(0, 0), cA, voffA); PG8_STAGE(PG8_SB(0, 1), cB + hstepB, voffB); PG8_STAGE(PG8_SA(0, 1), cA + hstepA, voffA);
;     if (wr == 1) PG8_BAR;
;     PG8_WAIT_V(4); PG8_BAR;
;     PG8_STAGE(PG8_SB(1, 0), cB + kstep, voffB); PG8_STAGE(PG8_SA(1, 0), cA + kstep, voffA); PG8_STAGE(PG8_SB(1, 1), cB + hstepB + kstep, voffB);
;     PG8_WAIT_V(6); PG8_BAR;
.LBB0_916:
	v_readlane_b32 s6, v254, 28
	v_readlane_b32 s7, v254, 29
	s_lshl_b64 s[6:7], s[6:7], 2
	s_add_u32 s6, s14, s6
	v_and_b32_e32 v21, 15, v20
	v_bfe_u32 v20, v20, 4, 2
	s_addc_u32 s7, s15, s7
	v_lshlrev_b32_e32 v22, 4, v20
	s_add_u32 s16, s6, 0x27ca5000
	v_lshl_or_b32 v197, s4, 6, v21
	v_lshl_or_b32 v22, v21, 6, v22
	v_lshlrev_b32_e32 v21, 2, v21
	s_addc_u32 s17, s7, 0
	s_lshl_b32 s4, s4, 13
	v_and_b32_e32 v23, 32, v21
	v_bitop3_b32 v24, v22, s4, v23 bitop3:0xde
	s_lshl_b32 s4, s5, 5
	s_and_b32 s6, s4, 0x60
	s_add_i32 m0, s35, 0x18000
	v_lshl_add_u64 v[10:11], v[10:11], 0, s[58:59]
	s_lshl_b32 s4, s6, 7
	s_waitcnt vmcnt(4)
	s_barrier
	global_load_lds_dwordx4 v[10:11], off
	v_lshl_add_u64 v[8:9], v[8:9], 0, s[58:59]
	s_add_i32 m0, s35, 0x1a000
	s_add_i32 s39, s35, 0x8000
	s_add_i32 s40, s35, 0xa000
	v_bitop3_b32 v230, v22, s4, v23 bitop3:0xde
	global_load_lds_dwordx4 v[8:9], off
	v_lshl_add_u64 v[6:7], v[6:7], 0, s[58:59]
	s_mov_b32 m0, s39
	s_add_u32 s4, s20, 0x160080
	global_load_lds_dwordx4 v[6:7], off
	v_lshl_add_u64 v[4:5], v[4:5], 0, s[58:59]
	s_mov_b32 m0, s40
	s_addc_u32 s5, s21, 0
	global_load_lds_dwordx4 v[4:5], off
	s_add_i32 m0, s35, 0x1c000
	v_lshl_add_u64 v[4:5], s[4:5], 0, v[2:3]
	global_load_lds_dwordx4 v[4:5], off
	v_lshl_add_u64 v[4:5], s[4:5], 0, v[190:191]
	s_add_i32 m0, s35, 0x1e000
	s_movk_i32 s4, 0x80
	global_load_lds_dwordx4 v[4:5], off
	s_add_u32 s98, s18, 0x2c0080
	s_addc_u32 s99, s19, 0
	v_lshl_add_u64 v[182:183], s[98:99], 0, v[0:1]
	s_add_i32 m0, s35, 0xc000
	s_nop 0
	global_load_lds_dwordx4 v[182:183], off
	v_lshl_add_u64 v[182:183], s[98:99], 0, v[188:189]
	s_add_i32 m0, s35, 0xe000
	s_nop 0
	global_load_lds_dwordx4 v[182:183], off
	v_lshlrev_b32_e32 v4, 6, v20
	s_movk_i32 s8, 0x2c00
	v_bitop3_b32 v231, v4, 64, v21 bitop3:0x36
	v_bitop3_b32 v232, v4, s4, v21 bitop3:0x36
	v_lshrrev_b32_e32 v5, 1, v16
	v_mul_lo_u32 v4, v18, s8
	s_mov_b32 s9, 0x2c000
	v_lshl_or_b32 v233, v20, 3, s6
	v_mad_u64_u32 v[4:5], s[6:7], v5, s9, v[4:5]
	v_or_b32_e32 v4, v4, v17
	v_add_lshl_u32 v4, v4, v19, 1
	v_mov_b32_e32 v5, v3
	s_mov_b64 s[10:11], 0x2c0080
	v_lshl_add_u64 v[192:193], v[4:5], 0, s[10:11]
	v_lshrrev_b32_e32 v5, 1, v12
	v_mul_lo_u32 v4, v14, s8
	v_mad_u64_u32 v[4:5], s[6:7], v5, s9, v[4:5]
	s_waitcnt vmcnt(8)
	v_or_b32_e32 v4, v4, v13
	v_add_lshl_u32 v4, v4, v15, 1
	v_mov_b32_e32 v5, v3
	s_mov_b32 s41, 0
	v_cmp_eq_u32_e64 s[4:5], 0, v20
	s_ashr_i32 s42, s26, 31
	v_lshl_add_u64 v[194:195], v[4:5], 0, s[10:11]
	v_add_u32_e32 v234, 0, v24
	s_barrier
	s_branch .LBB0_918

; #define PG8_STAGE(bufoff, gbase, voff) do { _Pragma("unroll") for (int _i = 0; _i < 2; ++_i) \
;         __builtin_amdgcn_global_load_lds((const unsigned*)((const char*)(gbase) + (voff)[_i]), (LAS unsigned*)(lds + (bufoff) + ldsw + _i * 8192), 16, 0, 0); } while (0)
; #define PG8_LDA(dst, b, h) do { _Pragma("unroll") for (int m = 0; m < 4; ++m) _Pragma("unroll") for (int k = 0; k < 2; ++k) dst[m][k] = *(const LAS bf16x8*)(lds + PG8_SA(b, h) + aoff + m * 2048 + k * 1024); } while (0)
; #define PG8_LDB(dst, b, h) do { _Pragma("unroll") for (int n = 0; n < 2; ++n) _Pragma("unroll") for (int k = 0; k < 2; ++k) dst[n][k] = *(const LAS bf16x8*)(lds + PG8_SB(b, h) + boff + n * 2048 + k * 1024); } while (0)
; #define PG8_MMA(ai, bj, At, Bt) do { __builtin_amdgcn_s_setprio(1); _Pragma("unroll") for (int m = 0; m < 4; ++m) _Pragma("unroll") for (int n = 0; n < 2; ++n) _Pragma("unroll") for (int k = 0; k < 2; ++k) \
;         acc[ai][bj][m][n] = __builtin_amdgcn_mfma_f32_16x16x32_bf16(Bt[n][k], At[m][k], acc[ai][bj][m][n], 0, 0, 0); __builtin_amdgcn_s_setprio(0); } while (0)
; #define PG8_WAIT_L(n) asm volatile("s_waitcnt lgkmcnt(" #n ")" ::: "memory")
; #define PG8_BAR __builtin_amdgcn_s_barrier()
; #define PG8_SCHED __builtin_amdgcn_sched_barrier(0)
; template <class Epi, int LDA, int LDB, int KK>
; __device__ __forceinline__ void gemm_phase(int wv, LAS unsigned char* lds, const Gemm g, const StaticOrder& S, const Epi& E) {
;     ...
;           for (; t < tend; t += 2) {
;             const bool last = (t == nt - 2);
;             const char* a1 = cA + (size_t)(t + 1) * kstep;
;             const char* a2 = last ? nA : cA + (size_t)(t + 2) * kstep; const char* b2 = last ? nB : cB + (size_t)(t + 2) * kstep;
;             const char* a3 = a2 + kstep; const char* b3 = b2 + kstep;
;             PG8_LDB(B0, 0, 0); PG8_SCHED; PG8_LDA(At, 0, 0); PG8_STAGE(PG8_SA(1, 1), a1 + hstepA, voffA);
;             PG8_WAIT_L(8); PG8_BAR; PG8_WAIT_L(0); PG8_MMA(0, 0, At, B0); PG8_BAR; PG8_SCHED;
;     ...
; #pragma unroll
;         for (int a = 0; a < 2; ++a)
; #pragma unroll
;             for (int b = 0; b < 2; ++b)
; #pragma unroll
;                 for (int m = 0; m < 4; ++m)
; #pragma unroll
;                     for (int n = 0; n < 2; ++n) acc[a][b][m][n] = (f32x4){0.f, 0.f, 0.f, 0.f};
.LBB0_924:
	s_add_u32 s47, s20, 0x100
	v_mov_b32_e32 v4, 0
	s_addc_u32 s55, s21, 0
	s_mov_b32 s56, -2
	s_waitcnt lgkmcnt(0)
	v_mov_b32_e32 v5, v4
	v_mov_b32_e32 v6, v4
	v_mov_b32_e32 v7, v4
	v_mov_b32_e32 v8, v4
	v_mov_b32_e32 v9, v4
	v_mov_b32_e32 v10, v4
	v_mov_b32_e32 v11, v4
	v_mov_b32_e32 v20, v4
	v_mov_b32_e32 v21, v4
	v_mov_b32_e32 v22, v4
	v_mov_b32_e32 v23, v4
	v_mov_b32_e32 v24, v4
	v_mov_b32_e32 v25, v4
	v_mov_b32_e32 v26, v4
	v_mov_b32_e32 v27, v4
	v_mov_b32_e32 v36, v4
	v_mov_b32_e32 v37, v4
	v_mov_b32_e32 v38, v4
	v_mov_b32_e32 v39, v4
	v_mov_b32_e32 v40, v4
	v_mov_b32_e32 v41, v4
	v_mov_b32_e32 v42, v4
	v_mov_b32_e32 v43, v4
	v_mov_b32_e32 v52, v4
	v_mov_b32_e32 v53, v4
	v_mov_b32_e32 v54, v4
	v_mov_b32_e32 v55, v4
	v_mov_b32_e32 v56, v4
	v_mov_b32_e32 v57, v4
	v_mov_b32_e32 v58, v4
	v_mov_b32_e32 v59, v4
	v_mov_b32_e32 v12, v4
	v_mov_b32_e32 v13, v4
	v_mov_b32_e32 v14, v4
	v_mov_b32_e32 v15, v4
	v_mov_b32_e32 v16, v4
	v_mov_b32_e32 v17, v4
	v_mov_b32_e32 v18, v4
	v_mov_b32_e32 v19, v4
	v_mov_b32_e32 v28, v4
	v_mov_b32_e32 v29, v4
	v_mov_b32_e32 v30, v4
	v_mov_b32_e32 v31, v4
	v_mov_b32_e32 v32, v4
	v_mov_b32_e32 v33, v4
	v_mov_b32_e32 v34, v4
	v_mov_b32_e32 v35, v4
	v_mov_b32_e32 v44, v4
	v_mov_b32_e32 v45, v4
	v_mov_b32_e32 v46, v4
	v_mov_b32_e32 v47, v4
	v_mov_b32_e32 v48, v4
	v_mov_b32_e32 v49, v4
	v_mov_b32_e32 v50, v4
	v_mov_b32_e32 v51, v4
	v_mov_b32_e32 v60, v4
	v_mov_b32_e32 v61, v4
	v_mov_b32_e32 v62, v4
	v_mov_b32_e32 v63, v4
	v_mov_b32_e32 v64, v4
	v_mov_b32_e32 v65, v4
	v_mov_b32_e32 v66, v4
	v_mov_b32_e32 v67, v4
	v_mov_b32_e32 v68, v4
	v_mov_b32_e32 v69, v4
	v_mov_b32_e32 v70, v4
	v_mov_b32_e32 v71, v4
	v_mov_b32_e32 v72, v4
	v_mov_b32_e32 v73, v4
	v_mov_b32_e32 v74, v4
	v_mov_b32_e32 v75, v4
	v_mov_b32_e32 v84, v4
	v_mov_b32_e32 v85, v4
	v_mov_b32_e32 v86, v4
	v_mov_b32_e32 v87, v4
	v_mov_b32_e32 v88, v4
	v_mov_b32_e32 v89, v4
	v_mov_b32_e32 v90, v4
	v_mov_b32_e32 v91, v4
	v_mov_b32_e32 v100, v4
	v_mov_b32_e32 v101, v4
	v_mov_b32_e32 v102, v4
	v_mov_b32_e32 v103, v4
	v_mov_b32_e32 v104, v4
	v_mov_b32_e32 v105, v4
	v_mov_b32_e32 v106, v4
	v_mov_b32_e32 v107, v4
	v_mov_b32_e32 v116, v4
	v_mov_b32_e32 v117, v4
	v_mov_b32_e32 v118, v4
	v_mov_b32_e32 v119, v4
	v_mov_b32_e32 v120, v4
	v_mov_b32_e32 v121, v4
	v_mov_b32_e32 v122, v4
	v_mov_b32_e32 v123, v4
	v_mov_b32_e32 v76, v4
	v_mov_b32_e32 v77, v4
	v_mov_b32_e32 v78, v4
	v_mov_b32_e32 v79, v4
	v_mov_b32_e32 v80, v4
	v_mov_b32_e32 v81, v4
	v_mov_b32_e32 v82, v4
	v_mov_b32_e32 v83, v4
	v_mov_b32_e32 v92, v4
	v_mov_b32_e32 v93, v4
	v_mov_b32_e32 v94, v4
	v_mov_b32_e32 v95, v4
	v_mov_b32_e32 v96, v4
	v_mov_b32_e32 v97, v4
	v_mov_b32_e32 v98, v4
	v_mov_b32_e32 v99, v4
	v_mov_b32_e32 v108, v4
	v_mov_b32_e32 v109, v4
	v_mov_b32_e32 v110, v4
	v_mov_b32_e32 v111, v4
	v_mov_b32_e32 v112, v4
	v_mov_b32_e32 v113, v4
	v_mov_b32_e32 v114, v4
	v_mov_b32_e32 v115, v4
	v_mov_b32_e32 v124, v4
	v_mov_b32_e32 v125, v4
	v_mov_b32_e32 v126, v4
	v_mov_b32_e32 v127, v4
	v_mov_b32_e32 v128, v4
	v_mov_b32_e32 v129, v4
	v_mov_b32_e32 v130, v4
	v_mov_b32_e32 v131, v4
	v_add_u32_e32 v180, 0x10000, v230
	ds_read_b128 v[132:135], v180 offset:0
	ds_read_b128 v[136:139], v180 offset:2048
	ds_read_b128 v[140:143], v180 offset:16384
	ds_read_b128 v[144:147], v180 offset:18432
	ds_read_b128 v[148:151], v234 offset:0
	ds_read_b128 v[152:155], v234 offset:2048
	ds_read_b128 v[156:159], v234 offset:4096
	ds_read_b128 v[160:163], v234 offset:6144
.Ldown_loop:
	s_add_u32 s20, s18, 0x100
	s_addc_u32 s21, s19, 0
	s_cmpk_eq_i32 s56, 0x54
	s_cselect_b32 s25, s9, s21
	s_cselect_b32 s24, s8, s20
	s_cselect_b32 s23, s11, s55
	s_cselect_b32 s22, s10, s47
	s_waitcnt lgkmcnt(0)
	v_mfma_f32_16x16x32_bf16 v[128:131], v[132:135], v[148:151], v[128:131]
	ds_read_b128 v[202:205], v180 offset:1024
	v_mfma_f32_16x16x32_bf16 v[124:127], v[136:139], v[148:151], v[124:127]
	ds_read_b128 v[206:209], v180 offset:3072
	v_mfma_f32_16x16x32_bf16 v[120:123], v[140:143], v[148:151], v[120:123]
	ds_read_b128 v[210:213], v180 offset:17408
	v_mfma_f32_16x16x32_bf16 v[116:119], v[144:147], v[148:151], v[116:119]
	ds_read_b128 v[214:217], v180 offset:19456
	v_mfma_f32_16x16x32_bf16 v[112:115], v[132:135], v[152:155], v[112:115]
	ds_read_b128 v[164:167], v234 offset:1024
	v_mfma_f32_16x16x32_bf16 v[108:111], v[136:139], v[152:155], v[108:111]
	ds_read_b128 v[168:171], v234 offset:3072
	v_mfma_f32_16x16x32_bf16 v[104:107], v[140:143], v[152:155], v[104:107]
	ds_read_b128 v[172:175], v234 offset:5120
	v_mfma_f32_16x16x32_bf16 v[100:103], v[144:147], v[152:155], v[100:103]
	ds_read_b128 v[176:179], v234 offset:7168
	v_mfma_f32_16x16x32_bf16 v[96:99], v[132:135], v[156:159], v[96:99]
	v_mfma_f32_16x16x32_bf16 v[92:95], v[136:139], v[156:159], v[92:95]
	v_mfma_f32_16x16x32_bf16 v[88:91], v[140:143], v[156:159], v[88:91]
	v_mfma_f32_16x16x32_bf16 v[84:87], v[144:147], v[156:159], v[84:87]
	v_mfma_f32_16x16x32_bf16 v[80:83], v[132:135], v[160:163], v[80:83]
	v_mfma_f32_16x16x32_bf16 v[76:79], v[136:139], v[160:163], v[76:79]
	v_mfma_f32_16x16x32_bf16 v[72:75], v[140:143], v[160:163], v[72:75]
	v_mfma_f32_16x16x32_bf16 v[68:71], v[144:147], v[160:163], v[68:71]
	s_waitcnt vmcnt(8) lgkmcnt(0)
	s_barrier
; #define PG8_STAGE(bufoff, gbase, voff) do { _Pragma("unroll") for (int _i = 0; _i < 2; ++_i) \
;         __builtin_amdgcn_global_load_lds((const unsigned*)((const char*)(gbase) + (voff)[_i]), (LAS unsigned*)(lds + (bufoff) + ldsw + _i * 8192), 16, 0, 0); } while (0)
; #define PG8_LDA(dst, b, h) do { _Pragma("unroll") for (int m = 0; m < 4; ++m) _Pragma("unroll") for (int k = 0; k < 2; ++k) dst[m][k] = *(const LAS bf16x8*)(lds + PG8_SA(b, h) + aoff + m * 2048 + k * 1024); } while (0)
; #define PG8_WAIT_V(n) asm volatile("s_waitcnt vmcnt(" #n ")" ::: "memory")
; #define PG8_BAR __builtin_amdgcn_s_barrier()
; template <class Epi, int LDA, int LDB, int KK>
; __device__ __forceinline__ void gemm_phase(int wv, LAS unsigned char* lds, const Gemm g, const StaticOrder& S, const Epi& E) {
;     ...
;           for (; t < tend; t += 2) {
;             const bool last = (t == nt - 2);
;             const char* a1 = cA + (size_t)(t + 1) * kstep;
;             const char* a2 = last ? nA : cA + (size_t)(t + 2) * kstep; const char* b2 = last ? nB : cB + (size_t)(t + 2) * kstep;
;             const char* a3 = a2 + kstep; const char* b3 = b2 + kstep;
;             PG8_LDB(B0, 0, 0); PG8_SCHED; PG8_LDA(At, 0, 0); PG8_STAGE(PG8_SA(1, 1), a1 + hstepA, voffA);
;             PG8_WAIT_L(8); PG8_BAR; PG8_WAIT_L(0); PG8_MMA(0, 0, At, B0); PG8_BAR; PG8_SCHED;
;             PG8_LDB(B1, 0, 1); PG8_STAGE(PG8_SB(0, 0), b2, voffB);
;             PG8_BAR; PG8_WAIT_L(0); PG8_MMA(0, 1, At, B1); PG8_BAR;
;             PG8_LDA(At, 0, 1); PG8_STAGE(PG8_SA(0, 0), a2, voffA);
;             PG8_BAR; PG8_WAIT_L(0); PG8_MMA(1, 0, At, B0); PG8_BAR; PG8_SCHED;
;             PG8_STAGE(PG8_SB(0, 1), b2 + hstepB, voffB);
;             PG8_WAIT_V(6); PG8_BAR; PG8_MMA(1, 1, At, B1); PG8_BAR;
;             PG8_LDB(B0, 1, 0); PG8_SCHED; PG8_LDA(At, 1, 0); PG8_STAGE(PG8_SA(0, 1), a2 + hstepA, voffA);
;             PG8_WAIT_L(8); PG8_BAR; PG8_WAIT_L(0); PG8_MMA(0, 0, At, B0); PG8_BAR; PG8_SCHED;
;             PG8_LDB(B1, 1, 1); PG8_STAGE(PG8_SB(1, 0), b3, voffB);
;             PG8_BAR; PG8_WAIT_L(0); PG8_MMA(0, 1, At, B1); PG8_BAR;
;             PG8_LDA(At, 1, 1); PG8_STAGE(PG8_SA(1, 0), a3, voffA);
;             PG8_BAR; PG8_WAIT_L(0); PG8_MMA(1, 0, At, B0); PG8_BAR; PG8_SCHED;
;             PG8_STAGE(PG8_SB(1, 1), b3 + hstepB, voffB);
;             PG8_WAIT_V(6); PG8_BAR; PG8_MMA(1, 1, At, B1); PG8_BAR;
	v_mfma_f32_16x16x32_bf16 v[128:131], v[202:205], v[164:167], v[128:131]
	ds_read_b128 v[148:151], v234 offset:16384
	v_mfma_f32_16x16x32_bf16 v[124:127], v[206:209], v[164:167], v[124:127]
	ds_read_b128 v[152:155], v234 offset:18432
	v_mfma_f32_16x16x32_bf16 v[120:123], v[210:213], v[164:167], v[120:123]
	ds_read_b128 v[156:159], v234 offset:20480
	v_mfma_f32_16x16x32_bf16 v[116:119], v[214:217], v[164:167], v[116:119]
	ds_read_b128 v[160:163], v234 offset:22528
	v_mfma_f32_16x16x32_bf16 v[112:115], v[202:205], v[168:171], v[112:115]
	v_lshl_add_u64 v[182:183], s[22:23], 0, v[2:3]
	s_add_i32 m0, s35, 0x10000
	v_mfma_f32_16x16x32_bf16 v[108:111], v[206:209], v[168:171], v[108:111]
	global_load_lds_dwordx4 v[182:183], off
	v_mfma_f32_16x16x32_bf16 v[104:107], v[210:213], v[168:171], v[104:107]
	v_mfma_f32_16x16x32_bf16 v[100:103], v[214:217], v[168:171], v[100:103]
	v_lshl_add_u64 v[182:183], s[22:23], 0, v[190:191]
	s_add_i32 m0, s35, 0x12000
	v_mfma_f32_16x16x32_bf16 v[96:99], v[202:205], v[172:175], v[96:99]
	global_load_lds_dwordx4 v[182:183], off
	v_mfma_f32_16x16x32_bf16 v[92:95], v[206:209], v[172:175], v[92:95]
	v_mfma_f32_16x16x32_bf16 v[88:91], v[210:213], v[172:175], v[88:91]
	v_lshl_add_u64 v[182:183], s[24:25], 0, v[0:1]
	s_mov_b32 m0, s35
	v_mfma_f32_16x16x32_bf16 v[84:87], v[214:217], v[172:175], v[84:87]
	global_load_lds_dwordx4 v[182:183], off
	v_mfma_f32_16x16x32_bf16 v[80:83], v[202:205], v[176:179], v[80:83]
	v_mfma_f32_16x16x32_bf16 v[76:79], v[206:209], v[176:179], v[76:79]
	v_mfma_f32_16x16x32_bf16 v[72:75], v[210:213], v[176:179], v[72:75]
	v_mfma_f32_16x16x32_bf16 v[68:71], v[214:217], v[176:179], v[68:71]
	s_waitcnt lgkmcnt(0)
	v_mfma_f32_16x16x32_bf16 v[64:67], v[132:135], v[148:151], v[64:67]
	ds_read_b128 v[164:167], v234 offset:17408
	v_mfma_f32_16x16x32_bf16 v[60:63], v[136:139], v[148:151], v[60:63]
	ds_read_b128 v[168:171], v234 offset:19456
	v_mfma_f32_16x16x32_bf16 v[56:59], v[140:143], v[148:151], v[56:59]
	ds_read_b128 v[172:175], v234 offset:21504
	v_mfma_f32_16x16x32_bf16 v[52:55], v[144:147], v[148:151], v[52:55]
	ds_read_b128 v[176:179], v234 offset:23552
	v_mfma_f32_16x16x32_bf16 v[48:51], v[132:135], v[152:155], v[48:51]
	v_lshl_add_u64 v[182:183], s[24:25], 0, v[188:189]
	s_add_i32 m0, s35, 0x2000
	v_mfma_f32_16x16x32_bf16 v[44:47], v[136:139], v[152:155], v[44:47]
	global_load_lds_dwordx4 v[182:183], off
	v_mfma_f32_16x16x32_bf16 v[40:43], v[140:143], v[152:155], v[40:43]
	v_mfma_f32_16x16x32_bf16 v[36:39], v[144:147], v[152:155], v[36:39]
	s_add_u32 s98, s22, 0x160000
	s_addc_u32 s99, s23, 0
	v_lshl_add_u64 v[182:183], s[98:99], 0, v[2:3]
	s_add_i32 m0, s35, 0x14000
	v_mfma_f32_16x16x32_bf16 v[32:35], v[132:135], v[156:159], v[32:35]
	global_load_lds_dwordx4 v[182:183], off
	v_mfma_f32_16x16x32_bf16 v[28:31], v[136:139], v[156:159], v[28:31]
	v_mfma_f32_16x16x32_bf16 v[24:27], v[140:143], v[156:159], v[24:27]
	v_lshl_add_u64 v[182:183], s[98:99], 0, v[190:191]
	s_add_i32 m0, s35, 0x16000
	v_mfma_f32_16x16x32_bf16 v[20:23], v[144:147], v[156:159], v[20:23]
	global_load_lds_dwordx4 v[182:183], off
	v_mfma_f32_16x16x32_bf16 v[16:19], v[132:135], v[160:163], v[16:19]
	v_mfma_f32_16x16x32_bf16 v[12:15], v[136:139], v[160:163], v[12:15]
	v_mfma_f32_16x16x32_bf16 v[8:11], v[140:143], v[160:163], v[8:11]
	v_mfma_f32_16x16x32_bf16 v[4:7], v[144:147], v[160:163], v[4:7]
	s_waitcnt vmcnt(8) lgkmcnt(0)
	s_barrier
	v_mfma_f32_16x16x32_bf16 v[64:67], v[202:205], v[164:167], v[64:67]
	ds_read_b128 v[132:135], v180 offset:32768
	v_mfma_f32_16x16x32_bf16 v[60:63], v[206:209], v[164:167], v[60:63]
	ds_read_b128 v[136:139], v180 offset:34816
	v_mfma_f32_16x16x32_bf16 v[56:59], v[210:213], v[164:167], v[56:59]
	ds_read_b128 v[140:143], v180 offset:49152
	v_mfma_f32_16x16x32_bf16 v[52:55], v[214:217], v[164:167], v[52:55]
	ds_read_b128 v[144:147], v180 offset:51200
	v_mfma_f32_16x16x32_bf16 v[48:51], v[202:205], v[168:171], v[48:51]
	ds_read_b128 v[148:151], v234 offset:32768
	v_mfma_f32_16x16x32_bf16 v[44:47], v[206:209], v[168:171], v[44:47]
	ds_read_b128 v[152:155], v234 offset:34816
	v_mfma_f32_16x16x32_bf16 v[40:43], v[210:213], v[168:171], v[40:43]
	ds_read_b128 v[156:159], v234 offset:36864
	v_mfma_f32_16x16x32_bf16 v[36:39], v[214:217], v[168:171], v[36:39]
	ds_read_b128 v[160:163], v234 offset:38912
	v_mfma_f32_16x16x32_bf16 v[32:35], v[202:205], v[172:175], v[32:35]
	s_add_u32 s98, s24, 0x2c0000
	s_addc_u32 s99, s25, 0
	v_lshl_add_u64 v[182:183], s[98:99], 0, v[0:1]
	s_add_i32 m0, s35, 0x4000
	v_mfma_f32_16x16x32_bf16 v[28:31], v[206:209], v[172:175], v[28:31]
	global_load_lds_dwordx4 v[182:183], off
	v_mfma_f32_16x16x32_bf16 v[24:27], v[210:213], v[172:175], v[24:27]
	v_mfma_f32_16x16x32_bf16 v[20:23], v[214:217], v[172:175], v[20:23]
	v_lshl_add_u64 v[182:183], s[98:99], 0, v[188:189]
	s_add_i32 m0, s35, 0x6000
	v_mfma_f32_16x16x32_bf16 v[16:19], v[202:205], v[176:179], v[16:19]
	global_load_lds_dwordx4 v[182:183], off
	v_mfma_f32_16x16x32_bf16 v[12:15], v[206:209], v[176:179], v[12:15]
	v_mfma_f32_16x16x32_bf16 v[8:11], v[210:213], v[176:179], v[8:11]
	v_mfma_f32_16x16x32_bf16 v[4:7], v[214:217], v[176:179], v[4:7]
	s_add_u32 s22, s22, 0x80
	s_addc_u32 s23, s23, 0
	s_add_u32 s24, s24, 0x80
	s_addc_u32 s25, s25, 0
	s_waitcnt lgkmcnt(0)
	v_mfma_f32_16x16x32_bf16 v[128:131], v[132:135], v[148:151], v[128:131]
	ds_read_b128 v[202:205], v180 offset:33792
	v_mfma_f32_16x16x32_bf16 v[124:127], v[136:139], v[148:151], v[124:127]
	ds_read_b128 v[206:209], v180 offset:35840
	v_mfma_f32_16x16x32_bf16 v[120:123], v[140:143], v[148:151], v[120:123]
	ds_read_b128 v[210:213], v180 offset:50176
	v_mfma_f32_16x16x32_bf16 v[116:119], v[144:147], v[148:151], v[116:119]
	ds_read_b128 v[214:217], v180 offset:52224
	v_mfma_f32_16x16x32_bf16 v[112:115], v[132:135], v[152:155], v[112:115]
	ds_read_b128 v[164:167], v234 offset:33792
	v_mfma_f32_16x16x32_bf16 v[108:111], v[136:139], v[152:155], v[108:111]
	ds_read_b128 v[168:171], v234 offset:35840
	v_mfma_f32_16x16x32_bf16 v[104:107], v[140:143], v[152:155], v[104:107]
	ds_read_b128 v[172:175], v234 offset:37888
	v_mfma_f32_16x16x32_bf16 v[100:103], v[144:147], v[152:155], v[100:103]
	ds_read_b128 v[176:179], v234 offset:39936
	v_mfma_f32_16x16x32_bf16 v[96:99], v[132:135], v[156:159], v[96:99]
	v_mfma_f32_16x16x32_bf16 v[92:95], v[136:139], v[156:159], v[92:95]
	v_mfma_f32_16x16x32_bf16 v[88:91], v[140:143], v[156:159], v[88:91]
	v_mfma_f32_16x16x32_bf16 v[84:87], v[144:147], v[156:159], v[84:87]
	v_mfma_f32_16x16x32_bf16 v[80:83], v[132:135], v[160:163], v[80:83]
	v_mfma_f32_16x16x32_bf16 v[76:79], v[136:139], v[160:163], v[76:79]
	v_mfma_f32_16x16x32_bf16 v[72:75], v[140:143], v[160:163], v[72:75]
	v_mfma_f32_16x16x32_bf16 v[68:71], v[144:147], v[160:163], v[68:71]
	s_waitcnt vmcnt(8) lgkmcnt(0)
	s_barrier
; #define PG8_STAGE(bufoff, gbase, voff) do { _Pragma("unroll") for (int _i = 0; _i < 2; ++_i) \
;         __builtin_amdgcn_global_load_lds((const unsigned*)((const char*)(gbase) + (voff)[_i]), (LAS unsigned*)(lds + (bufoff) + ldsw + _i * 8192), 16, 0, 0); } while (0)
; #define PG8_LDA(dst, b, h) do { _Pragma("unroll") for (int m = 0; m < 4; ++m) _Pragma("unroll") for (int k = 0; k < 2; ++k) dst[m][k] = *(const LAS bf16x8*)(lds + PG8_SA(b, h) + aoff + m * 2048 + k * 1024); } while (0)
; #define PG8_WAIT_V(n) asm volatile("s_waitcnt vmcnt(" #n ")" ::: "memory")
; template <class Epi, int LDA, int LDB, int KK>
; __device__ __forceinline__ void gemm_phase(int wv, LAS unsigned char* lds, const Gemm g, const StaticOrder& S, const Epi& E) {
;     ...
;           for (; t < tend; t += 2) {
;             const bool last = (t == nt - 2);
;             const char* a1 = cA + (size_t)(t + 1) * kstep;
;             const char* a2 = last ? nA : cA + (size_t)(t + 2) * kstep; const char* b2 = last ? nB : cB + (size_t)(t + 2) * kstep;
;             const char* a3 = a2 + kstep; const char* b3 = b2 + kstep;
;             PG8_LDB(B0, 0, 0); PG8_SCHED; PG8_LDA(At, 0, 0); PG8_STAGE(PG8_SA(1, 1), a1 + hstepA, voffA);
;             PG8_WAIT_L(8); PG8_BAR; PG8_WAIT_L(0); PG8_MMA(0, 0, At, B0); PG8_BAR; PG8_SCHED;
;             PG8_LDB(B1, 0, 1); PG8_STAGE(PG8_SB(0, 0), b2, voffB);
;             PG8_BAR; PG8_WAIT_L(0); PG8_MMA(0, 1, At, B1); PG8_BAR;
;             PG8_LDA(At, 0, 1); PG8_STAGE(PG8_SA(0, 0), a2, voffA);
;             PG8_BAR; PG8_WAIT_L(0); PG8_MMA(1, 0, At, B0); PG8_BAR; PG8_SCHED;
;             PG8_STAGE(PG8_SB(0, 1), b2 + hstepB, voffB);
;             PG8_WAIT_V(6); PG8_BAR; PG8_MMA(1, 1, At, B1); PG8_BAR;
;             PG8_LDB(B0, 1, 0); PG8_SCHED; PG8_LDA(At, 1, 0); PG8_STAGE(PG8_SA(0, 1), a2 + hstepA, voffA);
;             PG8_WAIT_L(8); PG8_BAR; PG8_WAIT_L(0); PG8_MMA(0, 0, At, B0); PG8_BAR; PG8_SCHED;
;             PG8_LDB(B1, 1, 1); PG8_STAGE(PG8_SB(1, 0), b3, voffB);
;             PG8_BAR; PG8_WAIT_L(0); PG8_MMA(0, 1, At, B1); PG8_BAR;
;             PG8_LDA(At, 1, 1); PG8_STAGE(PG8_SA(1, 0), a3, voffA);
;             PG8_BAR; PG8_WAIT_L(0); PG8_MMA(1, 0, At, B0); PG8_BAR; PG8_SCHED;
;             PG8_STAGE(PG8_SB(1, 1), b3 + hstepB, voffB);
;             PG8_WAIT_V(6); PG8_BAR; PG8_MMA(1, 1, At, B1); PG8_BAR;
;           }
	v_mfma_f32_16x16x32_bf16 v[128:131], v[202:205], v[164:167], v[128:131]
	ds_read_b128 v[148:151], v234 offset:49152
	v_mfma_f32_16x16x32_bf16 v[124:127], v[206:209], v[164:167], v[124:127]
	ds_read_b128 v[152:155], v234 offset:51200
	v_mfma_f32_16x16x32_bf16 v[120:123], v[210:213], v[164:167], v[120:123]
	ds_read_b128 v[156:159], v234 offset:53248
	v_mfma_f32_16x16x32_bf16 v[116:119], v[214:217], v[164:167], v[116:119]
	ds_read_b128 v[160:163], v234 offset:55296
	v_mfma_f32_16x16x32_bf16 v[112:115], v[202:205], v[168:171], v[112:115]
	v_lshl_add_u64 v[182:183], s[22:23], 0, v[2:3]
	s_add_i32 m0, s35, 0x18000
	v_mfma_f32_16x16x32_bf16 v[108:111], v[206:209], v[168:171], v[108:111]
	global_load_lds_dwordx4 v[182:183], off
	v_mfma_f32_16x16x32_bf16 v[104:107], v[210:213], v[168:171], v[104:107]
	v_mfma_f32_16x16x32_bf16 v[100:103], v[214:217], v[168:171], v[100:103]
	v_lshl_add_u64 v[182:183], s[22:23], 0, v[190:191]
	s_add_i32 m0, s35, 0x1a000
	v_mfma_f32_16x16x32_bf16 v[96:99], v[202:205], v[172:175], v[96:99]
	global_load_lds_dwordx4 v[182:183], off
	v_mfma_f32_16x16x32_bf16 v[92:95], v[206:209], v[172:175], v[92:95]
	v_mfma_f32_16x16x32_bf16 v[88:91], v[210:213], v[172:175], v[88:91]
	v_lshl_add_u64 v[182:183], s[24:25], 0, v[0:1]
	s_add_i32 m0, s35, 0x8000
	v_mfma_f32_16x16x32_bf16 v[84:87], v[214:217], v[172:175], v[84:87]
	global_load_lds_dwordx4 v[182:183], off
	v_mfma_f32_16x16x32_bf16 v[80:83], v[202:205], v[176:179], v[80:83]
	v_mfma_f32_16x16x32_bf16 v[76:79], v[206:209], v[176:179], v[76:79]
	v_mfma_f32_16x16x32_bf16 v[72:75], v[210:213], v[176:179], v[72:75]
	v_mfma_f32_16x16x32_bf16 v[68:71], v[214:217], v[176:179], v[68:71]
	s_waitcnt lgkmcnt(0)
	v_mfma_f32_16x16x32_bf16 v[64:67], v[132:135], v[148:151], v[64:67]
	ds_read_b128 v[164:167], v234 offset:50176
	v_mfma_f32_16x16x32_bf16 v[60:63], v[136:139], v[148:151], v[60:63]
	ds_read_b128 v[168:171], v234 offset:52224
	v_mfma_f32_16x16x32_bf16 v[56:59], v[140:143], v[148:151], v[56:59]
	ds_read_b128 v[172:175], v234 offset:54272
	v_mfma_f32_16x16x32_bf16 v[52:55], v[144:147], v[148:151], v[52:55]
	ds_read_b128 v[176:179], v234 offset:56320
	v_mfma_f32_16x16x32_bf16 v[48:51], v[132:135], v[152:155], v[48:51]
	v_lshl_add_u64 v[182:183], s[24:25], 0, v[188:189]
	s_add_i32 m0, s35, 0xa000
	v_mfma_f32_16x16x32_bf16 v[44:47], v[136:139], v[152:155], v[44:47]
	global_load_lds_dwordx4 v[182:183], off
	v_mfma_f32_16x16x32_bf16 v[40:43], v[140:143], v[152:155], v[40:43]
	v_mfma_f32_16x16x32_bf16 v[36:39], v[144:147], v[152:155], v[36:39]
	s_add_u32 s98, s22, 0x160000
	s_addc_u32 s99, s23, 0
	v_lshl_add_u64 v[182:183], s[98:99], 0, v[2:3]
	s_add_i32 m0, s35, 0x1c000
	v_mfma_f32_16x16x32_bf16 v[32:35], v[132:135], v[156:159], v[32:35]
	global_load_lds_dwordx4 v[182:183], off
	v_mfma_f32_16x16x32_bf16 v[28:31], v[136:139], v[156:159], v[28:31]
	v_mfma_f32_16x16x32_bf16 v[24:27], v[140:143], v[156:159], v[24:27]
	v_lshl_add_u64 v[182:183], s[98:99], 0, v[190:191]
	s_add_i32 m0, s35, 0x1e000
	v_mfma_f32_16x16x32_bf16 v[20:23], v[144:147], v[156:159], v[20:23]
	global_load_lds_dwordx4 v[182:183], off
	v_mfma_f32_16x16x32_bf16 v[16:19], v[132:135], v[160:163], v[16:19]
	v_mfma_f32_16x16x32_bf16 v[12:15], v[136:139], v[160:163], v[12:15]
	v_mfma_f32_16x16x32_bf16 v[8:11], v[140:143], v[160:163], v[8:11]
	v_mfma_f32_16x16x32_bf16 v[4:7], v[144:147], v[160:163], v[4:7]
	s_waitcnt vmcnt(8) lgkmcnt(0)
	s_barrier
	v_mfma_f32_16x16x32_bf16 v[64:67], v[202:205], v[164:167], v[64:67]
	ds_read_b128 v[132:135], v180 offset:0
	v_mfma_f32_16x16x32_bf16 v[60:63], v[206:209], v[164:167], v[60:63]
	ds_read_b128 v[136:139], v180 offset:2048
	v_mfma_f32_16x16x32_bf16 v[56:59], v[210:213], v[164:167], v[56:59]
	ds_read_b128 v[140:143], v180 offset:16384
	v_mfma_f32_16x16x32_bf16 v[52:55], v[214:217], v[164:167], v[52:55]
	ds_read_b128 v[144:147], v180 offset:18432
	v_mfma_f32_16x16x32_bf16 v[48:51], v[202:205], v[168:171], v[48:51]
	ds_read_b128 v[148:151], v234 offset:0
	v_mfma_f32_16x16x32_bf16 v[44:47], v[206:209], v[168:171], v[44:47]
	ds_read_b128 v[152:155], v234 offset:2048
	v_mfma_f32_16x16x32_bf16 v[40:43], v[210:213], v[168:171], v[40:43]
	ds_read_b128 v[156:159], v234 offset:4096
	v_mfma_f32_16x16x32_bf16 v[36:39], v[214:217], v[168:171], v[36:39]
	ds_read_b128 v[160:163], v234 offset:6144
	v_mfma_f32_16x16x32_bf16 v[32:35], v[202:205], v[172:175], v[32:35]
	s_add_u32 s98, s24, 0x2c0000
	s_addc_u32 s99, s25, 0
	v_lshl_add_u64 v[182:183], s[98:99], 0, v[0:1]
	s_add_i32 m0, s35, 0xc000
	v_mfma_f32_16x16x32_bf16 v[28:31], v[206:209], v[172:175], v[28:31]
	global_load_lds_dwordx4 v[182:183], off
	v_mfma_f32_16x16x32_bf16 v[24:27], v[210:213], v[172:175], v[24:27]
	v_mfma_f32_16x16x32_bf16 v[20:23], v[214:217], v[172:175], v[20:23]
	v_lshl_add_u64 v[182:183], s[98:99], 0, v[188:189]
	s_add_i32 m0, s35, 0xe000
	v_mfma_f32_16x16x32_bf16 v[16:19], v[202:205], v[176:179], v[16:19]
	global_load_lds_dwordx4 v[182:183], off
	v_mfma_f32_16x16x32_bf16 v[12:15], v[206:209], v[176:179], v[12:15]
	v_mfma_f32_16x16x32_bf16 v[8:11], v[210:213], v[176:179], v[8:11]
	v_mfma_f32_16x16x32_bf16 v[4:7], v[214:217], v[176:179], v[4:7]
	s_add_i32 s56, s56, 2
	s_add_u32 s47, s47, 0x100
	s_addc_u32 s55, s55, 0
	s_cmpk_gt_u32 s56, 0x55
	s_mov_b64 s[18:19], s[20:21]
	s_cbranch_scc0 .Ldown_loop
; #define LAS __attribute__((address_space(3)))
; __device__ __forceinline__ float shx(float v, int mask, int lane) { return __int_as_float(__builtin_amdgcn_ds_bpermute((lane ^ mask) << 2, __float_as_int(v))); }
; __device__ __forceinline__ u32x4 pack8(const f32x4& a, const f32x4& b) { u32x4 w; w.x = pack2(a[0], a[1]); w.y = pack2(a[2], a[3]); w.z = pack2(b[0], b[1]); w.w = pack2(b[2], b[3]); return w; }
;     __device__ __forceinline__ void operator()(AccT& acc, const pg8::Unit& u, int wr, int wc, int fr, int fq, const LAS float* rs) const {
;         int row0 = u.pm * 256 + wr * 64 + fr; asm volatile("" : "+v"(row0)); const int cb = u.pn * 256 + wc * 32 + 8 * fq, lane = fr + 16 * fq;
; #pragma unroll
;         for (int ai = 0; ai < 2; ++ai) {
;             f32x4 hv[4][2][2];
; #pragma unroll
;             for (int m = 0; m < 4; ++m)
; #pragma unroll
;                 for (int bj = 0; bj < 2; ++bj) { const float* hp = h + (size_t)(row0 + ai * 128 + m * 16) * D + cb + bj * 128; hv[m][bj][0] = *(const f32x4*)hp; hv[m][bj][1] = *(const f32x4*)(hp + 4); }
; #pragma unroll
;             for (int m = 0; m < 4; ++m) {
;                 const int row = row0 + ai * 128 + m * 16; float ss = 0.f;
; #pragma unroll
;                 for (int bj = 0; bj < 2; ++bj) {
;                     const int col = cb + bj * 128; float* hp = h + (size_t)row * D + col;
;                     const f32x4 o0 = hv[m][bj][0] + acc[ai][bj][m][0], o1 = hv[m][bj][1] + acc[ai][bj][m][1];
;                     *(f32x4*)hp = o0; *(f32x4*)(hp + 4) = o1;
;                     *(u32x4*)(hb + (size_t)row * D + col) = pack8(o0, o1);
;                     ss += o0[0] * o0[0] + o0[1] * o0[1] + o0[2] * o0[2] + o0[3] * o0[3] + o1[0] * o1[0] + o1[1] * o1[1] + o1[2] * o1[2] + o1[3] * o1[3];
;                 }
;                 ss += shx(ss, 16, lane); ss += shx(ss, 32, lane);
;                 if (fq == 0) atomicAdd(rsqn + row, ss);
;             }
;         }
;     }
	s_waitcnt lgkmcnt(0)
	v_lshl_or_b32 v202, s45, 8, v233
	v_lshl_add_u32 v206, s46, 8, v197
	v_ashrrev_i32_e32 v203, 31, v202
	v_lshlrev_b64 v[244:245], 2, v[202:203]
	v_ashrrev_i32_e32 v207, 31, v206
	v_lshl_add_u64 v[204:205], s[14:15], 0, v[244:245]
	v_lshlrev_b64 v[246:247], 13, v[206:207]
	v_lshl_add_u64 v[132:133], v[204:205], 0, v[246:247]
	global_load_dwordx4 v[236:239], v[132:133], off offset:16
	global_load_dwordx4 v[240:243], v[132:133], off
	global_load_dwordx4 v[180:183], v[132:133], off offset:528
	global_load_dwordx4 v[184:187], v[132:133], off offset:512
	v_add_u32_e32 v214, 16, v206
	v_ashrrev_i32_e32 v215, 31, v214
	v_add_u32_e32 v210, 32, v206
	v_add_u32_e32 v208, 48, v206
	v_lshlrev_b64 v[218:219], 13, v[214:215]
	v_ashrrev_i32_e32 v211, 31, v210
	v_ashrrev_i32_e32 v209, 31, v208
	v_lshl_add_u64 v[132:133], v[204:205], 0, v[218:219]
	v_lshlrev_b64 v[216:217], 13, v[210:211]
	v_lshlrev_b64 v[212:213], 13, v[208:209]
	global_load_dwordx4 v[172:175], v[132:133], off offset:16
	global_load_dwordx4 v[176:179], v[132:133], off
	global_load_dwordx4 v[164:167], v[132:133], off offset:528
	global_load_dwordx4 v[168:171], v[132:133], off offset:512
	v_lshl_add_u64 v[132:133], v[204:205], 0, v[216:217]
	v_lshl_add_u64 v[136:137], v[204:205], 0, v[212:213]
	global_load_dwordx4 v[156:159], v[132:133], off offset:16
	global_load_dwordx4 v[160:163], v[132:133], off
	global_load_dwordx4 v[140:143], v[132:133], off offset:528
	global_load_dwordx4 v[148:151], v[132:133], off offset:512
	global_load_dwordx4 v[144:147], v[136:137], off offset:16
	global_load_dwordx4 v[152:155], v[136:137], off
	s_nop 0
	global_load_dwordx4 v[132:135], v[136:137], off offset:528
	s_nop 0
	global_load_dwordx4 v[136:139], v[136:137], off offset:512
	v_lshl_add_u64 v[246:247], s[14:15], 0, v[246:247]
	v_lshl_add_u64 v[244:245], v[246:247], 0, v[244:245]
	s_waitcnt vmcnt(0)
	v_pk_add_f32 v[126:127], v[126:127], v[238:239]
	v_pk_add_f32 v[130:131], v[130:131], v[242:243]
	v_pk_add_f32 v[128:129], v[128:129], v[240:241]
	v_pk_add_f32 v[124:125], v[124:125], v[236:237]
	global_store_dwordx4 v[244:245], v[128:131], off
	global_store_dwordx4 v[244:245], v[124:127], off offset:16
	v_cvt_pk_bf16_f32 v236, v128, v129
	v_lshlrev_b64 v[240:241], 12, v[206:207]
	v_mul_f32_e32 v129, v129, v129
	v_fmac_f32_e32 v129, v128, v128
	v_lshl_add_u64 v[240:241], s[12:13], 0, v[240:241]
	v_fmac_f32_e32 v129, v130, v130
	v_lshl_add_u64 v[240:241], v[202:203], 1, v[240:241]
	v_fmac_f32_e32 v129, v131, v131
	v_pk_add_f32 v[122:123], v[122:123], v[186:187]
	v_pk_add_f32 v[120:121], v[120:121], v[184:185]
	v_cvt_pk_bf16_f32 v237, v130, v131
	v_cvt_pk_bf16_f32 v238, v124, v125
	v_cvt_pk_bf16_f32 v239, v126, v127
	global_store_dwordx4 v[240:241], v[236:239], off
	v_fmac_f32_e32 v129, v124, v124
	v_pk_add_f32 v[118:119], v[118:119], v[182:183]
	v_pk_add_f32 v[116:117], v[116:117], v[180:181]
	global_store_dwordx4 v[244:245], v[120:123], off offset:512
	global_store_dwordx4 v[244:245], v[116:119], off offset:528
	v_cvt_pk_bf16_f32 v124, v120, v121
	v_fmac_f32_e32 v129, v125, v125
	v_mul_f32_e32 v121, v121, v121
	v_fmac_f32_e32 v121, v120, v120
	v_fmac_f32_e32 v121, v122, v122
	v_fmac_f32_e32 v121, v123, v123
	v_fmac_f32_e32 v121, v116, v116
	v_fmac_f32_e32 v121, v117, v117
	v_fmac_f32_e32 v129, v126, v126
	v_fmac_f32_e32 v121, v118, v118
	v_fmac_f32_e32 v129, v127, v127
	v_fmac_f32_e32 v121, v119, v119
	v_cvt_pk_bf16_f32 v126, v116, v117
	v_add_f32_e32 v116, v129, v121
	ds_bpermute_b32 v117, v231, v116
	v_cvt_pk_bf16_f32 v125, v122, v123
	v_cvt_pk_bf16_f32 v127, v118, v119
	global_store_dwordx4 v[240:241], v[124:127], off offset:256
	s_waitcnt lgkmcnt(0)
	v_add_f32_e32 v116, v116, v117
	ds_bpermute_b32 v117, v232, v116
	s_and_saveexec_b64 s[18:19], s[4:5]
	s_cbranch_execz .LBB0_928
	s_waitcnt lgkmcnt(0)
	v_add_f32_e32 v118, v116, v117
	v_lshl_add_u64 v[116:117], v[206:207], 2, s[16:17]
	global_atomic_add_f32 v[116:117], v118, off

; #define PG8_WAIT_V(n) asm volatile("s_waitcnt vmcnt(" #n ")" ::: "memory")
; #define PG8_BAR __builtin_amdgcn_s_barrier()
; template <class Epi, int LDA, int LDB, int KK>
; __device__ __forceinline__ void gemm_phase(int wv, LAS unsigned char* lds, const Gemm g, const StaticOrder& S, const Epi& E) {
;     ...
;     PG8_WAIT_V(0);
;     if (wr == 0) PG8_BAR;
;     PG8_BAR;
.LBB0_942:
	s_waitcnt vmcnt(0)
	s_cmpk_gt_u32 s27, 0xff
	s_cbranch_scc1 .LBB0_944
.LBB0_944:
	s_barrier

; #define LAS __attribute__((address_space(3)))
; __global__ void __launch_bounds__(512, 2) fwd_megakernel(Params p_unused) {
;     extern __shared__ __attribute__((aligned(16))) unsigned char smem[];
;     LAS unsigned char* lds = (LAS unsigned char*)smem;
;     cg::grid_group grid = cg::this_grid();
;     const int wv = __builtin_amdgcn_readfirstlane((int)threadIdx.x >> 6);
	.amdhsa_kernel _Z14fwd_megakernel6Params
		.amdhsa_group_segment_fixed_size 0
		.amdhsa_private_segment_fixed_size 0
		.amdhsa_kernarg_size 424
		.amdhsa_user_sgpr_count 2
		.amdhsa_user_sgpr_dispatch_ptr 0
		.amdhsa_user_sgpr_queue_ptr 0
		.amdhsa_user_sgpr_kernarg_segment_ptr 1
		.amdhsa_user_sgpr_dispatch_id 0
		.amdhsa_user_sgpr_kernarg_preload_length 0
		.amdhsa_user_sgpr_kernarg_preload_offset 0
		.amdhsa_user_sgpr_private_segment_size 0
		.amdhsa_uses_dynamic_stack 0
		.amdhsa_enable_private_segment 0
		.amdhsa_system_sgpr_workgroup_id_x 1
		.amdhsa_system_sgpr_workgroup_id_y 0
		.amdhsa_system_sgpr_workgroup_id_z 0
		.amdhsa_system_sgpr_workgroup_info 0
		.amdhsa_system_vgpr_workitem_id 2
		.amdhsa_next_free_vgpr 255
		.amdhsa_next_free_sgpr 102
		.amdhsa_accum_offset 256
		.amdhsa_reserve_vcc 1
		.amdhsa_float_round_mode_32 0
		.amdhsa_float_round_mode_16_64 0
		.amdhsa_float_denorm_mode_32 3
		.amdhsa_float_denorm_mode_16_64 3
		.amdhsa_dx10_clamp 1
		.amdhsa_ieee_mode 1
		.amdhsa_fp16_overflow 0
		.amdhsa_tg_split 0
		.amdhsa_exception_fp_ieee_invalid_op 0
		.amdhsa_exception_fp_denorm_src 0
		.amdhsa_exception_fp_ieee_div_zero 0
		.amdhsa_exception_fp_ieee_overflow 0
		.amdhsa_exception_fp_ieee_underflow 0
		.amdhsa_exception_fp_ieee_inexact 0
		.amdhsa_exception_int_div_zero 0
	.end_amdhsa_kernel

; __global__ void __launch_bounds__(512, 2) fwd_megakernel(Params p_unused) {
;     extern __shared__ __attribute__((aligned(16))) unsigned char smem[];
amdhsa.kernels:
  - .agpr_count:     0
    .args:
      - .offset:         0
        .size:           168
        .value_kind:     by_value
      - .offset:         168
        .size:           4
        .value_kind:     hidden_block_count_x
      - .offset:         172
        .size:           4
        .value_kind:     hidden_block_count_y
      - .offset:         176
        .size:           4
        .value_kind:     hidden_block_count_z
      - .offset:         180
        .size:           2
        .value_kind:     hidden_group_size_x
      - .offset:         182
        .size:           2
        .value_kind:     hidden_group_size_y
      - .offset:         184
        .size:           2
        .value_kind:     hidden_group_size_z
      - .offset:         186
        .size:           2
        .value_kind:     hidden_remainder_x
      - .offset:         188
        .size:           2
        .value_kind:     hidden_remainder_y
      - .offset:         190
        .size:           2
        .value_kind:     hidden_remainder_z
      - .offset:         208
        .size:           8
        .value_kind:     hidden_global_offset_x
      - .offset:         216
        .size:           8
        .value_kind:     hidden_global_offset_y
      - .offset:         224
        .size:           8
        .value_kind:     hidden_global_offset_z
      - .offset:         232
        .size:           2
        .value_kind:     hidden_grid_dims
      - .offset:         256
        .size:           8
        .value_kind:     hidden_multigrid_sync_arg
      - .offset:         288
        .size:           4
        .value_kind:     hidden_dynamic_lds_size
    .group_segment_fixed_size: 0
    .kernarg_segment_align: 8
    .kernarg_segment_size: 424
    .language:       OpenCL C
    .language_version:
      - 2
      - 0
    .max_flat_workgroup_size: 512
    .name:           _Z14fwd_megakernel6Params
    .private_segment_fixed_size: 0
    .sgpr_count:     108
    .sgpr_spill_count: 34
    .symbol:         _Z14fwd_megakernel6Params.kd
    .uniform_work_group_size: 1
    .uses_dynamic_stack: false
    .vgpr_count:     255
    .vgpr_spill_count: 0
    .wavefront_size: 64
